# w_in epilogue Q / K|V paths: rope table quads of the next 16-row block prefetched (two register sets, all eight row addresses computed up front)
# speedup vs baseline: 1.0066x; 1.0066x over previous
; __device__ __forceinline__ float shx16(float v, int odd  ) { const unsigned x = __builtin_bit_cast(unsigned, v); auto r = __builtin_amdgcn_permlane16_swap(x, x, false, false); return __builtin_bit_cast(float, odd ? r[0] : r[1]); }
; __device__ __forceinline__ void st_bf4(bf16_t* p, const f32x4 v) { u32x2 w; w.x = cvt_pk_bf16(v[0], v[1]); w.y = cvt_pk_bf16(v[2], v[3]); *(u32x2*)p = w; }
;     __device__ __forceinline__ void operator()(const f32x4 (&acc)[2][2][4][2], const Unit& u, int wr, int wc, int fr, int fq) const {
;     ...
;             for (int m = 0; m < 4; ++m) { const int row = u.pm * 256 + ai * 128 + wr * 64 + m * 16 + fr;
; #pragma unroll
;                 for (int bj = 0; bj < 2; ++bj)
; #pragma unroll
;                     for (int n = 0; n < 2; ++n) { const int tc = bj * 128 + wc * 32 + 8 * fq + 4 * n; f32x4 v = acc[ai][bj][m][n];
;                         if (pn < 2) { *(f32x4*)(XA + (size_t)row * 512 + pn * 256 + tc) = v; }
;                         else if (pn <= 4) {
;                             const bool isv = (pn == 4 && bj == 1);
;                             if (!isv && (wc & 1) == 0) {
;                                 const int tix = row < cfg::MP ? (row & 2047) : 2048 + (row & 3);
;                                 const f32x4 cs = *(const f32x4*)(ropec + tix * 8 + 4 * n), sn = *(const f32x4*)(ropes + tix * 8 + 4 * n);
; #pragma unroll
;                                 for (int i = 0; i < 4; ++i) { const float p = shx16(v[i], fq & 1); const float rv = v[i] * cs[i] + (fq == 0 ? -p : p) * sn[i]; v[i] = fq < 2 ? rv : v[i]; }
;                             }
;                             if (pn < 4) st_bf4(Q + (size_t)row * 512 + (pn - 2) * 256 + tc, v);
.Lsp_q0:
	s_nop 7
	v_mov_b32_e32 v232, v172
	v_cmp_gt_i32_e32 vcc, 0x4000, v232
	v_and_b32_e32 v233, 0x7ff, v232
	s_nop 0
	v_cndmask_b32_e32 v233, v151, v233, vcc
	v_lshlrev_b32_e32 v224, 5, v233
	v_or_b32_e32 v232, 16, v172
	v_cmp_gt_i32_e32 vcc, 0x4000, v232
	v_and_b32_e32 v233, 0x7ff, v232
	s_nop 0
	v_cndmask_b32_e32 v233, v151, v233, vcc
	v_lshlrev_b32_e32 v225, 5, v233
	v_or_b32_e32 v232, 32, v172
	v_cmp_gt_i32_e32 vcc, 0x4000, v232
	v_and_b32_e32 v233, 0x7ff, v232
	s_nop 0
	v_cndmask_b32_e32 v233, v151, v233, vcc
	v_lshlrev_b32_e32 v226, 5, v233
	v_or_b32_e32 v232, 48, v172
	v_cmp_gt_i32_e32 vcc, 0x4000, v232
	v_and_b32_e32 v233, 0x7ff, v232
	s_nop 0
	v_cndmask_b32_e32 v233, v151, v233, vcc
	v_lshlrev_b32_e32 v227, 5, v233
	v_or_b32_e32 v232, 128, v172
	v_cmp_gt_i32_e32 vcc, 0x4000, v232
	v_and_b32_e32 v233, 0x7ff, v232
	s_nop 0
	v_cndmask_b32_e32 v233, v151, v233, vcc
	v_lshlrev_b32_e32 v228, 5, v233
	v_or_b32_e32 v232, 144, v172
	v_cmp_gt_i32_e32 vcc, 0x4000, v232
	v_and_b32_e32 v233, 0x7ff, v232
	s_nop 0
	v_cndmask_b32_e32 v233, v151, v233, vcc
	v_lshlrev_b32_e32 v229, 5, v233
	v_or_b32_e32 v232, 160, v172
	v_cmp_gt_i32_e32 vcc, 0x4000, v232
	v_and_b32_e32 v233, 0x7ff, v232
	s_nop 0
	v_cndmask_b32_e32 v233, v151, v233, vcc
	v_lshlrev_b32_e32 v230, 5, v233
	v_or_b32_e32 v232, 176, v172
	v_cmp_gt_i32_e32 vcc, 0x4000, v232
	v_and_b32_e32 v233, 0x7ff, v232
	s_nop 0
	v_cndmask_b32_e32 v233, v151, v233, vcc
	v_lshlrev_b32_e32 v231, 5, v233
	global_load_dwordx4 v[208:211], v224, s[44:45]
	global_load_dwordx4 v[212:215], v224, s[4:5]
	global_load_dwordx4 v[216:219], v224, s[44:45] offset:16
	global_load_dwordx4 v[220:223], v224, s[4:5] offset:16
	global_load_dwordx4 v[234:237], v225, s[44:45]
	global_load_dwordx4 v[238:241], v225, s[4:5]
	global_load_dwordx4 v[242:245], v225, s[44:45] offset:16
	global_load_dwordx4 v[246:249], v225, s[4:5] offset:16
	v_lshlrev_b32_e32 v96, 2, v203
	v_mov_b32_e32 v96, v126
	v_mov_b32_e32 v146, v126
	s_nop 1
	v_permlane16_swap_b32_e32 v96, v146
	v_cndmask_b32_e64 v96, v96, v146, s[6:7]
	v_cndmask_b32_e64 v147, v96, -v96, s[10:11]
	v_mov_b32_e32 v148, v126
	s_waitcnt vmcnt(4)
	v_mov_b32_e32 v146, v208
	v_mov_b32_e32 v149, v212
	v_pk_mul_f32 v[146:147], v[148:149], v[146:147]
	v_mov_b32_e32 v186, v127
	v_add_f32_e32 v96, v146, v147
	v_cndmask_b32_e64 v130, v126, v96, s[8:9]
	v_mov_b32_e32 v96, v127
	v_mov_b32_e32 v146, v127
	s_nop 1
	v_permlane16_swap_b32_e32 v96, v146
	v_cndmask_b32_e64 v96, v96, v146, s[6:7]
	v_cndmask_b32_e64 v147, v96, -v96, s[10:11]
	v_mov_b32_e32 v146, v209
	v_mov_b32_e32 v187, v213
	v_pk_mul_f32 v[146:147], v[186:187], v[146:147]
	v_mov_b32_e32 v148, v128
	v_add_f32_e32 v96, v146, v147
	v_cndmask_b32_e64 v131, v127, v96, s[8:9]
	v_mov_b32_e32 v96, v128
	v_mov_b32_e32 v146, v128
	s_nop 1
	v_permlane16_swap_b32_e32 v96, v146
	v_cndmask_b32_e64 v96, v96, v146, s[6:7]
	v_cndmask_b32_e64 v147, v96, -v96, s[10:11]
	v_mov_b32_e32 v149, v214
	v_mov_b32_e32 v146, v210
	v_pk_mul_f32 v[146:147], v[148:149], v[146:147]
	v_mov_b32_e32 v188, v129
	v_add_f32_e32 v96, v146, v147
	v_cndmask_b32_e64 v132, v128, v96, s[8:9]
	v_mov_b32_e32 v96, v129
	v_mov_b32_e32 v146, v129
	s_nop 1
	v_permlane16_swap_b32_e32 v96, v146
	v_cndmask_b32_e64 v96, v96, v146, s[6:7]
	v_cndmask_b32_e64 v147, v96, -v96, s[10:11]
	v_mov_b32_e32 v146, v211
	v_mov_b32_e32 v189, v215
	v_pk_mul_f32 v[146:147], v[188:189], v[146:147]
	v_mov_b32_e32 v173, v130
	v_add_f32_e32 v96, v146, v147
	v_cndmask_b32_e64 v133, v129, v96, s[8:9]
	v_mov_b32_e32 v205, v131
	v_mov_b32_e32 v204, v132
	v_mov_b32_e32 v206, v133
	v_lshl_add_u64 v[130:131], s[82:83], 0, v[174:175]
	v_lshl_add_u64 v[130:131], s[0:1], 1, v[130:131]
	v_lshlrev_b32_e32 v96, 1, v142
	v_lshl_add_u64 v[130:131], v[130:131], 0, v[96:97]
	v_cvt_pk_bf16_f32 v132, v173, v205
	v_cvt_pk_bf16_f32 v133, v204, v206
	global_store_dwordx2 v[130:131], v[132:133], off offset:-1024
	s_ashr_i32 s93, s0, 31
	s_mov_b32 s92, s0
	v_lshlrev_b32_e32 v130, 2, v142
	v_lshlrev_b32_e32 v96, 2, v203
	v_mov_b32_e32 v96, v122
	v_mov_b32_e32 v131, v122
	s_nop 1
	v_permlane16_swap_b32_e32 v96, v131
	v_cndmask_b32_e64 v96, v96, v131, s[6:7]
	v_cndmask_b32_e64 v147, v96, -v96, s[10:11]
	v_mov_b32_e32 v148, v122
	v_mov_b32_e32 v131, v123
	v_mov_b32_e32 v146, v216
	v_mov_b32_e32 v149, v220
	v_pk_mul_f32 v[146:147], v[148:149], v[146:147]
	v_mov_b32_e32 v186, v123
	v_add_f32_e32 v96, v146, v147
	v_cndmask_b32_e64 v126, v122, v96, s[8:9]
	v_mov_b32_e32 v96, v123
	s_nop 1
	v_permlane16_swap_b32_e32 v96, v131
	v_cndmask_b32_e64 v96, v96, v131, s[6:7]
	v_cndmask_b32_e64 v147, v96, -v96, s[10:11]
	v_mov_b32_e32 v146, v217
	v_mov_b32_e32 v187, v221
	v_pk_mul_f32 v[146:147], v[186:187], v[146:147]
	v_mov_b32_e32 v131, v124
	v_add_f32_e32 v96, v146, v147
	v_cndmask_b32_e64 v127, v123, v96, s[8:9]
	v_mov_b32_e32 v96, v124
	s_nop 1
	v_permlane16_swap_b32_e32 v96, v131
	v_cndmask_b32_e64 v96, v96, v131, s[6:7]
	v_cndmask_b32_e64 v147, v96, -v96, s[10:11]
	v_mov_b32_e32 v148, v124
	v_mov_b32_e32 v149, v222
	v_mov_b32_e32 v146, v218
	v_pk_mul_f32 v[146:147], v[148:149], v[146:147]
	v_mov_b32_e32 v131, v125
	v_add_f32_e32 v96, v146, v147
	v_cndmask_b32_e64 v128, v124, v96, s[8:9]
	v_mov_b32_e32 v96, v125
	s_nop 1
	v_permlane16_swap_b32_e32 v96, v131
	v_cndmask_b32_e64 v96, v96, v131, s[6:7]
	v_cndmask_b32_e64 v147, v96, -v96, s[10:11]
	v_mov_b32_e32 v188, v125
	v_mov_b32_e32 v146, v219
	v_mov_b32_e32 v189, v223
	v_pk_mul_f32 v[146:147], v[188:189], v[146:147]
	v_mov_b32_e32 v131, v126
	v_add_f32_e32 v96, v146, v147
	v_cndmask_b32_e64 v129, v125, v96, s[8:9]
	v_mov_b32_e32 v204, v127
	v_mov_b32_e32 v173, v128
	v_mov_b32_e32 v205, v129
; __device__ __forceinline__ float shx16(float v, int odd  ) { const unsigned x = __builtin_bit_cast(unsigned, v); auto r = __builtin_amdgcn_permlane16_swap(x, x, false, false); return __builtin_bit_cast(float, odd ? r[0] : r[1]); }
; __device__ __forceinline__ void st_bf4(bf16_t* p, const f32x4 v) { u32x2 w; w.x = cvt_pk_bf16(v[0], v[1]); w.y = cvt_pk_bf16(v[2], v[3]); *(u32x2*)p = w; }
;     __device__ __forceinline__ void operator()(const f32x4 (&acc)[2][2][4][2], const Unit& u, int wr, int wc, int fr, int fq) const {
;     ...
;             for (int m = 0; m < 4; ++m) { const int row = u.pm * 256 + ai * 128 + wr * 64 + m * 16 + fr;
; #pragma unroll
;                 for (int bj = 0; bj < 2; ++bj)
; #pragma unroll
;                     for (int n = 0; n < 2; ++n) { const int tc = bj * 128 + wc * 32 + 8 * fq + 4 * n; f32x4 v = acc[ai][bj][m][n];
;                         if (pn < 2) { *(f32x4*)(XA + (size_t)row * 512 + pn * 256 + tc) = v; }
;                         else if (pn <= 4) {
;                             const bool isv = (pn == 4 && bj == 1);
;                             if (!isv && (wc & 1) == 0) {
;                                 const int tix = row < cfg::MP ? (row & 2047) : 2048 + (row & 3);
;                                 const f32x4 cs = *(const f32x4*)(ropec + tix * 8 + 4 * n), sn = *(const f32x4*)(ropes + tix * 8 + 4 * n);
; #pragma unroll
;                                 for (int i = 0; i < 4; ++i) { const float p = shx16(v[i], fq & 1); const float rv = v[i] * cs[i] + (fq == 0 ? -p : p) * sn[i]; v[i] = fq < 2 ? rv : v[i]; }
;                             }
;                             if (pn < 4) st_bf4(Q + (size_t)row * 512 + (pn - 2) * 256 + tc, v);
	v_lshl_add_u64 v[126:127], s[82:83], 0, v[174:175]
	v_lshl_add_u64 v[126:127], s[0:1], 1, v[126:127]
	v_lshlrev_b32_e32 v96, 1, v142
	v_lshl_add_u64 v[126:127], v[126:127], 0, v[96:97]
	v_cvt_pk_bf16_f32 v128, v131, v204
	v_cvt_pk_bf16_f32 v129, v173, v205
	global_store_dwordx2 v[126:127], v[128:129], off offset:-1016
	v_readlane_b32 s70, v254, 59
	v_readlane_b32 s71, v254, 60
	v_lshlrev_b32_e32 v96, 2, v203
	v_mov_b32_e32 v96, v118
	v_mov_b32_e32 v128, v118
	s_nop 1
	v_permlane16_swap_b32_e32 v96, v128
	v_cndmask_b32_e64 v96, v96, v128, s[6:7]
	v_cndmask_b32_e64 v129, v96, -v96, s[10:11]
	v_mov_b32_e32 v146, v118
	v_mov_b32_e32 v128, v208
	v_mov_b32_e32 v147, v212
	v_pk_mul_f32 v[128:129], v[146:147], v[128:129]
	v_mov_b32_e32 v182, v119
	v_add_f32_e32 v96, v128, v129
	v_cndmask_b32_e64 v122, v118, v96, s[8:9]
	v_mov_b32_e32 v96, v119
	v_mov_b32_e32 v128, v119
	s_nop 1
	v_permlane16_swap_b32_e32 v96, v128
	v_cndmask_b32_e64 v96, v96, v128, s[6:7]
	v_cndmask_b32_e64 v129, v96, -v96, s[10:11]
	v_mov_b32_e32 v128, v209
	v_mov_b32_e32 v183, v213
	v_pk_mul_f32 v[128:129], v[182:183], v[128:129]
	v_mov_b32_e32 v146, v120
	v_add_f32_e32 v96, v128, v129
	v_cndmask_b32_e64 v123, v119, v96, s[8:9]
	v_mov_b32_e32 v96, v120
	v_mov_b32_e32 v128, v120
	s_nop 1
	v_permlane16_swap_b32_e32 v96, v128
	v_cndmask_b32_e64 v96, v96, v128, s[6:7]
	v_cndmask_b32_e64 v129, v96, -v96, s[10:11]
	v_mov_b32_e32 v147, v214
	v_mov_b32_e32 v128, v210
	v_pk_mul_f32 v[128:129], v[146:147], v[128:129]
	v_mov_b32_e32 v184, v121
	v_add_f32_e32 v96, v128, v129
	v_cndmask_b32_e64 v124, v120, v96, s[8:9]
	v_mov_b32_e32 v96, v121
	v_mov_b32_e32 v128, v121
	s_nop 1
	v_permlane16_swap_b32_e32 v96, v128
	v_cndmask_b32_e64 v96, v96, v128, s[6:7]
	v_cndmask_b32_e64 v129, v96, -v96, s[10:11]
	v_mov_b32_e32 v128, v211
	v_mov_b32_e32 v185, v215
	v_pk_mul_f32 v[128:129], v[184:185], v[128:129]
	v_mov_b32_e32 v131, v122
	v_add_f32_e32 v96, v128, v129
	v_cndmask_b32_e64 v125, v121, v96, s[8:9]
	v_mov_b32_e32 v184, v123
	v_mov_b32_e32 v173, v124
	v_mov_b32_e32 v185, v125
	v_lshl_add_u64 v[122:123], s[82:83], 0, v[174:175]
	v_lshl_add_u64 v[122:123], s[0:1], 1, v[122:123]
	v_lshlrev_b32_e32 v96, 1, v142
	v_lshl_add_u64 v[122:123], v[122:123], 0, v[96:97]
	v_cvt_pk_bf16_f32 v124, v131, v184
	v_cvt_pk_bf16_f32 v125, v173, v185
	global_store_dwordx2 v[122:123], v[124:125], off offset:-768
	v_lshlrev_b32_e32 v96, 2, v203
	v_mov_b32_e32 v96, v114
	v_mov_b32_e32 v128, v114
	s_nop 1
	v_permlane16_swap_b32_e32 v96, v128
	v_cndmask_b32_e64 v96, v96, v128, s[6:7]
	v_cndmask_b32_e64 v129, v96, -v96, s[10:11]
	v_mov_b32_e32 v146, v114
	v_mov_b32_e32 v128, v216
	v_mov_b32_e32 v147, v220
	v_pk_mul_f32 v[128:129], v[146:147], v[128:129]
	v_mov_b32_e32 v122, v115
	v_add_f32_e32 v96, v128, v129
	v_cndmask_b32_e64 v118, v114, v96, s[8:9]
	v_mov_b32_e32 v96, v115
	s_nop 1
	v_permlane16_swap_b32_e32 v96, v122
	v_cndmask_b32_e64 v96, v96, v122, s[6:7]
	v_cndmask_b32_e64 v129, v96, -v96, s[10:11]
	v_mov_b32_e32 v122, v115
	v_mov_b32_e32 v128, v217
	v_mov_b32_e32 v123, v221
	v_pk_mul_f32 v[122:123], v[122:123], v[128:129]
	v_mov_b32_e32 v128, v116
	v_add_f32_e32 v96, v122, v123
	v_cndmask_b32_e64 v119, v115, v96, s[8:9]
	v_mov_b32_e32 v96, v116
	v_mov_b32_e32 v122, v116
	s_nop 1
	v_permlane16_swap_b32_e32 v96, v122
	v_cndmask_b32_e64 v96, v96, v122, s[6:7]
	v_cndmask_b32_e64 v123, v96, -v96, s[10:11]
	v_mov_b32_e32 v129, v222
	v_mov_b32_e32 v122, v218
	v_pk_mul_f32 v[122:123], v[128:129], v[122:123]
	v_mov_b32_e32 v124, v117
	v_add_f32_e32 v96, v122, v123
	v_cndmask_b32_e64 v120, v116, v96, s[8:9]
	v_mov_b32_e32 v96, v117
	v_mov_b32_e32 v122, v117
	s_nop 1
	v_permlane16_swap_b32_e32 v96, v122
	v_cndmask_b32_e64 v96, v96, v122, s[6:7]
	v_cndmask_b32_e64 v123, v96, -v96, s[10:11]
	v_mov_b32_e32 v122, v219
	v_mov_b32_e32 v125, v223
	v_pk_mul_f32 v[122:123], v[124:125], v[122:123]
	v_mov_b32_e32 v128, v118
	v_add_f32_e32 v96, v122, v123
	v_cndmask_b32_e64 v121, v117, v96, s[8:9]
	v_mov_b32_e32 v131, v119
	v_mov_b32_e32 v129, v120
	v_mov_b32_e32 v173, v121
	s_mov_b64 s[70:71], -1
	s_andn2_b64 vcc, exec, s[70:71]
	v_lshl_add_u64 v[118:119], s[82:83], 0, v[174:175]
	v_lshl_add_u64 v[118:119], s[0:1], 1, v[118:119]
	v_lshlrev_b32_e32 v96, 1, v142
	v_lshl_add_u64 v[118:119], v[118:119], 0, v[96:97]
	v_cvt_pk_bf16_f32 v120, v128, v131
	v_cvt_pk_bf16_f32 v121, v129, v173
	global_store_dwordx2 v[118:119], v[120:121], off offset:-760
	v_or_b32_e32 v114, 16, v172
	v_mad_i64_i32 v[124:125], s[18:19], v114, s61, 0
	s_movk_i32 s18, 0x7df
	s_nop 0
	v_bitop3_b32 v96, v172, s18, 16 bitop3:0xc8
	s_movk_i32 s18, 0x4000
	v_cmp_gt_i32_e32 vcc, s18, v114
	s_nop 1
	v_cndmask_b32_e32 v116, v151, v96, vcc
	v_ashrrev_i32_e32 v115, 31, v114
	v_lshlrev_b32_e32 v176, 3, v116
	v_add_u32_e32 v116, 0xffffc010, v172
	v_lshrrev_b32_e32 v173, 2, v116
	v_lshlrev_b64 v[118:119], 10, v[114:115]
	v_lshlrev_b32_e32 v96, 2, v176
	global_load_dwordx4 v[208:211], v226, s[44:45]
	global_load_dwordx4 v[212:215], v226, s[4:5]
	global_load_dwordx4 v[216:219], v226, s[44:45] offset:16
	global_load_dwordx4 v[220:223], v226, s[4:5] offset:16
	v_mov_b32_e32 v96, v110
	v_mov_b32_e32 v131, v110
	s_nop 1
	v_permlane16_swap_b32_e32 v96, v131
	v_cndmask_b32_e64 v96, v96, v131, s[6:7]
	v_cndmask_b32_e64 v133, v96, -v96, s[10:11]
	v_mov_b32_e32 v146, v110
	v_mov_b32_e32 v131, v111
	s_waitcnt vmcnt(8)
; __device__ __forceinline__ float shx16(float v, int odd  ) { const unsigned x = __builtin_bit_cast(unsigned, v); auto r = __builtin_amdgcn_permlane16_swap(x, x, false, false); return __builtin_bit_cast(float, odd ? r[0] : r[1]); }
; __device__ __forceinline__ void st_bf4(bf16_t* p, const f32x4 v) { u32x2 w; w.x = cvt_pk_bf16(v[0], v[1]); w.y = cvt_pk_bf16(v[2], v[3]); *(u32x2*)p = w; }
;     __device__ __forceinline__ void operator()(const f32x4 (&acc)[2][2][4][2], const Unit& u, int wr, int wc, int fr, int fq) const {
;     ...
;                                 const int tix = row < cfg::MP ? (row & 2047) : 2048 + (row & 3);
;                                 const f32x4 cs = *(const f32x4*)(ropec + tix * 8 + 4 * n), sn = *(const f32x4*)(ropes + tix * 8 + 4 * n);
; #pragma unroll
;                                 for (int i = 0; i < 4; ++i) { const float p = shx16(v[i], fq & 1); const float rv = v[i] * cs[i] + (fq == 0 ? -p : p) * sn[i]; v[i] = fq < 2 ? rv : v[i]; }
;                             }
;                             if (pn < 4) st_bf4(Q + (size_t)row * 512 + (pn - 2) * 256 + tc, v);
	v_mov_b32_e32 v132, v234
	v_mov_b32_e32 v147, v238
	v_pk_mul_f32 v[132:133], v[146:147], v[132:133]
	v_mov_b32_e32 v178, v111
	v_add_f32_e32 v96, v132, v133
	v_cndmask_b32_e64 v114, v110, v96, s[8:9]
	v_mov_b32_e32 v96, v111
	s_nop 1
	v_permlane16_swap_b32_e32 v96, v131
	v_cndmask_b32_e64 v96, v96, v131, s[6:7]
	v_cndmask_b32_e64 v133, v96, -v96, s[10:11]
	v_mov_b32_e32 v132, v235
	v_mov_b32_e32 v179, v239
	v_pk_mul_f32 v[132:133], v[178:179], v[132:133]
	v_mov_b32_e32 v131, v112
	v_add_f32_e32 v96, v132, v133
	v_cndmask_b32_e64 v115, v111, v96, s[8:9]
	v_mov_b32_e32 v96, v112
	s_nop 1
	v_permlane16_swap_b32_e32 v96, v131
	v_cndmask_b32_e64 v96, v96, v131, s[6:7]
	v_cndmask_b32_e64 v133, v96, -v96, s[10:11]
	v_mov_b32_e32 v146, v112
	v_mov_b32_e32 v147, v240
	v_mov_b32_e32 v132, v236
	v_pk_mul_f32 v[132:133], v[146:147], v[132:133]
	v_mov_b32_e32 v131, v113
	v_add_f32_e32 v96, v132, v133
	v_cndmask_b32_e64 v116, v112, v96, s[8:9]
	v_mov_b32_e32 v96, v113
	s_nop 1
	v_permlane16_swap_b32_e32 v96, v131
	v_cndmask_b32_e64 v96, v96, v131, s[6:7]
	v_cndmask_b32_e64 v133, v96, -v96, s[10:11]
	v_mov_b32_e32 v180, v113
	v_mov_b32_e32 v132, v237
	v_mov_b32_e32 v181, v241
	v_pk_mul_f32 v[132:133], v[180:181], v[132:133]
	v_mov_b32_e32 v131, v114
	v_add_f32_e32 v96, v132, v133
	v_cndmask_b32_e64 v117, v113, v96, s[8:9]
	v_mov_b32_e32 v178, v115
	v_mov_b32_e32 v177, v116
	v_mov_b32_e32 v179, v117
	v_lshl_add_u64 v[114:115], s[82:83], 0, v[118:119]
	v_lshl_add_u64 v[114:115], s[0:1], 1, v[114:115]
	v_lshlrev_b32_e32 v96, 1, v142
	v_lshl_add_u64 v[114:115], v[114:115], 0, v[96:97]
	v_cvt_pk_bf16_f32 v116, v131, v178
	v_cvt_pk_bf16_f32 v117, v177, v179
	global_store_dwordx2 v[114:115], v[116:117], off offset:-1024
	v_lshlrev_b32_e32 v96, 2, v176
	v_mov_b32_e32 v96, v106
	v_mov_b32_e32 v116, v106
	s_nop 1
	v_permlane16_swap_b32_e32 v96, v116
	v_cndmask_b32_e64 v96, v96, v116, s[6:7]
	v_cndmask_b32_e64 v117, v96, -v96, s[10:11]
	v_mov_b32_e32 v132, v106
	v_mov_b32_e32 v116, v242
	v_mov_b32_e32 v133, v246
	v_pk_mul_f32 v[116:117], v[132:133], v[116:117]
	v_mov_b32_e32 v178, v107
	v_add_f32_e32 v96, v116, v117
	v_cndmask_b32_e64 v110, v106, v96, s[8:9]
	v_mov_b32_e32 v96, v107
	v_mov_b32_e32 v116, v107
	s_nop 1
	v_permlane16_swap_b32_e32 v96, v116
	v_cndmask_b32_e64 v96, v96, v116, s[6:7]
	v_cndmask_b32_e64 v117, v96, -v96, s[10:11]
	v_mov_b32_e32 v116, v243
	v_mov_b32_e32 v179, v247
	v_pk_mul_f32 v[116:117], v[178:179], v[116:117]
	v_mov_b32_e32 v132, v108
	v_add_f32_e32 v96, v116, v117
	v_cndmask_b32_e64 v111, v107, v96, s[8:9]
	v_mov_b32_e32 v96, v108
	v_mov_b32_e32 v116, v108
	s_nop 1
	v_permlane16_swap_b32_e32 v96, v116
	v_cndmask_b32_e64 v96, v96, v116, s[6:7]
	v_cndmask_b32_e64 v117, v96, -v96, s[10:11]
	v_mov_b32_e32 v133, v248
	v_mov_b32_e32 v116, v244
	v_pk_mul_f32 v[116:117], v[132:133], v[116:117]
	v_mov_b32_e32 v180, v109
	v_add_f32_e32 v96, v116, v117
	v_cndmask_b32_e64 v112, v108, v96, s[8:9]
	v_mov_b32_e32 v96, v109
	v_mov_b32_e32 v116, v109
	s_nop 1
	v_permlane16_swap_b32_e32 v96, v116
	v_cndmask_b32_e64 v96, v96, v116, s[6:7]
	v_cndmask_b32_e64 v117, v96, -v96, s[10:11]
	v_mov_b32_e32 v116, v245
	v_mov_b32_e32 v181, v249
	v_pk_mul_f32 v[116:117], v[180:181], v[116:117]
	v_mov_b32_e32 v131, v110
	v_add_f32_e32 v96, v116, v117
	v_cndmask_b32_e64 v113, v109, v96, s[8:9]
	v_mov_b32_e32 v175, v111
	v_mov_b32_e32 v174, v112
	v_mov_b32_e32 v177, v113
	v_lshl_add_u64 v[110:111], s[82:83], 0, v[118:119]
	v_lshl_add_u64 v[110:111], s[0:1], 1, v[110:111]
	v_lshlrev_b32_e32 v96, 1, v142
	v_lshl_add_u64 v[110:111], v[110:111], 0, v[96:97]
	v_cvt_pk_bf16_f32 v112, v131, v175
	v_cvt_pk_bf16_f32 v113, v174, v177
	global_store_dwordx2 v[110:111], v[112:113], off offset:-1016
	v_lshlrev_b32_e32 v96, 2, v176
	v_mov_b32_e32 v96, v102
	v_mov_b32_e32 v112, v102
	s_nop 1
	v_permlane16_swap_b32_e32 v96, v112
	v_cndmask_b32_e64 v96, v96, v112, s[6:7]
	v_cndmask_b32_e64 v113, v96, -v96, s[10:11]
	v_mov_b32_e32 v116, v102
	v_mov_b32_e32 v112, v234
	v_mov_b32_e32 v117, v238
	v_pk_mul_f32 v[112:113], v[116:117], v[112:113]
	v_mov_b32_e32 v126, v103
	v_add_f32_e32 v96, v112, v113
	v_cndmask_b32_e64 v106, v102, v96, s[8:9]
	v_mov_b32_e32 v96, v103
	v_mov_b32_e32 v112, v103
	s_nop 1
	v_permlane16_swap_b32_e32 v96, v112
	v_cndmask_b32_e64 v96, v96, v112, s[6:7]
	v_cndmask_b32_e64 v113, v96, -v96, s[10:11]
	v_mov_b32_e32 v112, v235
	v_mov_b32_e32 v127, v239
	v_pk_mul_f32 v[112:113], v[126:127], v[112:113]
	v_mov_b32_e32 v116, v104
	v_add_f32_e32 v96, v112, v113
	v_cndmask_b32_e64 v107, v103, v96, s[8:9]
	v_mov_b32_e32 v96, v104
	v_mov_b32_e32 v112, v104
	s_nop 1
	v_permlane16_swap_b32_e32 v96, v112
	v_cndmask_b32_e64 v96, v96, v112, s[6:7]
	v_cndmask_b32_e64 v113, v96, -v96, s[10:11]
	v_mov_b32_e32 v117, v240
	v_mov_b32_e32 v112, v236
	v_pk_mul_f32 v[112:113], v[116:117], v[112:113]
	v_mov_b32_e32 v128, v105
	v_add_f32_e32 v96, v112, v113
	v_cndmask_b32_e64 v108, v104, v96, s[8:9]
	v_mov_b32_e32 v96, v105
	v_mov_b32_e32 v112, v105
	s_nop 1
	v_permlane16_swap_b32_e32 v96, v112
	v_cndmask_b32_e64 v96, v96, v112, s[6:7]
	v_cndmask_b32_e64 v113, v96, -v96, s[10:11]
	v_mov_b32_e32 v112, v237
	v_mov_b32_e32 v129, v241
	v_pk_mul_f32 v[112:113], v[128:129], v[112:113]
	v_mov_b32_e32 v126, v106
	v_add_f32_e32 v96, v112, v113
	v_cndmask_b32_e64 v109, v105, v96, s[8:9]
	v_mov_b32_e32 v128, v107
	v_mov_b32_e32 v127, v108
	v_mov_b32_e32 v129, v109
	v_lshl_add_u64 v[106:107], s[82:83], 0, v[118:119]
	v_lshl_add_u64 v[106:107], s[0:1], 1, v[106:107]
	v_lshlrev_b32_e32 v96, 1, v142
	v_lshl_add_u64 v[106:107], v[106:107], 0, v[96:97]
	v_cvt_pk_bf16_f32 v108, v126, v128
; __device__ __forceinline__ float shx16(float v, int odd  ) { const unsigned x = __builtin_bit_cast(unsigned, v); auto r = __builtin_amdgcn_permlane16_swap(x, x, false, false); return __builtin_bit_cast(float, odd ? r[0] : r[1]); }
; __device__ __forceinline__ void st_bf4(bf16_t* p, const f32x4 v) { u32x2 w; w.x = cvt_pk_bf16(v[0], v[1]); w.y = cvt_pk_bf16(v[2], v[3]); *(u32x2*)p = w; }
;     __device__ __forceinline__ void operator()(const f32x4 (&acc)[2][2][4][2], const Unit& u, int wr, int wc, int fr, int fq) const {
;     ...
;                                 const int tix = row < cfg::MP ? (row & 2047) : 2048 + (row & 3);
;                                 const f32x4 cs = *(const f32x4*)(ropec + tix * 8 + 4 * n), sn = *(const f32x4*)(ropes + tix * 8 + 4 * n);
; #pragma unroll
;                                 for (int i = 0; i < 4; ++i) { const float p = shx16(v[i], fq & 1); const float rv = v[i] * cs[i] + (fq == 0 ? -p : p) * sn[i]; v[i] = fq < 2 ? rv : v[i]; }
;                             }
;                             if (pn < 4) st_bf4(Q + (size_t)row * 512 + (pn - 2) * 256 + tc, v);
	v_cvt_pk_bf16_f32 v109, v127, v129
	global_store_dwordx2 v[106:107], v[108:109], off offset:-768
	v_lshlrev_b32_e32 v96, 2, v176
	v_mov_b32_e32 v96, v98
	v_mov_b32_e32 v112, v98
	s_nop 1
	v_permlane16_swap_b32_e32 v96, v112
	v_cndmask_b32_e64 v96, v96, v112, s[6:7]
	v_cndmask_b32_e64 v113, v96, -v96, s[10:11]
	v_mov_b32_e32 v116, v98
	v_mov_b32_e32 v112, v242
	v_mov_b32_e32 v117, v246
	v_pk_mul_f32 v[112:113], v[116:117], v[112:113]
	v_mov_b32_e32 v106, v99
	v_add_f32_e32 v96, v112, v113
	v_cndmask_b32_e64 v102, v98, v96, s[8:9]
	v_mov_b32_e32 v96, v99
	s_nop 1
	v_permlane16_swap_b32_e32 v96, v106
	v_cndmask_b32_e64 v96, v96, v106, s[6:7]
	v_cndmask_b32_e64 v113, v96, -v96, s[10:11]
	v_mov_b32_e32 v106, v99
	v_mov_b32_e32 v112, v243
	v_mov_b32_e32 v107, v247
	v_pk_mul_f32 v[106:107], v[106:107], v[112:113]
	v_mov_b32_e32 v112, v100
	v_add_f32_e32 v96, v106, v107
	v_cndmask_b32_e64 v103, v99, v96, s[8:9]
	v_mov_b32_e32 v96, v100
	v_mov_b32_e32 v106, v100
	s_nop 1
	v_permlane16_swap_b32_e32 v96, v106
	v_cndmask_b32_e64 v96, v96, v106, s[6:7]
	v_cndmask_b32_e64 v107, v96, -v96, s[10:11]
	v_mov_b32_e32 v113, v248
	v_mov_b32_e32 v106, v244
	v_pk_mul_f32 v[106:107], v[112:113], v[106:107]
	v_mov_b32_e32 v108, v101
	v_add_f32_e32 v96, v106, v107
	v_cndmask_b32_e64 v104, v100, v96, s[8:9]
	v_mov_b32_e32 v96, v101
	v_mov_b32_e32 v106, v101
	s_nop 1
	v_permlane16_swap_b32_e32 v96, v106
	v_cndmask_b32_e64 v96, v96, v106, s[6:7]
	v_cndmask_b32_e64 v107, v96, -v96, s[10:11]
	v_mov_b32_e32 v106, v245
	v_mov_b32_e32 v109, v249
	v_pk_mul_f32 v[106:107], v[108:109], v[106:107]
	v_mov_b32_e32 v112, v102
	v_add_f32_e32 v96, v106, v107
	v_cndmask_b32_e64 v105, v101, v96, s[8:9]
	v_mov_b32_e32 v116, v103
	v_mov_b32_e32 v113, v104
	v_mov_b32_e32 v117, v105
	s_mov_b64 s[70:71], -1
	s_andn2_b64 vcc, exec, s[70:71]
	v_lshl_add_u64 v[102:103], s[82:83], 0, v[118:119]
	v_lshl_add_u64 v[102:103], s[0:1], 1, v[102:103]
	v_lshlrev_b32_e32 v96, 1, v142
	v_lshl_add_u64 v[102:103], v[102:103], 0, v[96:97]
	v_cvt_pk_bf16_f32 v104, v112, v116
	v_cvt_pk_bf16_f32 v105, v113, v117
	global_store_dwordx2 v[102:103], v[104:105], off offset:-760
	v_or_b32_e32 v98, 32, v172
	v_mad_i64_i32 v[108:109], s[18:19], v98, s61, 0
	s_movk_i32 s18, 0x7ef
	s_nop 0
	v_bitop3_b32 v96, v172, s18, 32 bitop3:0xc8
	s_movk_i32 s18, 0x4000
	v_cmp_gt_i32_e32 vcc, s18, v98
	s_nop 1
	v_cndmask_b32_e32 v100, v151, v96, vcc
	v_ashrrev_i32_e32 v99, 31, v98
	v_lshlrev_b32_e32 v119, 3, v100
	v_add_u32_e32 v100, 0xffffc020, v172
	v_lshrrev_b32_e32 v118, 2, v100
	v_lshlrev_b64 v[102:103], 10, v[98:99]
	v_lshlrev_b32_e32 v96, 2, v119
	global_load_dwordx4 v[234:237], v227, s[44:45]
	global_load_dwordx4 v[238:241], v227, s[4:5]
	global_load_dwordx4 v[242:245], v227, s[44:45] offset:16
	global_load_dwordx4 v[246:249], v227, s[4:5] offset:16
	v_mov_b32_e32 v96, v92
	v_mov_b32_e32 v120, v92
	s_nop 1
	v_permlane16_swap_b32_e32 v96, v120
	v_cndmask_b32_e64 v96, v96, v120, s[6:7]
	v_cndmask_b32_e64 v121, v96, -v96, s[10:11]
	v_mov_b32_e32 v122, v92
	s_waitcnt vmcnt(8)
	v_mov_b32_e32 v120, v208
	v_mov_b32_e32 v123, v212
	v_pk_mul_f32 v[120:121], v[122:123], v[120:121]
	v_mov_b32_e32 v114, v93
	v_add_f32_e32 v96, v120, v121
	v_cndmask_b32_e64 v98, v92, v96, s[8:9]
	v_mov_b32_e32 v96, v93
	s_nop 1
	v_permlane16_swap_b32_e32 v96, v114
	v_cndmask_b32_e64 v96, v96, v114, s[6:7]
	v_cndmask_b32_e64 v121, v96, -v96, s[10:11]
	v_mov_b32_e32 v114, v93
	v_mov_b32_e32 v120, v209
	v_mov_b32_e32 v115, v213
	v_pk_mul_f32 v[114:115], v[114:115], v[120:121]
	v_mov_b32_e32 v120, v94
	v_add_f32_e32 v96, v114, v115
	v_cndmask_b32_e64 v99, v93, v96, s[8:9]
	v_mov_b32_e32 v96, v94
	v_mov_b32_e32 v114, v94
	s_nop 1
	v_permlane16_swap_b32_e32 v96, v114
	v_cndmask_b32_e64 v96, v96, v114, s[6:7]
	v_cndmask_b32_e64 v115, v96, -v96, s[10:11]
	v_mov_b32_e32 v121, v214
	v_mov_b32_e32 v114, v210
	v_pk_mul_f32 v[114:115], v[120:121], v[114:115]
	v_mov_b32_e32 v116, v95
	v_add_f32_e32 v96, v114, v115
	v_cndmask_b32_e64 v100, v94, v96, s[8:9]
	v_mov_b32_e32 v96, v95
	v_mov_b32_e32 v114, v95
	s_nop 1
	v_permlane16_swap_b32_e32 v96, v114
	v_cndmask_b32_e64 v96, v96, v114, s[6:7]
	v_cndmask_b32_e64 v115, v96, -v96, s[10:11]
	v_mov_b32_e32 v114, v211
	v_mov_b32_e32 v117, v215
	v_pk_mul_f32 v[114:115], v[116:117], v[114:115]
	v_mov_b32_e32 v120, v98
	v_add_f32_e32 v96, v114, v115
	v_cndmask_b32_e64 v101, v95, v96, s[8:9]
	v_mov_b32_e32 v122, v99
	v_mov_b32_e32 v121, v100
	v_mov_b32_e32 v123, v101
	v_lshl_add_u64 v[98:99], s[82:83], 0, v[102:103]
	v_lshl_add_u64 v[98:99], s[0:1], 1, v[98:99]
	v_lshlrev_b32_e32 v96, 1, v142
	v_lshl_add_u64 v[98:99], v[98:99], 0, v[96:97]
	v_cvt_pk_bf16_f32 v100, v120, v122
	v_cvt_pk_bf16_f32 v101, v121, v123
	global_store_dwordx2 v[98:99], v[100:101], off offset:-1024
	v_lshlrev_b32_e32 v96, 2, v119
	v_mov_b32_e32 v96, v88
	v_mov_b32_e32 v100, v88
	s_nop 1
	v_permlane16_swap_b32_e32 v96, v100
	v_cndmask_b32_e64 v96, v96, v100, s[6:7]
	v_cndmask_b32_e64 v101, v96, -v96, s[10:11]
	v_mov_b32_e32 v120, v88
	v_mov_b32_e32 v96, v89
	v_mov_b32_e32 v100, v216
	v_mov_b32_e32 v121, v220
	v_pk_mul_f32 v[100:101], v[120:121], v[100:101]
	v_mov_b32_e32 v114, v89
	v_add_f32_e32 v92, v100, v101
	v_mov_b32_e32 v100, v89
	s_nop 1
	v_permlane16_swap_b32_e32 v96, v100
	v_cndmask_b32_e64 v96, v96, v100, s[6:7]
	v_cndmask_b32_e64 v101, v96, -v96, s[10:11]
	v_mov_b32_e32 v100, v217
	v_mov_b32_e32 v115, v221
	v_pk_mul_f32 v[100:101], v[114:115], v[100:101]
	v_mov_b32_e32 v96, v90
	v_add_f32_e32 v93, v100, v101
	v_mov_b32_e32 v100, v90
	s_nop 1
	v_permlane16_swap_b32_e32 v96, v100
	v_cndmask_b32_e64 v96, v96, v100, s[6:7]
; __device__ __forceinline__ float shx16(float v, int odd  ) { const unsigned x = __builtin_bit_cast(unsigned, v); auto r = __builtin_amdgcn_permlane16_swap(x, x, false, false); return __builtin_bit_cast(float, odd ? r[0] : r[1]); }
; __device__ __forceinline__ void st_bf4(bf16_t* p, const f32x4 v) { u32x2 w; w.x = cvt_pk_bf16(v[0], v[1]); w.y = cvt_pk_bf16(v[2], v[3]); *(u32x2*)p = w; }
;     __device__ __forceinline__ void operator()(const f32x4 (&acc)[2][2][4][2], const Unit& u, int wr, int wc, int fr, int fq) const {
;     ...
;                                 const int tix = row < cfg::MP ? (row & 2047) : 2048 + (row & 3);
;                                 const f32x4 cs = *(const f32x4*)(ropec + tix * 8 + 4 * n), sn = *(const f32x4*)(ropes + tix * 8 + 4 * n);
; #pragma unroll
;                                 for (int i = 0; i < 4; ++i) { const float p = shx16(v[i], fq & 1); const float rv = v[i] * cs[i] + (fq == 0 ? -p : p) * sn[i]; v[i] = fq < 2 ? rv : v[i]; }
;                             }
;                             if (pn < 4) st_bf4(Q + (size_t)row * 512 + (pn - 2) * 256 + tc, v);
	v_cndmask_b32_e64 v101, v96, -v96, s[10:11]
	v_mov_b32_e32 v114, v90
	v_mov_b32_e32 v115, v222
	v_mov_b32_e32 v100, v218
	v_pk_mul_f32 v[100:101], v[114:115], v[100:101]
	v_mov_b32_e32 v96, v91
	v_add_f32_e32 v94, v100, v101
	v_mov_b32_e32 v100, v91
	s_nop 1
	v_permlane16_swap_b32_e32 v96, v100
	v_cndmask_b32_e64 v96, v96, v100, s[6:7]
	v_cndmask_b32_e64 v101, v96, -v96, s[10:11]
	v_mov_b32_e32 v116, v91
	v_mov_b32_e32 v100, v219
	v_mov_b32_e32 v117, v223
	v_pk_mul_f32 v[100:101], v[116:117], v[100:101]
	v_cndmask_b32_e64 v92, v88, v92, s[8:9]
	v_add_f32_e32 v95, v100, v101
	v_cndmask_b32_e64 v93, v89, v93, s[8:9]
	v_cndmask_b32_e64 v94, v90, v94, s[8:9]
	v_cndmask_b32_e64 v95, v91, v95, s[8:9]
	v_mov_b32_e32 v116, v92
	v_mov_b32_e32 v120, v93
	v_mov_b32_e32 v117, v94
	v_mov_b32_e32 v121, v95
	v_lshl_add_u64 v[92:93], s[82:83], 0, v[102:103]
	v_lshl_add_u64 v[92:93], s[0:1], 1, v[92:93]
	v_lshlrev_b32_e32 v96, 1, v142
	v_lshl_add_u64 v[92:93], v[92:93], 0, v[96:97]
	v_cvt_pk_bf16_f32 v94, v116, v120
	v_cvt_pk_bf16_f32 v95, v117, v121
	global_store_dwordx2 v[92:93], v[94:95], off offset:-1016
	v_lshlrev_b32_e32 v94, 2, v119
	v_mov_b32_e32 v94, v84
	v_mov_b32_e32 v95, v84
	s_nop 1
	v_permlane16_swap_b32_e32 v94, v95
	v_cndmask_b32_e64 v94, v94, v95, s[6:7]
	v_cndmask_b32_e64 v95, v94, -v94, s[10:11]
	v_mov_b32_e32 v100, v84
	v_mov_b32_e32 v94, v208
	v_mov_b32_e32 v101, v212
	v_pk_mul_f32 v[94:95], v[100:101], v[94:95]
	v_mov_b32_e32 v110, v85
	v_add_f32_e32 v88, v94, v95
	v_mov_b32_e32 v94, v85
	v_mov_b32_e32 v95, v85
	s_nop 1
	v_permlane16_swap_b32_e32 v94, v95
	v_cndmask_b32_e64 v94, v94, v95, s[6:7]
	v_cndmask_b32_e64 v95, v94, -v94, s[10:11]
	v_mov_b32_e32 v94, v209
	v_mov_b32_e32 v111, v213
	v_pk_mul_f32 v[94:95], v[110:111], v[94:95]
	v_mov_b32_e32 v100, v86
	v_add_f32_e32 v89, v94, v95
	v_mov_b32_e32 v94, v86
	v_mov_b32_e32 v95, v86
	s_nop 1
	v_permlane16_swap_b32_e32 v94, v95
	v_cndmask_b32_e64 v94, v94, v95, s[6:7]
	v_cndmask_b32_e64 v95, v94, -v94, s[10:11]
	v_mov_b32_e32 v101, v214
	v_mov_b32_e32 v94, v210
	v_pk_mul_f32 v[94:95], v[100:101], v[94:95]
	v_mov_b32_e32 v112, v87
	v_add_f32_e32 v90, v94, v95
	v_mov_b32_e32 v94, v87
	v_mov_b32_e32 v95, v87
	s_nop 1
	v_permlane16_swap_b32_e32 v94, v95
	v_cndmask_b32_e64 v94, v94, v95, s[6:7]
	v_cndmask_b32_e64 v95, v94, -v94, s[10:11]
	v_mov_b32_e32 v94, v211
	v_mov_b32_e32 v113, v215
	v_pk_mul_f32 v[94:95], v[112:113], v[94:95]
	v_cndmask_b32_e64 v88, v84, v88, s[8:9]
	v_add_f32_e32 v91, v94, v95
	v_cndmask_b32_e64 v89, v85, v89, s[8:9]
	v_cndmask_b32_e64 v90, v86, v90, s[8:9]
	v_cndmask_b32_e64 v91, v87, v91, s[8:9]
	v_mov_b32_e32 v110, v88
	v_mov_b32_e32 v112, v89
	v_mov_b32_e32 v111, v90
	v_mov_b32_e32 v113, v91
	v_lshl_add_u64 v[88:89], s[82:83], 0, v[102:103]
	v_lshl_add_u64 v[88:89], s[0:1], 1, v[88:89]
	v_lshlrev_b32_e32 v96, 1, v142
	v_lshl_add_u64 v[88:89], v[88:89], 0, v[96:97]
	v_cvt_pk_bf16_f32 v90, v110, v112
	v_cvt_pk_bf16_f32 v91, v111, v113
	global_store_dwordx2 v[88:89], v[90:91], off offset:-768
	v_lshlrev_b32_e32 v88, 2, v119
	v_mov_b32_e32 v94, v80
	v_mov_b32_e32 v95, v80
	s_nop 1
	v_permlane16_swap_b32_e32 v94, v95
	v_cndmask_b32_e64 v94, v94, v95, s[6:7]
	v_cndmask_b32_e64 v95, v94, -v94, s[10:11]
	v_mov_b32_e32 v100, v80
	v_mov_b32_e32 v94, v216
	v_mov_b32_e32 v101, v220
	v_pk_mul_f32 v[94:95], v[100:101], v[94:95]
	v_mov_b32_e32 v88, v81
	v_add_f32_e32 v84, v94, v95
	v_mov_b32_e32 v94, v81
	s_nop 1
	v_permlane16_swap_b32_e32 v88, v94
	v_cndmask_b32_e64 v88, v88, v94, s[6:7]
	v_cndmask_b32_e64 v95, v88, -v88, s[10:11]
	v_mov_b32_e32 v88, v81
	v_mov_b32_e32 v94, v217
	v_mov_b32_e32 v89, v221
	v_pk_mul_f32 v[88:89], v[88:89], v[94:95]
	v_mov_b32_e32 v94, v82
	v_add_f32_e32 v85, v88, v89
	v_mov_b32_e32 v88, v82
	v_mov_b32_e32 v89, v82
	s_nop 1
	v_permlane16_swap_b32_e32 v88, v89
	v_cndmask_b32_e64 v88, v88, v89, s[6:7]
	v_cndmask_b32_e64 v89, v88, -v88, s[10:11]
	v_mov_b32_e32 v95, v222
	v_mov_b32_e32 v88, v218
	v_pk_mul_f32 v[88:89], v[94:95], v[88:89]
	v_mov_b32_e32 v90, v83
	v_add_f32_e32 v86, v88, v89
	v_mov_b32_e32 v88, v83
	v_mov_b32_e32 v89, v83
	s_nop 1
	v_permlane16_swap_b32_e32 v88, v89
	v_cndmask_b32_e64 v88, v88, v89, s[6:7]
	v_cndmask_b32_e64 v89, v88, -v88, s[10:11]
	v_mov_b32_e32 v88, v219
	v_mov_b32_e32 v91, v223
	v_pk_mul_f32 v[88:89], v[90:91], v[88:89]
	v_cndmask_b32_e64 v84, v80, v84, s[8:9]
	v_add_f32_e32 v87, v88, v89
	v_cndmask_b32_e64 v85, v81, v85, s[8:9]
	v_cndmask_b32_e64 v86, v82, v86, s[8:9]
	v_cndmask_b32_e64 v87, v83, v87, s[8:9]
	v_mov_b32_e32 v94, v84
	v_mov_b32_e32 v100, v85
	v_mov_b32_e32 v95, v86
	v_mov_b32_e32 v101, v87
	s_mov_b64 s[70:71], -1
	s_andn2_b64 vcc, exec, s[70:71]
	v_lshl_add_u64 v[84:85], s[82:83], 0, v[102:103]
	v_lshl_add_u64 v[84:85], s[0:1], 1, v[84:85]
	v_lshlrev_b32_e32 v96, 1, v142
	v_lshl_add_u64 v[84:85], v[84:85], 0, v[96:97]
	v_cvt_pk_bf16_f32 v86, v94, v100
	v_cvt_pk_bf16_f32 v87, v95, v101
	global_store_dwordx2 v[84:85], v[86:87], off offset:-760
	v_or_b32_e32 v80, 48, v172
	s_movk_i32 s18, 0x7ff
	v_bitop3_b32 v82, v172, s18, 48 bitop3:0xc8
	s_movk_i32 s18, 0x4000
	v_cmp_gt_i32_e32 vcc, s18, v80
	v_ashrrev_i32_e32 v81, 31, v80
	s_nop 0
	v_cndmask_b32_e32 v83, v151, v82, vcc
	v_lshlrev_b32_e32 v103, 3, v83
	v_add_u32_e32 v83, 0xffffc030, v172
	v_lshrrev_b32_e32 v102, 2, v83
	v_lshlrev_b64 v[84:85], 10, v[80:81]
	v_lshlrev_b32_e32 v96, 2, v103
	global_load_dwordx4 v[208:211], v228, s[44:45]
	global_load_dwordx4 v[212:215], v228, s[4:5]
	global_load_dwordx4 v[216:219], v228, s[44:45] offset:16
	global_load_dwordx4 v[220:223], v228, s[4:5] offset:16
	v_mov_b32_e32 v96, v76
	v_mov_b32_e32 v104, v76
	s_nop 1
	v_permlane16_swap_b32_e32 v96, v104
	v_cndmask_b32_e64 v96, v96, v104, s[6:7]
	v_cndmask_b32_e64 v105, v96, -v96, s[10:11]
	v_mov_b32_e32 v96, v77
	v_mov_b32_e32 v106, v76
	s_waitcnt vmcnt(8)
; __device__ __forceinline__ float shx16(float v, int odd  ) { const unsigned x = __builtin_bit_cast(unsigned, v); auto r = __builtin_amdgcn_permlane16_swap(x, x, false, false); return __builtin_bit_cast(float, odd ? r[0] : r[1]); }
; __device__ __forceinline__ void st_bf4(bf16_t* p, const f32x4 v) { u32x2 w; w.x = cvt_pk_bf16(v[0], v[1]); w.y = cvt_pk_bf16(v[2], v[3]); *(u32x2*)p = w; }
;     __device__ __forceinline__ void operator()(const f32x4 (&acc)[2][2][4][2], const Unit& u, int wr, int wc, int fr, int fq) const {
;     ...
;                                 const int tix = row < cfg::MP ? (row & 2047) : 2048 + (row & 3);
;                                 const f32x4 cs = *(const f32x4*)(ropec + tix * 8 + 4 * n), sn = *(const f32x4*)(ropes + tix * 8 + 4 * n);
; #pragma unroll
;                                 for (int i = 0; i < 4; ++i) { const float p = shx16(v[i], fq & 1); const float rv = v[i] * cs[i] + (fq == 0 ? -p : p) * sn[i]; v[i] = fq < 2 ? rv : v[i]; }
;                             }
;                             if (pn < 4) st_bf4(Q + (size_t)row * 512 + (pn - 2) * 256 + tc, v);
	v_mov_b32_e32 v104, v234
	v_mov_b32_e32 v107, v238
	v_mov_b32_e32 v98, v77
	s_nop 1
	v_permlane16_swap_b32_e32 v96, v98
	v_pk_mul_f32 v[104:105], v[106:107], v[104:105]
	v_cndmask_b32_e64 v96, v96, v98, s[6:7]
	v_add_f32_e32 v80, v104, v105
	v_cndmask_b32_e64 v105, v96, -v96, s[10:11]
	v_mov_b32_e32 v98, v77
	v_mov_b32_e32 v104, v235
	v_mov_b32_e32 v99, v239
	v_pk_mul_f32 v[98:99], v[98:99], v[104:105]
	v_mov_b32_e32 v96, v78
	v_add_f32_e32 v81, v98, v99
	v_mov_b32_e32 v98, v78
	s_nop 1
	v_permlane16_swap_b32_e32 v96, v98
	v_cndmask_b32_e64 v96, v96, v98, s[6:7]
	v_cndmask_b32_e64 v99, v96, -v96, s[10:11]
	v_mov_b32_e32 v104, v78
	v_mov_b32_e32 v105, v240
	v_mov_b32_e32 v98, v236
	v_pk_mul_f32 v[98:99], v[104:105], v[98:99]
	v_mov_b32_e32 v96, v79
	v_add_f32_e32 v82, v98, v99
	v_mov_b32_e32 v98, v79
	s_nop 1
	v_permlane16_swap_b32_e32 v96, v98
	v_cndmask_b32_e64 v96, v96, v98, s[6:7]
	v_cndmask_b32_e64 v99, v96, -v96, s[10:11]
	v_mov_b32_e32 v100, v79
	v_mov_b32_e32 v98, v237
	v_mov_b32_e32 v101, v241
	v_pk_mul_f32 v[98:99], v[100:101], v[98:99]
	v_cndmask_b32_e64 v80, v76, v80, s[8:9]
	v_add_f32_e32 v83, v98, v99
	v_cndmask_b32_e64 v81, v77, v81, s[8:9]
	v_cndmask_b32_e64 v82, v78, v82, s[8:9]
	v_cndmask_b32_e64 v83, v79, v83, s[8:9]
	v_mov_b32_e32 v104, v80
	v_mov_b32_e32 v106, v81
	v_mov_b32_e32 v105, v82
	v_mov_b32_e32 v107, v83
	v_lshl_add_u64 v[80:81], s[82:83], 0, v[84:85]
	v_lshl_add_u64 v[80:81], s[0:1], 1, v[80:81]
	v_lshlrev_b32_e32 v96, 1, v142
	v_lshl_add_u64 v[80:81], v[80:81], 0, v[96:97]
	v_cvt_pk_bf16_f32 v82, v104, v106
	v_cvt_pk_bf16_f32 v83, v105, v107
	global_store_dwordx2 v[80:81], v[82:83], off offset:-1024
	v_lshlrev_b32_e32 v82, 2, v103
	v_mov_b32_e32 v82, v72
	v_mov_b32_e32 v83, v72
	s_nop 1
	v_permlane16_swap_b32_e32 v82, v83
	v_cndmask_b32_e64 v82, v82, v83, s[6:7]
	v_cndmask_b32_e64 v83, v82, -v82, s[10:11]
	v_mov_b32_e32 v104, v72
	v_mov_b32_e32 v82, v242
	v_mov_b32_e32 v105, v246
	v_pk_mul_f32 v[82:83], v[104:105], v[82:83]
	v_mov_b32_e32 v98, v73
	v_add_f32_e32 v76, v82, v83
	v_mov_b32_e32 v82, v73
	v_mov_b32_e32 v83, v73
	s_nop 1
	v_permlane16_swap_b32_e32 v82, v83
	v_cndmask_b32_e64 v82, v82, v83, s[6:7]
	v_cndmask_b32_e64 v83, v82, -v82, s[10:11]
	v_mov_b32_e32 v82, v243
	v_mov_b32_e32 v99, v247
	v_pk_mul_f32 v[82:83], v[98:99], v[82:83]
	v_mov_b32_e32 v98, v74
	v_add_f32_e32 v77, v82, v83
	v_mov_b32_e32 v82, v74
	v_mov_b32_e32 v83, v74
	s_nop 1
	v_permlane16_swap_b32_e32 v82, v83
	v_cndmask_b32_e64 v82, v82, v83, s[6:7]
	v_cndmask_b32_e64 v83, v82, -v82, s[10:11]
	v_mov_b32_e32 v99, v248
	v_mov_b32_e32 v82, v244
	v_pk_mul_f32 v[82:83], v[98:99], v[82:83]
	v_mov_b32_e32 v100, v75
	v_add_f32_e32 v78, v82, v83
	v_mov_b32_e32 v82, v75
	v_mov_b32_e32 v83, v75
	s_nop 1
	v_permlane16_swap_b32_e32 v82, v83
	v_cndmask_b32_e64 v82, v82, v83, s[6:7]
	v_cndmask_b32_e64 v83, v82, -v82, s[10:11]
	v_mov_b32_e32 v82, v245
	v_mov_b32_e32 v101, v249
	v_pk_mul_f32 v[82:83], v[100:101], v[82:83]
	v_cndmask_b32_e64 v76, v72, v76, s[8:9]
	v_add_f32_e32 v79, v82, v83
	v_cndmask_b32_e64 v77, v73, v77, s[8:9]
	v_cndmask_b32_e64 v78, v74, v78, s[8:9]
	v_cndmask_b32_e64 v79, v75, v79, s[8:9]
	v_mov_b32_e32 v100, v76
	v_mov_b32_e32 v104, v77
	v_mov_b32_e32 v101, v78
	v_mov_b32_e32 v105, v79
	v_lshl_add_u64 v[76:77], s[82:83], 0, v[84:85]
	v_lshl_add_u64 v[76:77], s[0:1], 1, v[76:77]
	v_lshlrev_b32_e32 v96, 1, v142
	v_lshl_add_u64 v[76:77], v[76:77], 0, v[96:97]
	v_cvt_pk_bf16_f32 v78, v100, v104
	v_cvt_pk_bf16_f32 v79, v101, v105
	global_store_dwordx2 v[76:77], v[78:79], off offset:-1016
	v_lshlrev_b32_e32 v78, 2, v103
	v_mov_b32_e32 v78, v68
	v_mov_b32_e32 v79, v68
	s_nop 1
	v_permlane16_swap_b32_e32 v78, v79
	v_cndmask_b32_e64 v78, v78, v79, s[6:7]
	v_cndmask_b32_e64 v79, v78, -v78, s[10:11]
	v_mov_b32_e32 v82, v68
	v_mov_b32_e32 v78, v234
	v_mov_b32_e32 v83, v238
	v_pk_mul_f32 v[78:79], v[82:83], v[78:79]
	v_mov_b32_e32 v92, v69
	v_add_f32_e32 v72, v78, v79
	v_mov_b32_e32 v78, v69
	v_mov_b32_e32 v79, v69
	s_nop 1
	v_permlane16_swap_b32_e32 v78, v79
	v_cndmask_b32_e64 v78, v78, v79, s[6:7]
	v_cndmask_b32_e64 v79, v78, -v78, s[10:11]
	v_mov_b32_e32 v78, v235
	v_mov_b32_e32 v93, v239
	v_pk_mul_f32 v[78:79], v[92:93], v[78:79]
	v_mov_b32_e32 v82, v70
	v_add_f32_e32 v73, v78, v79
	v_mov_b32_e32 v78, v70
	v_mov_b32_e32 v79, v70
	s_nop 1
	v_permlane16_swap_b32_e32 v78, v79
	v_cndmask_b32_e64 v78, v78, v79, s[6:7]
	v_cndmask_b32_e64 v79, v78, -v78, s[10:11]
	v_mov_b32_e32 v83, v240
	v_mov_b32_e32 v78, v236
	v_pk_mul_f32 v[78:79], v[82:83], v[78:79]
	v_mov_b32_e32 v94, v71
	v_add_f32_e32 v74, v78, v79
	v_mov_b32_e32 v78, v71
	v_mov_b32_e32 v79, v71
	s_nop 1
	v_permlane16_swap_b32_e32 v78, v79
	v_cndmask_b32_e64 v78, v78, v79, s[6:7]
	v_cndmask_b32_e64 v79, v78, -v78, s[10:11]
	v_mov_b32_e32 v78, v237
	v_mov_b32_e32 v95, v241
	v_pk_mul_f32 v[78:79], v[94:95], v[78:79]
	v_cndmask_b32_e64 v72, v68, v72, s[8:9]
	v_add_f32_e32 v75, v78, v79
	v_cndmask_b32_e64 v73, v69, v73, s[8:9]
	v_cndmask_b32_e64 v74, v70, v74, s[8:9]
	v_cndmask_b32_e64 v75, v71, v75, s[8:9]
	v_mov_b32_e32 v92, v72
	v_mov_b32_e32 v94, v73
	v_mov_b32_e32 v93, v74
	v_mov_b32_e32 v95, v75
	v_lshl_add_u64 v[72:73], s[82:83], 0, v[84:85]
	v_lshl_add_u64 v[72:73], s[0:1], 1, v[72:73]
	v_lshlrev_b32_e32 v96, 1, v142
	v_lshl_add_u64 v[72:73], v[72:73], 0, v[96:97]
	v_cvt_pk_bf16_f32 v74, v92, v94
	v_cvt_pk_bf16_f32 v75, v93, v95
	global_store_dwordx2 v[72:73], v[74:75], off offset:-768
	v_lshlrev_b32_e32 v72, 2, v103
	v_mov_b32_e32 v78, v64
	v_mov_b32_e32 v79, v64
	s_nop 1
	v_permlane16_swap_b32_e32 v78, v79
	v_cndmask_b32_e64 v78, v78, v79, s[6:7]
	v_cndmask_b32_e64 v79, v78, -v78, s[10:11]
; __device__ __forceinline__ float shx16(float v, int odd  ) { const unsigned x = __builtin_bit_cast(unsigned, v); auto r = __builtin_amdgcn_permlane16_swap(x, x, false, false); return __builtin_bit_cast(float, odd ? r[0] : r[1]); }
; __device__ __forceinline__ void st_bf4(bf16_t* p, const f32x4 v) { u32x2 w; w.x = cvt_pk_bf16(v[0], v[1]); w.y = cvt_pk_bf16(v[2], v[3]); *(u32x2*)p = w; }
;     __device__ __forceinline__ void operator()(const f32x4 (&acc)[2][2][4][2], const Unit& u, int wr, int wc, int fr, int fq) const {
;     ...
;                                 const int tix = row < cfg::MP ? (row & 2047) : 2048 + (row & 3);
;                                 const f32x4 cs = *(const f32x4*)(ropec + tix * 8 + 4 * n), sn = *(const f32x4*)(ropes + tix * 8 + 4 * n);
; #pragma unroll
;                                 for (int i = 0; i < 4; ++i) { const float p = shx16(v[i], fq & 1); const float rv = v[i] * cs[i] + (fq == 0 ? -p : p) * sn[i]; v[i] = fq < 2 ? rv : v[i]; }
;                             }
;                             if (pn < 4) st_bf4(Q + (size_t)row * 512 + (pn - 2) * 256 + tc, v);
	v_mov_b32_e32 v82, v64
	v_mov_b32_e32 v78, v242
	v_mov_b32_e32 v83, v246
	v_pk_mul_f32 v[78:79], v[82:83], v[78:79]
	v_mov_b32_e32 v72, v65
	v_add_f32_e32 v68, v78, v79
	v_mov_b32_e32 v78, v65
	s_nop 1
	v_permlane16_swap_b32_e32 v72, v78
	v_cndmask_b32_e64 v72, v72, v78, s[6:7]
	v_cndmask_b32_e64 v79, v72, -v72, s[10:11]
	v_mov_b32_e32 v72, v65
	v_mov_b32_e32 v78, v243
	v_mov_b32_e32 v73, v247
	v_pk_mul_f32 v[72:73], v[72:73], v[78:79]
	v_mov_b32_e32 v78, v66
	v_add_f32_e32 v69, v72, v73
	v_mov_b32_e32 v72, v66
	v_mov_b32_e32 v73, v66
	s_nop 1
	v_permlane16_swap_b32_e32 v72, v73
	v_cndmask_b32_e64 v72, v72, v73, s[6:7]
	v_cndmask_b32_e64 v73, v72, -v72, s[10:11]
	v_mov_b32_e32 v79, v248
	v_mov_b32_e32 v72, v244
	v_pk_mul_f32 v[72:73], v[78:79], v[72:73]
	v_mov_b32_e32 v74, v67
	v_add_f32_e32 v70, v72, v73
	v_mov_b32_e32 v72, v67
	v_mov_b32_e32 v73, v67
	s_nop 1
	v_permlane16_swap_b32_e32 v72, v73
	v_cndmask_b32_e64 v72, v72, v73, s[6:7]
	v_cndmask_b32_e64 v73, v72, -v72, s[10:11]
	v_mov_b32_e32 v72, v245
	v_mov_b32_e32 v75, v249
	v_pk_mul_f32 v[72:73], v[74:75], v[72:73]
	v_cndmask_b32_e64 v68, v64, v68, s[8:9]
	v_add_f32_e32 v71, v72, v73
	v_cndmask_b32_e64 v69, v65, v69, s[8:9]
	v_cndmask_b32_e64 v70, v66, v70, s[8:9]
	v_cndmask_b32_e64 v71, v67, v71, s[8:9]
	v_mov_b32_e32 v78, v68
	v_mov_b32_e32 v82, v69
	v_mov_b32_e32 v79, v70
	v_mov_b32_e32 v83, v71
	s_mov_b64 s[70:71], -1
	s_andn2_b64 vcc, exec, s[70:71]
	v_lshl_add_u64 v[68:69], s[82:83], 0, v[84:85]
	v_lshl_add_u64 v[68:69], s[0:1], 1, v[68:69]
	v_lshlrev_b32_e32 v96, 1, v142
	v_lshl_add_u64 v[68:69], v[68:69], 0, v[96:97]
	v_cvt_pk_bf16_f32 v70, v78, v82
	v_cvt_pk_bf16_f32 v71, v79, v83
	global_store_dwordx2 v[68:69], v[70:71], off offset:-760
	s_add_i32 s46, s53, 0x80
	v_or_b32_e32 v68, s46, v143
	v_mad_i64_i32 v[76:77], s[18:19], v68, s61, 0
	v_mov_b32_e32 v64, 0x7cf
	s_movk_i32 s18, 0x4000
	v_bitop3_b32 v64, s46, v64, v143 bitop3:0xc8
	v_cmp_gt_i32_e32 vcc, s18, v68
	v_ashrrev_i32_e32 v69, 31, v68
	s_nop 0
	v_cndmask_b32_e32 v65, v151, v64, vcc
	v_lshlrev_b32_e32 v87, 3, v65
	v_add_u32_e32 v65, 0xffffc000, v68
	v_lshrrev_b32_e32 v86, 2, v65
	v_lshlrev_b64 v[70:71], 10, v[68:69]
	s_mov_b32 s75, 0x400000
	v_lshlrev_b32_e32 v69, 2, v87
	global_load_dwordx4 v[234:237], v229, s[44:45]
	global_load_dwordx4 v[238:241], v229, s[4:5]
	global_load_dwordx4 v[242:245], v229, s[44:45] offset:16
	global_load_dwordx4 v[246:249], v229, s[4:5] offset:16
	v_mov_b32_e32 v69, v60
	v_mov_b32_e32 v88, v60
	s_nop 1
	v_permlane16_swap_b32_e32 v69, v88
	v_cndmask_b32_e64 v69, v69, v88, s[6:7]
	v_cndmask_b32_e64 v89, v69, -v69, s[10:11]
	v_mov_b32_e32 v69, v61
	v_mov_b32_e32 v90, v60
	s_waitcnt vmcnt(8)
	v_mov_b32_e32 v88, v208
	v_mov_b32_e32 v91, v212
	v_mov_b32_e32 v82, v61
	s_nop 1
	v_permlane16_swap_b32_e32 v69, v82
	v_pk_mul_f32 v[88:89], v[90:91], v[88:89]
	v_cndmask_b32_e64 v69, v69, v82, s[6:7]
	v_add_f32_e32 v64, v88, v89
	v_cndmask_b32_e64 v89, v69, -v69, s[10:11]
	v_mov_b32_e32 v82, v61
	v_mov_b32_e32 v88, v209
	v_mov_b32_e32 v83, v213
	v_pk_mul_f32 v[82:83], v[82:83], v[88:89]
	v_mov_b32_e32 v69, v62
	v_add_f32_e32 v65, v82, v83
	v_mov_b32_e32 v82, v62
	s_nop 1
	v_permlane16_swap_b32_e32 v69, v82
	v_cndmask_b32_e64 v69, v69, v82, s[6:7]
	v_cndmask_b32_e64 v83, v69, -v69, s[10:11]
	v_mov_b32_e32 v88, v62
	v_mov_b32_e32 v89, v214
	v_mov_b32_e32 v82, v210
	v_pk_mul_f32 v[82:83], v[88:89], v[82:83]
	v_mov_b32_e32 v69, v63
	v_add_f32_e32 v66, v82, v83
	v_mov_b32_e32 v82, v63
	s_nop 1
	v_permlane16_swap_b32_e32 v69, v82
	v_cndmask_b32_e64 v69, v69, v82, s[6:7]
	v_cndmask_b32_e64 v83, v69, -v69, s[10:11]
	v_mov_b32_e32 v84, v63
	v_mov_b32_e32 v82, v211
	v_mov_b32_e32 v85, v215
	v_pk_mul_f32 v[82:83], v[84:85], v[82:83]
	v_cndmask_b32_e64 v64, v60, v64, s[8:9]
	v_add_f32_e32 v67, v82, v83
	v_cndmask_b32_e64 v65, v61, v65, s[8:9]
	v_cndmask_b32_e64 v66, v62, v66, s[8:9]
	v_cndmask_b32_e64 v67, v63, v67, s[8:9]
	v_mov_b32_e32 v69, v64
	v_mov_b32_e32 v89, v65
	v_mov_b32_e32 v88, v66
	v_mov_b32_e32 v90, v67
	v_lshl_add_u64 v[64:65], s[82:83], 0, v[70:71]
	v_lshl_add_u64 v[64:65], s[0:1], 1, v[64:65]
	v_lshlrev_b32_e32 v96, 1, v142
	v_lshl_add_u64 v[64:65], v[64:65], 0, v[96:97]
	v_cvt_pk_bf16_f32 v66, v69, v89
	v_cvt_pk_bf16_f32 v67, v88, v90
	global_store_dwordx2 v[64:65], v[66:67], off offset:-1024
	v_lshlrev_b32_e32 v66, 2, v87
	v_mov_b32_e32 v66, v56
	v_mov_b32_e32 v67, v56
	s_nop 1
	v_permlane16_swap_b32_e32 v66, v67
	v_cndmask_b32_e64 v66, v66, v67, s[6:7]
	v_cndmask_b32_e64 v67, v66, -v66, s[10:11]
	v_mov_b32_e32 v88, v56
	v_mov_b32_e32 v66, v216
	v_mov_b32_e32 v89, v220
	v_pk_mul_f32 v[66:67], v[88:89], v[66:67]
	v_mov_b32_e32 v82, v57
	v_add_f32_e32 v60, v66, v67
	v_mov_b32_e32 v66, v57
	v_mov_b32_e32 v67, v57
	s_nop 1
	v_permlane16_swap_b32_e32 v66, v67
	v_cndmask_b32_e64 v66, v66, v67, s[6:7]
	v_cndmask_b32_e64 v67, v66, -v66, s[10:11]
	v_mov_b32_e32 v66, v217
	v_mov_b32_e32 v83, v221
	v_pk_mul_f32 v[66:67], v[82:83], v[66:67]
	v_mov_b32_e32 v82, v58
	v_add_f32_e32 v61, v66, v67
	v_mov_b32_e32 v66, v58
	v_mov_b32_e32 v67, v58
	s_nop 1
	v_permlane16_swap_b32_e32 v66, v67
	v_cndmask_b32_e64 v66, v66, v67, s[6:7]
	v_cndmask_b32_e64 v67, v66, -v66, s[10:11]
	v_mov_b32_e32 v83, v222
	v_mov_b32_e32 v66, v218
	v_pk_mul_f32 v[66:67], v[82:83], v[66:67]
	v_mov_b32_e32 v84, v59
	v_add_f32_e32 v62, v66, v67
	v_mov_b32_e32 v66, v59
	v_mov_b32_e32 v67, v59
	s_nop 1
	v_permlane16_swap_b32_e32 v66, v67
	v_cndmask_b32_e64 v66, v66, v67, s[6:7]
	v_cndmask_b32_e64 v67, v66, -v66, s[10:11]
	v_mov_b32_e32 v66, v219
	v_mov_b32_e32 v85, v223
	v_pk_mul_f32 v[66:67], v[84:85], v[66:67]
	v_cndmask_b32_e64 v60, v56, v60, s[8:9]
; __device__ __forceinline__ float shx16(float v, int odd  ) { const unsigned x = __builtin_bit_cast(unsigned, v); auto r = __builtin_amdgcn_permlane16_swap(x, x, false, false); return __builtin_bit_cast(float, odd ? r[0] : r[1]); }
; __device__ __forceinline__ void st_bf4(bf16_t* p, const f32x4 v) { u32x2 w; w.x = cvt_pk_bf16(v[0], v[1]); w.y = cvt_pk_bf16(v[2], v[3]); *(u32x2*)p = w; }
;     __device__ __forceinline__ void operator()(const f32x4 (&acc)[2][2][4][2], const Unit& u, int wr, int wc, int fr, int fq) const {
;     ...
;                                 const int tix = row < cfg::MP ? (row & 2047) : 2048 + (row & 3);
;                                 const f32x4 cs = *(const f32x4*)(ropec + tix * 8 + 4 * n), sn = *(const f32x4*)(ropes + tix * 8 + 4 * n);
; #pragma unroll
;                                 for (int i = 0; i < 4; ++i) { const float p = shx16(v[i], fq & 1); const float rv = v[i] * cs[i] + (fq == 0 ? -p : p) * sn[i]; v[i] = fq < 2 ? rv : v[i]; }
;                             }
;                             if (pn < 4) st_bf4(Q + (size_t)row * 512 + (pn - 2) * 256 + tc, v);
	v_add_f32_e32 v63, v66, v67
	v_cndmask_b32_e64 v61, v57, v61, s[8:9]
	v_cndmask_b32_e64 v62, v58, v62, s[8:9]
	v_cndmask_b32_e64 v63, v59, v63, s[8:9]
	v_mov_b32_e32 v69, v60
	v_mov_b32_e32 v85, v61
	v_mov_b32_e32 v84, v62
	v_mov_b32_e32 v88, v63
	v_lshl_add_u64 v[60:61], s[82:83], 0, v[70:71]
	v_lshl_add_u64 v[60:61], s[0:1], 1, v[60:61]
	v_lshlrev_b32_e32 v96, 1, v142
	v_lshl_add_u64 v[60:61], v[60:61], 0, v[96:97]
	v_cvt_pk_bf16_f32 v62, v69, v85
	v_cvt_pk_bf16_f32 v63, v84, v88
	global_store_dwordx2 v[60:61], v[62:63], off offset:-1016
	v_lshlrev_b32_e32 v62, 2, v87
	v_mov_b32_e32 v62, v52
	v_mov_b32_e32 v63, v52
	s_nop 1
	v_permlane16_swap_b32_e32 v62, v63
	v_cndmask_b32_e64 v62, v62, v63, s[6:7]
	v_cndmask_b32_e64 v63, v62, -v62, s[10:11]
	v_mov_b32_e32 v66, v52
	v_mov_b32_e32 v62, v208
	v_mov_b32_e32 v67, v212
	v_pk_mul_f32 v[62:63], v[66:67], v[62:63]
	v_mov_b32_e32 v78, v53
	v_add_f32_e32 v56, v62, v63
	v_mov_b32_e32 v62, v53
	v_mov_b32_e32 v63, v53
	s_nop 1
	v_permlane16_swap_b32_e32 v62, v63
	v_cndmask_b32_e64 v62, v62, v63, s[6:7]
	v_cndmask_b32_e64 v63, v62, -v62, s[10:11]
	v_mov_b32_e32 v62, v209
	v_mov_b32_e32 v79, v213
	v_pk_mul_f32 v[62:63], v[78:79], v[62:63]
	v_mov_b32_e32 v66, v54
	v_add_f32_e32 v57, v62, v63
	v_mov_b32_e32 v62, v54
	v_mov_b32_e32 v63, v54
	s_nop 1
	v_permlane16_swap_b32_e32 v62, v63
	v_cndmask_b32_e64 v62, v62, v63, s[6:7]
	v_cndmask_b32_e64 v63, v62, -v62, s[10:11]
	v_mov_b32_e32 v67, v214
	v_mov_b32_e32 v62, v210
	v_pk_mul_f32 v[62:63], v[66:67], v[62:63]
	v_mov_b32_e32 v80, v55
	v_add_f32_e32 v58, v62, v63
	v_mov_b32_e32 v62, v55
	v_mov_b32_e32 v63, v55
	s_nop 1
	v_permlane16_swap_b32_e32 v62, v63
	v_cndmask_b32_e64 v62, v62, v63, s[6:7]
	v_cndmask_b32_e64 v63, v62, -v62, s[10:11]
	v_mov_b32_e32 v62, v211
	v_mov_b32_e32 v81, v215
	v_pk_mul_f32 v[62:63], v[80:81], v[62:63]
	v_cndmask_b32_e64 v56, v52, v56, s[8:9]
	v_add_f32_e32 v59, v62, v63
	v_cndmask_b32_e64 v57, v53, v57, s[8:9]
	v_cndmask_b32_e64 v58, v54, v58, s[8:9]
	v_cndmask_b32_e64 v59, v55, v59, s[8:9]
	v_mov_b32_e32 v69, v56
	v_mov_b32_e32 v79, v57
	v_mov_b32_e32 v78, v58
	v_mov_b32_e32 v80, v59
	v_lshl_add_u64 v[56:57], s[82:83], 0, v[70:71]
	v_lshl_add_u64 v[56:57], s[0:1], 1, v[56:57]
	v_lshlrev_b32_e32 v96, 1, v142
	v_lshl_add_u64 v[56:57], v[56:57], 0, v[96:97]
	v_cvt_pk_bf16_f32 v58, v69, v79
	v_cvt_pk_bf16_f32 v59, v78, v80
	global_store_dwordx2 v[56:57], v[58:59], off offset:-768
	v_lshlrev_b32_e32 v56, 2, v87
	v_mov_b32_e32 v62, v48
	v_mov_b32_e32 v63, v48
	s_nop 1
	v_permlane16_swap_b32_e32 v62, v63
	v_cndmask_b32_e64 v62, v62, v63, s[6:7]
	v_cndmask_b32_e64 v63, v62, -v62, s[10:11]
	v_mov_b32_e32 v66, v48
	v_mov_b32_e32 v62, v216
	v_mov_b32_e32 v67, v220
	v_pk_mul_f32 v[62:63], v[66:67], v[62:63]
	v_mov_b32_e32 v56, v49
	v_add_f32_e32 v52, v62, v63
	v_mov_b32_e32 v62, v49
	s_nop 1
	v_permlane16_swap_b32_e32 v56, v62
	v_cndmask_b32_e64 v56, v56, v62, s[6:7]
	v_cndmask_b32_e64 v63, v56, -v56, s[10:11]
	v_mov_b32_e32 v56, v49
	v_mov_b32_e32 v62, v217
	v_mov_b32_e32 v57, v221
	v_pk_mul_f32 v[56:57], v[56:57], v[62:63]
	v_mov_b32_e32 v62, v50
	v_add_f32_e32 v53, v56, v57
	v_mov_b32_e32 v56, v50
	v_mov_b32_e32 v57, v50
	s_nop 1
	v_permlane16_swap_b32_e32 v56, v57
	v_cndmask_b32_e64 v56, v56, v57, s[6:7]
	v_cndmask_b32_e64 v57, v56, -v56, s[10:11]
	v_mov_b32_e32 v63, v222
	v_mov_b32_e32 v56, v218
	v_pk_mul_f32 v[56:57], v[62:63], v[56:57]
	v_mov_b32_e32 v58, v51
	v_add_f32_e32 v54, v56, v57
	v_mov_b32_e32 v56, v51
	v_mov_b32_e32 v57, v51
	s_nop 1
	v_permlane16_swap_b32_e32 v56, v57
	v_cndmask_b32_e64 v56, v56, v57, s[6:7]
	v_cndmask_b32_e64 v57, v56, -v56, s[10:11]
	v_mov_b32_e32 v56, v219
	v_mov_b32_e32 v59, v223
	v_pk_mul_f32 v[56:57], v[58:59], v[56:57]
	v_cndmask_b32_e64 v52, v48, v52, s[8:9]
	v_add_f32_e32 v55, v56, v57
	v_cndmask_b32_e64 v53, v49, v53, s[8:9]
	v_cndmask_b32_e64 v54, v50, v54, s[8:9]
	v_cndmask_b32_e64 v55, v51, v55, s[8:9]
	v_mov_b32_e32 v62, v52
	v_mov_b32_e32 v66, v53
	v_mov_b32_e32 v63, v54
	v_mov_b32_e32 v67, v55
	s_mov_b64 s[70:71], -1
	s_andn2_b64 vcc, exec, s[70:71]
	v_lshl_add_u64 v[52:53], s[82:83], 0, v[70:71]
	v_lshl_add_u64 v[52:53], s[0:1], 1, v[52:53]
	v_lshlrev_b32_e32 v96, 1, v142
	v_lshl_add_u64 v[52:53], v[52:53], 0, v[96:97]
	v_cvt_pk_bf16_f32 v54, v62, v66
	v_cvt_pk_bf16_f32 v55, v63, v67
	global_store_dwordx2 v[52:53], v[54:55], off offset:-760
	v_or_b32_e32 v48, 16, v68
	v_mad_i64_i32 v[58:59], s[18:19], v48, s61, 0
	s_movk_i32 s18, 0x7df
	s_nop 0
	v_bitop3_b32 v50, v68, s18, 16 bitop3:0xc8
	s_movk_i32 s18, 0x4000
	v_cmp_gt_i32_e32 vcc, s18, v48
	v_ashrrev_i32_e32 v49, 31, v48
	s_nop 0
	v_cndmask_b32_e32 v51, v151, v50, vcc
	v_lshlrev_b32_e32 v70, 3, v51
	v_add_u32_e32 v51, 0xffffc010, v68
	v_lshrrev_b32_e32 v69, 2, v51
	v_lshlrev_b64 v[52:53], 10, v[48:49]
	v_lshlrev_b32_e32 v64, 2, v70
	global_load_dwordx4 v[208:211], v230, s[44:45]
	global_load_dwordx4 v[212:215], v230, s[4:5]
	global_load_dwordx4 v[216:219], v230, s[44:45] offset:16
	global_load_dwordx4 v[220:223], v230, s[4:5] offset:16
	v_mov_b32_e32 v71, v44
	v_mov_b32_e32 v72, v44
	s_nop 1
	v_permlane16_swap_b32_e32 v71, v72
	v_cndmask_b32_e64 v71, v71, v72, s[6:7]
	v_cndmask_b32_e64 v73, v71, -v71, s[10:11]
	v_mov_b32_e32 v71, v45
	v_mov_b32_e32 v74, v44
	s_waitcnt vmcnt(8)
; __device__ __forceinline__ float shx16(float v, int odd  ) { const unsigned x = __builtin_bit_cast(unsigned, v); auto r = __builtin_amdgcn_permlane16_swap(x, x, false, false); return __builtin_bit_cast(float, odd ? r[0] : r[1]); }
; __device__ __forceinline__ void st_bf4(bf16_t* p, const f32x4 v) { u32x2 w; w.x = cvt_pk_bf16(v[0], v[1]); w.y = cvt_pk_bf16(v[2], v[3]); *(u32x2*)p = w; }
;     __device__ __forceinline__ void operator()(const f32x4 (&acc)[2][2][4][2], const Unit& u, int wr, int wc, int fr, int fq) const {
;     ...
;                                 const int tix = row < cfg::MP ? (row & 2047) : 2048 + (row & 3);
;                                 const f32x4 cs = *(const f32x4*)(ropec + tix * 8 + 4 * n), sn = *(const f32x4*)(ropes + tix * 8 + 4 * n);
; #pragma unroll
;                                 for (int i = 0; i < 4; ++i) { const float p = shx16(v[i], fq & 1); const float rv = v[i] * cs[i] + (fq == 0 ? -p : p) * sn[i]; v[i] = fq < 2 ? rv : v[i]; }
;                             }
;                             if (pn < 4) st_bf4(Q + (size_t)row * 512 + (pn - 2) * 256 + tc, v);
	v_mov_b32_e32 v72, v234
	v_mov_b32_e32 v75, v238
	v_mov_b32_e32 v64, v45
	s_nop 1
	v_permlane16_swap_b32_e32 v64, v71
	v_pk_mul_f32 v[72:73], v[74:75], v[72:73]
	v_cndmask_b32_e64 v64, v64, v71, s[6:7]
	v_add_f32_e32 v48, v72, v73
	v_cndmask_b32_e64 v73, v64, -v64, s[10:11]
	v_mov_b32_e32 v64, v45
	v_mov_b32_e32 v72, v235
	v_mov_b32_e32 v65, v239
	v_pk_mul_f32 v[64:65], v[64:65], v[72:73]
	v_mov_b32_e32 v72, v46
	v_add_f32_e32 v49, v64, v65
	v_mov_b32_e32 v64, v46
	v_mov_b32_e32 v65, v46
	s_nop 1
	v_permlane16_swap_b32_e32 v64, v65
	v_cndmask_b32_e64 v64, v64, v65, s[6:7]
	v_cndmask_b32_e64 v65, v64, -v64, s[10:11]
	v_mov_b32_e32 v73, v240
	v_mov_b32_e32 v64, v236
	v_pk_mul_f32 v[64:65], v[72:73], v[64:65]
	v_mov_b32_e32 v66, v47
	v_add_f32_e32 v50, v64, v65
	v_mov_b32_e32 v64, v47
	v_mov_b32_e32 v65, v47
	s_nop 1
	v_permlane16_swap_b32_e32 v64, v65
	v_cndmask_b32_e64 v64, v64, v65, s[6:7]
	v_cndmask_b32_e64 v65, v64, -v64, s[10:11]
	v_mov_b32_e32 v64, v237
	v_mov_b32_e32 v67, v241
	v_pk_mul_f32 v[64:65], v[66:67], v[64:65]
	v_cndmask_b32_e64 v48, v44, v48, s[8:9]
	v_add_f32_e32 v51, v64, v65
	v_cndmask_b32_e64 v49, v45, v49, s[8:9]
	v_cndmask_b32_e64 v50, v46, v50, s[8:9]
	v_cndmask_b32_e64 v51, v47, v51, s[8:9]
	v_mov_b32_e32 v71, v48
	v_mov_b32_e32 v73, v49
	v_mov_b32_e32 v72, v50
	v_mov_b32_e32 v74, v51
	v_lshl_add_u64 v[48:49], s[82:83], 0, v[52:53]
	v_lshl_add_u64 v[48:49], s[0:1], 1, v[48:49]
	v_lshlrev_b32_e32 v96, 1, v142
	v_lshl_add_u64 v[48:49], v[48:49], 0, v[96:97]
	v_cvt_pk_bf16_f32 v50, v71, v73
	v_cvt_pk_bf16_f32 v51, v72, v74
	global_store_dwordx2 v[48:49], v[50:51], off offset:-1024
	v_lshlrev_b32_e32 v50, 2, v70
	v_mov_b32_e32 v50, v40
	v_mov_b32_e32 v51, v40
	s_nop 1
	v_permlane16_swap_b32_e32 v50, v51
	v_cndmask_b32_e64 v50, v50, v51, s[6:7]
	v_cndmask_b32_e64 v51, v50, -v50, s[10:11]
	v_mov_b32_e32 v72, v40
	v_mov_b32_e32 v50, v242
	v_mov_b32_e32 v73, v246
	v_pk_mul_f32 v[50:51], v[72:73], v[50:51]
	v_mov_b32_e32 v64, v41
	v_add_f32_e32 v44, v50, v51
	v_mov_b32_e32 v50, v41
	v_mov_b32_e32 v51, v41
	s_nop 1
	v_permlane16_swap_b32_e32 v50, v51
	v_cndmask_b32_e64 v50, v50, v51, s[6:7]
	v_cndmask_b32_e64 v51, v50, -v50, s[10:11]
	v_mov_b32_e32 v50, v243
	v_mov_b32_e32 v65, v247
	v_pk_mul_f32 v[50:51], v[64:65], v[50:51]
	v_mov_b32_e32 v64, v42
	v_add_f32_e32 v45, v50, v51
	v_mov_b32_e32 v50, v42
	v_mov_b32_e32 v51, v42
	s_nop 1
	v_permlane16_swap_b32_e32 v50, v51
	v_cndmask_b32_e64 v50, v50, v51, s[6:7]
	v_cndmask_b32_e64 v51, v50, -v50, s[10:11]
	v_mov_b32_e32 v65, v248
	v_mov_b32_e32 v50, v244
	v_pk_mul_f32 v[50:51], v[64:65], v[50:51]
	v_mov_b32_e32 v66, v43
	v_add_f32_e32 v46, v50, v51
	v_mov_b32_e32 v50, v43
	v_mov_b32_e32 v51, v43
	s_nop 1
	v_permlane16_swap_b32_e32 v50, v51
	v_cndmask_b32_e64 v50, v50, v51, s[6:7]
	v_cndmask_b32_e64 v51, v50, -v50, s[10:11]
	v_mov_b32_e32 v50, v245
	v_mov_b32_e32 v67, v249
	v_pk_mul_f32 v[50:51], v[66:67], v[50:51]
	v_cndmask_b32_e64 v44, v40, v44, s[8:9]
	v_add_f32_e32 v47, v50, v51
	v_cndmask_b32_e64 v45, v41, v45, s[8:9]
	v_cndmask_b32_e64 v46, v42, v46, s[8:9]
	v_cndmask_b32_e64 v47, v43, v47, s[8:9]
	v_mov_b32_e32 v66, v44
	v_mov_b32_e32 v71, v45
	v_mov_b32_e32 v67, v46
	v_mov_b32_e32 v72, v47
	v_lshl_add_u64 v[44:45], s[82:83], 0, v[52:53]
	v_lshl_add_u64 v[44:45], s[0:1], 1, v[44:45]
	v_lshlrev_b32_e32 v96, 1, v142
	v_lshl_add_u64 v[44:45], v[44:45], 0, v[96:97]
	v_cvt_pk_bf16_f32 v46, v66, v71
	v_cvt_pk_bf16_f32 v47, v67, v72
	global_store_dwordx2 v[44:45], v[46:47], off offset:-1016
	v_lshlrev_b32_e32 v46, 2, v70
	v_mov_b32_e32 v46, v36
	v_mov_b32_e32 v47, v36
	s_nop 1
	v_permlane16_swap_b32_e32 v46, v47
	v_cndmask_b32_e64 v46, v46, v47, s[6:7]
	v_cndmask_b32_e64 v47, v46, -v46, s[10:11]
	v_mov_b32_e32 v50, v36
	v_mov_b32_e32 v46, v234
	v_mov_b32_e32 v51, v238
	v_pk_mul_f32 v[46:47], v[50:51], v[46:47]
	v_mov_b32_e32 v60, v37
	v_add_f32_e32 v40, v46, v47
	v_mov_b32_e32 v46, v37
	v_mov_b32_e32 v47, v37
	s_nop 1
	v_permlane16_swap_b32_e32 v46, v47
	v_cndmask_b32_e64 v46, v46, v47, s[6:7]
	v_cndmask_b32_e64 v47, v46, -v46, s[10:11]
	v_mov_b32_e32 v46, v235
	v_mov_b32_e32 v61, v239
	v_pk_mul_f32 v[46:47], v[60:61], v[46:47]
	v_mov_b32_e32 v50, v38
	v_add_f32_e32 v41, v46, v47
	v_mov_b32_e32 v46, v38
	v_mov_b32_e32 v47, v38
	s_nop 1
	v_permlane16_swap_b32_e32 v46, v47
	v_cndmask_b32_e64 v46, v46, v47, s[6:7]
	v_cndmask_b32_e64 v47, v46, -v46, s[10:11]
	v_mov_b32_e32 v51, v240
	v_mov_b32_e32 v46, v236
	v_pk_mul_f32 v[46:47], v[50:51], v[46:47]
	v_mov_b32_e32 v62, v39
	v_add_f32_e32 v42, v46, v47
	v_mov_b32_e32 v46, v39
	v_mov_b32_e32 v47, v39
	s_nop 1
	v_permlane16_swap_b32_e32 v46, v47
	v_cndmask_b32_e64 v46, v46, v47, s[6:7]
	v_cndmask_b32_e64 v47, v46, -v46, s[10:11]
	v_mov_b32_e32 v46, v237
	v_mov_b32_e32 v63, v241
	v_pk_mul_f32 v[46:47], v[62:63], v[46:47]
	v_cndmask_b32_e64 v40, v36, v40, s[8:9]
	v_add_f32_e32 v43, v46, v47
	v_cndmask_b32_e64 v41, v37, v41, s[8:9]
	v_cndmask_b32_e64 v42, v38, v42, s[8:9]
	v_cndmask_b32_e64 v43, v39, v43, s[8:9]
	v_mov_b32_e32 v60, v40
	v_mov_b32_e32 v62, v41
	v_mov_b32_e32 v61, v42
	v_mov_b32_e32 v63, v43
	v_lshl_add_u64 v[40:41], s[82:83], 0, v[52:53]
	v_lshl_add_u64 v[40:41], s[0:1], 1, v[40:41]
	v_lshlrev_b32_e32 v96, 1, v142
	v_lshl_add_u64 v[40:41], v[40:41], 0, v[96:97]
	v_cvt_pk_bf16_f32 v42, v60, v62
	v_cvt_pk_bf16_f32 v43, v61, v63
	global_store_dwordx2 v[40:41], v[42:43], off offset:-768
	v_lshlrev_b32_e32 v40, 2, v70
	v_mov_b32_e32 v46, v32
	v_mov_b32_e32 v47, v32
	s_nop 1
	v_permlane16_swap_b32_e32 v46, v47
	v_cndmask_b32_e64 v46, v46, v47, s[6:7]
	v_cndmask_b32_e64 v47, v46, -v46, s[10:11]
	v_mov_b32_e32 v50, v32
; __device__ __forceinline__ float shx16(float v, int odd  ) { const unsigned x = __builtin_bit_cast(unsigned, v); auto r = __builtin_amdgcn_permlane16_swap(x, x, false, false); return __builtin_bit_cast(float, odd ? r[0] : r[1]); }
; __device__ __forceinline__ void st_bf4(bf16_t* p, const f32x4 v) { u32x2 w; w.x = cvt_pk_bf16(v[0], v[1]); w.y = cvt_pk_bf16(v[2], v[3]); *(u32x2*)p = w; }
;     __device__ __forceinline__ void operator()(const f32x4 (&acc)[2][2][4][2], const Unit& u, int wr, int wc, int fr, int fq) const {
;     ...
;                                 const int tix = row < cfg::MP ? (row & 2047) : 2048 + (row & 3);
;                                 const f32x4 cs = *(const f32x4*)(ropec + tix * 8 + 4 * n), sn = *(const f32x4*)(ropes + tix * 8 + 4 * n);
; #pragma unroll
;                                 for (int i = 0; i < 4; ++i) { const float p = shx16(v[i], fq & 1); const float rv = v[i] * cs[i] + (fq == 0 ? -p : p) * sn[i]; v[i] = fq < 2 ? rv : v[i]; }
;                             }
;                             if (pn < 4) st_bf4(Q + (size_t)row * 512 + (pn - 2) * 256 + tc, v);
	v_mov_b32_e32 v46, v242
	v_mov_b32_e32 v51, v246
	v_pk_mul_f32 v[46:47], v[50:51], v[46:47]
	v_mov_b32_e32 v40, v33
	v_add_f32_e32 v36, v46, v47
	v_mov_b32_e32 v46, v33
	s_nop 1
	v_permlane16_swap_b32_e32 v40, v46
	v_cndmask_b32_e64 v40, v40, v46, s[6:7]
	v_cndmask_b32_e64 v47, v40, -v40, s[10:11]
	v_mov_b32_e32 v40, v33
	v_mov_b32_e32 v46, v243
	v_mov_b32_e32 v41, v247
	v_pk_mul_f32 v[40:41], v[40:41], v[46:47]
	v_mov_b32_e32 v46, v34
	v_add_f32_e32 v37, v40, v41
	v_mov_b32_e32 v40, v34
	v_mov_b32_e32 v41, v34
	s_nop 1
	v_permlane16_swap_b32_e32 v40, v41
	v_cndmask_b32_e64 v40, v40, v41, s[6:7]
	v_cndmask_b32_e64 v41, v40, -v40, s[10:11]
	v_mov_b32_e32 v47, v248
	v_mov_b32_e32 v40, v244
	v_pk_mul_f32 v[40:41], v[46:47], v[40:41]
	v_mov_b32_e32 v42, v35
	v_add_f32_e32 v38, v40, v41
	v_mov_b32_e32 v40, v35
	v_mov_b32_e32 v41, v35
	s_nop 1
	v_permlane16_swap_b32_e32 v40, v41
	v_cndmask_b32_e64 v40, v40, v41, s[6:7]
	v_cndmask_b32_e64 v41, v40, -v40, s[10:11]
	v_mov_b32_e32 v40, v245
	v_mov_b32_e32 v43, v249
	v_pk_mul_f32 v[40:41], v[42:43], v[40:41]
	v_cndmask_b32_e64 v36, v32, v36, s[8:9]
	v_add_f32_e32 v39, v40, v41
	v_cndmask_b32_e64 v37, v33, v37, s[8:9]
	v_cndmask_b32_e64 v38, v34, v38, s[8:9]
	v_cndmask_b32_e64 v39, v35, v39, s[8:9]
	v_mov_b32_e32 v46, v36
	v_mov_b32_e32 v50, v37
	v_mov_b32_e32 v47, v38
	v_mov_b32_e32 v51, v39
	s_mov_b64 s[70:71], -1
	s_andn2_b64 vcc, exec, s[70:71]
	v_lshl_add_u64 v[36:37], s[82:83], 0, v[52:53]
	v_lshl_add_u64 v[36:37], s[0:1], 1, v[36:37]
	v_lshlrev_b32_e32 v96, 1, v142
	v_lshl_add_u64 v[36:37], v[36:37], 0, v[96:97]
	v_cvt_pk_bf16_f32 v38, v46, v50
	v_cvt_pk_bf16_f32 v39, v47, v51
	global_store_dwordx2 v[36:37], v[38:39], off offset:-760
	v_or_b32_e32 v32, 32, v68
	v_mad_i64_i32 v[42:43], s[18:19], v32, s61, 0
	s_movk_i32 s18, 0x7ef
	s_nop 0
	v_bitop3_b32 v34, v68, s18, 32 bitop3:0xc8
	s_movk_i32 s18, 0x4000
	v_cmp_gt_i32_e32 vcc, s18, v32
	v_ashrrev_i32_e32 v33, 31, v32
	s_nop 0
	v_cndmask_b32_e32 v35, v151, v34, vcc
	v_lshlrev_b32_e32 v53, 3, v35
	v_add_u32_e32 v35, 0xffffc020, v68
	v_lshrrev_b32_e32 v52, 2, v35
	v_lshlrev_b64 v[36:37], 10, v[32:33]
	v_lshlrev_b32_e32 v48, 2, v53
	global_load_dwordx4 v[234:237], v231, s[44:45]
	global_load_dwordx4 v[238:241], v231, s[4:5]
	global_load_dwordx4 v[242:245], v231, s[44:45] offset:16
	global_load_dwordx4 v[246:249], v231, s[4:5] offset:16
	v_mov_b32_e32 v54, v28
	v_mov_b32_e32 v55, v28
	s_nop 1
	v_permlane16_swap_b32_e32 v54, v55
	v_cndmask_b32_e64 v54, v54, v55, s[6:7]
	v_cndmask_b32_e64 v55, v54, -v54, s[10:11]
	v_mov_b32_e32 v56, v28
	s_waitcnt vmcnt(8)
	v_mov_b32_e32 v54, v208
	v_mov_b32_e32 v57, v212
	v_pk_mul_f32 v[54:55], v[56:57], v[54:55]
	v_mov_b32_e32 v48, v29
	v_add_f32_e32 v32, v54, v55
	v_mov_b32_e32 v54, v29
	s_nop 1
	v_permlane16_swap_b32_e32 v48, v54
	v_cndmask_b32_e64 v48, v48, v54, s[6:7]
	v_cndmask_b32_e64 v55, v48, -v48, s[10:11]
	v_mov_b32_e32 v48, v29
	v_mov_b32_e32 v54, v209
	v_mov_b32_e32 v49, v213
	v_pk_mul_f32 v[48:49], v[48:49], v[54:55]
	v_mov_b32_e32 v54, v30
	v_add_f32_e32 v33, v48, v49
	v_mov_b32_e32 v48, v30
	v_mov_b32_e32 v49, v30
	s_nop 1
	v_permlane16_swap_b32_e32 v48, v49
	v_cndmask_b32_e64 v48, v48, v49, s[6:7]
	v_cndmask_b32_e64 v49, v48, -v48, s[10:11]
	v_mov_b32_e32 v55, v214
	v_mov_b32_e32 v48, v210
	v_pk_mul_f32 v[48:49], v[54:55], v[48:49]
	v_mov_b32_e32 v50, v31
	v_add_f32_e32 v34, v48, v49
	v_mov_b32_e32 v48, v31
	v_mov_b32_e32 v49, v31
	s_nop 1
	v_permlane16_swap_b32_e32 v48, v49
	v_cndmask_b32_e64 v48, v48, v49, s[6:7]
	v_cndmask_b32_e64 v49, v48, -v48, s[10:11]
	v_mov_b32_e32 v48, v211
	v_mov_b32_e32 v51, v215
	v_pk_mul_f32 v[48:49], v[50:51], v[48:49]
	v_cndmask_b32_e64 v32, v28, v32, s[8:9]
	v_add_f32_e32 v35, v48, v49
	v_cndmask_b32_e64 v33, v29, v33, s[8:9]
	v_cndmask_b32_e64 v34, v30, v34, s[8:9]
	v_cndmask_b32_e64 v35, v31, v35, s[8:9]
	v_mov_b32_e32 v54, v32
	v_mov_b32_e32 v56, v33
	v_mov_b32_e32 v55, v34
	v_mov_b32_e32 v57, v35
	v_lshl_add_u64 v[32:33], s[82:83], 0, v[36:37]
	v_lshl_add_u64 v[32:33], s[0:1], 1, v[32:33]
	v_lshlrev_b32_e32 v96, 1, v142
	v_lshl_add_u64 v[32:33], v[32:33], 0, v[96:97]
	v_cvt_pk_bf16_f32 v34, v54, v56
	v_cvt_pk_bf16_f32 v35, v55, v57
	global_store_dwordx2 v[32:33], v[34:35], off offset:-1024
	v_lshlrev_b32_e32 v34, 2, v53
	v_mov_b32_e32 v34, v24
	v_mov_b32_e32 v35, v24
	s_nop 1
	v_permlane16_swap_b32_e32 v34, v35
	v_cndmask_b32_e64 v34, v34, v35, s[6:7]
	v_cndmask_b32_e64 v35, v34, -v34, s[10:11]
	v_mov_b32_e32 v54, v24
	v_mov_b32_e32 v34, v216
	v_mov_b32_e32 v55, v220
	v_pk_mul_f32 v[34:35], v[54:55], v[34:35]
	v_mov_b32_e32 v48, v25
	v_add_f32_e32 v28, v34, v35
	v_mov_b32_e32 v34, v25
	v_mov_b32_e32 v35, v25
	s_nop 1
	v_permlane16_swap_b32_e32 v34, v35
	v_cndmask_b32_e64 v34, v34, v35, s[6:7]
	v_cndmask_b32_e64 v35, v34, -v34, s[10:11]
	v_mov_b32_e32 v34, v217
	v_mov_b32_e32 v49, v221
	v_pk_mul_f32 v[34:35], v[48:49], v[34:35]
	v_mov_b32_e32 v48, v26
	v_add_f32_e32 v29, v34, v35
	v_mov_b32_e32 v34, v26
	v_mov_b32_e32 v35, v26
	s_nop 1
	v_permlane16_swap_b32_e32 v34, v35
	v_cndmask_b32_e64 v34, v34, v35, s[6:7]
	v_cndmask_b32_e64 v35, v34, -v34, s[10:11]
	v_mov_b32_e32 v49, v222
	v_mov_b32_e32 v34, v218
	v_pk_mul_f32 v[34:35], v[48:49], v[34:35]
	v_mov_b32_e32 v50, v27
	v_add_f32_e32 v30, v34, v35
	v_mov_b32_e32 v34, v27
	v_mov_b32_e32 v35, v27
	s_nop 1
	v_permlane16_swap_b32_e32 v34, v35
	v_cndmask_b32_e64 v34, v34, v35, s[6:7]
	v_cndmask_b32_e64 v35, v34, -v34, s[10:11]
	v_mov_b32_e32 v34, v219
	v_mov_b32_e32 v51, v223
	v_pk_mul_f32 v[34:35], v[50:51], v[34:35]
	v_cndmask_b32_e64 v28, v24, v28, s[8:9]
	v_add_f32_e32 v31, v34, v35
	v_cndmask_b32_e64 v29, v25, v29, s[8:9]
; __device__ __forceinline__ float shx16(float v, int odd  ) { const unsigned x = __builtin_bit_cast(unsigned, v); auto r = __builtin_amdgcn_permlane16_swap(x, x, false, false); return __builtin_bit_cast(float, odd ? r[0] : r[1]); }
; __device__ __forceinline__ void st_bf4(bf16_t* p, const f32x4 v) { u32x2 w; w.x = cvt_pk_bf16(v[0], v[1]); w.y = cvt_pk_bf16(v[2], v[3]); *(u32x2*)p = w; }
;     __device__ __forceinline__ void operator()(const f32x4 (&acc)[2][2][4][2], const Unit& u, int wr, int wc, int fr, int fq) const {
;     ...
;                                 const int tix = row < cfg::MP ? (row & 2047) : 2048 + (row & 3);
;                                 const f32x4 cs = *(const f32x4*)(ropec + tix * 8 + 4 * n), sn = *(const f32x4*)(ropes + tix * 8 + 4 * n);
; #pragma unroll
;                                 for (int i = 0; i < 4; ++i) { const float p = shx16(v[i], fq & 1); const float rv = v[i] * cs[i] + (fq == 0 ? -p : p) * sn[i]; v[i] = fq < 2 ? rv : v[i]; }
;                             }
;                             if (pn < 4) st_bf4(Q + (size_t)row * 512 + (pn - 2) * 256 + tc, v);
	v_cndmask_b32_e64 v30, v26, v30, s[8:9]
	v_cndmask_b32_e64 v31, v27, v31, s[8:9]
	v_mov_b32_e32 v50, v28
	v_mov_b32_e32 v54, v29
	v_mov_b32_e32 v51, v30
	v_mov_b32_e32 v55, v31
	v_lshl_add_u64 v[28:29], s[82:83], 0, v[36:37]
	v_lshl_add_u64 v[28:29], s[0:1], 1, v[28:29]
	v_lshlrev_b32_e32 v96, 1, v142
	v_lshl_add_u64 v[28:29], v[28:29], 0, v[96:97]
	v_cvt_pk_bf16_f32 v30, v50, v54
	v_cvt_pk_bf16_f32 v31, v51, v55
	global_store_dwordx2 v[28:29], v[30:31], off offset:-1016
	v_lshlrev_b32_e32 v30, 2, v53
	v_mov_b32_e32 v30, v20
	v_mov_b32_e32 v31, v20
	s_nop 1
	v_permlane16_swap_b32_e32 v30, v31
	v_cndmask_b32_e64 v30, v30, v31, s[6:7]
	v_cndmask_b32_e64 v31, v30, -v30, s[10:11]
	v_mov_b32_e32 v34, v20
	v_mov_b32_e32 v30, v208
	v_mov_b32_e32 v35, v212
	v_pk_mul_f32 v[30:31], v[34:35], v[30:31]
	v_mov_b32_e32 v44, v21
	v_add_f32_e32 v24, v30, v31
	v_mov_b32_e32 v30, v21
	v_mov_b32_e32 v31, v21
	s_nop 1
	v_permlane16_swap_b32_e32 v30, v31
	v_cndmask_b32_e64 v30, v30, v31, s[6:7]
	v_cndmask_b32_e64 v31, v30, -v30, s[10:11]
	v_mov_b32_e32 v30, v209
	v_mov_b32_e32 v45, v213
	v_pk_mul_f32 v[30:31], v[44:45], v[30:31]
	v_mov_b32_e32 v34, v22
	v_add_f32_e32 v25, v30, v31
	v_mov_b32_e32 v30, v22
	v_mov_b32_e32 v31, v22
	s_nop 1
	v_permlane16_swap_b32_e32 v30, v31
	v_cndmask_b32_e64 v30, v30, v31, s[6:7]
	v_cndmask_b32_e64 v31, v30, -v30, s[10:11]
	v_mov_b32_e32 v35, v214
	v_mov_b32_e32 v30, v210
	v_pk_mul_f32 v[30:31], v[34:35], v[30:31]
	v_mov_b32_e32 v46, v23
	v_add_f32_e32 v26, v30, v31
	v_mov_b32_e32 v30, v23
	v_mov_b32_e32 v31, v23
	s_nop 1
	v_permlane16_swap_b32_e32 v30, v31
	v_cndmask_b32_e64 v30, v30, v31, s[6:7]
	v_cndmask_b32_e64 v31, v30, -v30, s[10:11]
	v_mov_b32_e32 v30, v211
	v_mov_b32_e32 v47, v215
	v_pk_mul_f32 v[30:31], v[46:47], v[30:31]
	v_cndmask_b32_e64 v24, v20, v24, s[8:9]
	v_add_f32_e32 v27, v30, v31
	v_cndmask_b32_e64 v25, v21, v25, s[8:9]
	v_cndmask_b32_e64 v26, v22, v26, s[8:9]
	v_cndmask_b32_e64 v27, v23, v27, s[8:9]
	v_mov_b32_e32 v44, v24
	v_mov_b32_e32 v46, v25
	v_mov_b32_e32 v45, v26
	v_mov_b32_e32 v47, v27
	v_lshl_add_u64 v[24:25], s[82:83], 0, v[36:37]
	v_lshl_add_u64 v[24:25], s[0:1], 1, v[24:25]
	v_lshlrev_b32_e32 v96, 1, v142
	v_lshl_add_u64 v[24:25], v[24:25], 0, v[96:97]
	v_cvt_pk_bf16_f32 v26, v44, v46
	v_cvt_pk_bf16_f32 v27, v45, v47
	global_store_dwordx2 v[24:25], v[26:27], off offset:-768
	v_lshlrev_b32_e32 v24, 2, v53
	v_mov_b32_e32 v30, v16
	v_mov_b32_e32 v31, v16
	s_nop 1
	v_permlane16_swap_b32_e32 v30, v31
	v_cndmask_b32_e64 v30, v30, v31, s[6:7]
	v_cndmask_b32_e64 v31, v30, -v30, s[10:11]
	v_mov_b32_e32 v34, v16
	v_mov_b32_e32 v30, v216
	v_mov_b32_e32 v35, v220
	v_pk_mul_f32 v[30:31], v[34:35], v[30:31]
	v_mov_b32_e32 v24, v17
	v_add_f32_e32 v20, v30, v31
	v_mov_b32_e32 v30, v17
	s_nop 1
	v_permlane16_swap_b32_e32 v24, v30
	v_cndmask_b32_e64 v24, v24, v30, s[6:7]
	v_cndmask_b32_e64 v31, v24, -v24, s[10:11]
	v_mov_b32_e32 v24, v17
	v_mov_b32_e32 v30, v217
	v_mov_b32_e32 v25, v221
	v_pk_mul_f32 v[24:25], v[24:25], v[30:31]
	v_mov_b32_e32 v30, v18
	v_add_f32_e32 v21, v24, v25
	v_mov_b32_e32 v24, v18
	v_mov_b32_e32 v25, v18
	s_nop 1
	v_permlane16_swap_b32_e32 v24, v25
	v_cndmask_b32_e64 v24, v24, v25, s[6:7]
	v_cndmask_b32_e64 v25, v24, -v24, s[10:11]
	v_mov_b32_e32 v31, v222
	v_mov_b32_e32 v24, v218
	v_pk_mul_f32 v[24:25], v[30:31], v[24:25]
	v_mov_b32_e32 v26, v19
	v_add_f32_e32 v22, v24, v25
	v_mov_b32_e32 v24, v19
	v_mov_b32_e32 v25, v19
	s_nop 1
	v_permlane16_swap_b32_e32 v24, v25
	v_cndmask_b32_e64 v24, v24, v25, s[6:7]
	v_cndmask_b32_e64 v25, v24, -v24, s[10:11]
	v_mov_b32_e32 v24, v219
	v_mov_b32_e32 v27, v223
	v_pk_mul_f32 v[24:25], v[26:27], v[24:25]
	v_cndmask_b32_e64 v20, v16, v20, s[8:9]
	v_add_f32_e32 v23, v24, v25
	v_cndmask_b32_e64 v21, v17, v21, s[8:9]
	v_cndmask_b32_e64 v22, v18, v22, s[8:9]
	v_cndmask_b32_e64 v23, v19, v23, s[8:9]
	v_mov_b32_e32 v30, v20
	v_mov_b32_e32 v34, v21
	v_mov_b32_e32 v31, v22
	v_mov_b32_e32 v35, v23
	s_mov_b64 s[70:71], -1
	s_andn2_b64 vcc, exec, s[70:71]
	v_lshl_add_u64 v[20:21], s[82:83], 0, v[36:37]
	v_lshl_add_u64 v[20:21], s[0:1], 1, v[20:21]
	v_lshlrev_b32_e32 v96, 1, v142
	v_lshl_add_u64 v[20:21], v[20:21], 0, v[96:97]
	v_cvt_pk_bf16_f32 v22, v30, v34
	v_cvt_pk_bf16_f32 v23, v31, v35
	global_store_dwordx2 v[20:21], v[22:23], off offset:-760
	v_or_b32_e32 v16, 48, v68
	v_mad_i64_i32 v[26:27], s[18:19], v16, s61, 0
	s_movk_i32 s18, 0x3fff
	s_nop 0
	v_cmp_lt_i32_e64 s[20:21], s18, v16
	s_movk_i32 s18, 0x7ff
	v_bitop3_b32 v18, v68, s18, 48 bitop3:0xc8
	s_movk_i32 s18, 0x4000
	v_cmp_gt_i32_e32 vcc, s18, v16
	v_add_u32_e32 v96, 0xfffff880, v18
	v_ashrrev_i32_e32 v17, 31, v16
	v_cndmask_b32_e32 v19, v151, v18, vcc
	v_lshlrev_b32_e32 v37, 3, v19
	v_add_u32_e32 v19, 0xffffc030, v68
	v_lshlrev_b64 v[28:29], 7, v[96:97]
	v_lshlrev_b64 v[24:25], 11, v[16:17]
	v_lshlrev_b64 v[22:23], 8, v[16:17]
	v_lshrrev_b32_e32 v36, 2, v19
	v_lshlrev_b64 v[20:21], 10, v[16:17]
	v_lshlrev_b32_e32 v32, 2, v37
	v_mov_b32_e32 v38, v12
	v_mov_b32_e32 v39, v12
	s_nop 1
	v_permlane16_swap_b32_e32 v38, v39
	v_cndmask_b32_e64 v38, v38, v39, s[6:7]
	v_cndmask_b32_e64 v39, v38, -v38, s[10:11]
	v_mov_b32_e32 v40, v12
	s_waitcnt vmcnt(4)
; __device__ __forceinline__ float shx16(float v, int odd  ) { const unsigned x = __builtin_bit_cast(unsigned, v); auto r = __builtin_amdgcn_permlane16_swap(x, x, false, false); return __builtin_bit_cast(float, odd ? r[0] : r[1]); }
; __device__ __forceinline__ void st_bf4(bf16_t* p, const f32x4 v) { u32x2 w; w.x = cvt_pk_bf16(v[0], v[1]); w.y = cvt_pk_bf16(v[2], v[3]); *(u32x2*)p = w; }
;     __device__ __forceinline__ void operator()(const f32x4 (&acc)[2][2][4][2], const Unit& u, int wr, int wc, int fr, int fq) const {
;     ...
;                                 const int tix = row < cfg::MP ? (row & 2047) : 2048 + (row & 3);
;                                 const f32x4 cs = *(const f32x4*)(ropec + tix * 8 + 4 * n), sn = *(const f32x4*)(ropes + tix * 8 + 4 * n);
; #pragma unroll
;                                 for (int i = 0; i < 4; ++i) { const float p = shx16(v[i], fq & 1); const float rv = v[i] * cs[i] + (fq == 0 ? -p : p) * sn[i]; v[i] = fq < 2 ? rv : v[i]; }
;                             }
;                             if (pn < 4) st_bf4(Q + (size_t)row * 512 + (pn - 2) * 256 + tc, v);
	v_mov_b32_e32 v38, v234
	v_mov_b32_e32 v41, v238
	v_pk_mul_f32 v[38:39], v[40:41], v[38:39]
	v_mov_b32_e32 v32, v13
	v_add_f32_e32 v16, v38, v39
	v_mov_b32_e32 v38, v13
	s_nop 1
	v_permlane16_swap_b32_e32 v32, v38
	v_cndmask_b32_e64 v32, v32, v38, s[6:7]
	v_cndmask_b32_e64 v39, v32, -v32, s[10:11]
	v_mov_b32_e32 v32, v13
	v_mov_b32_e32 v38, v235
	v_mov_b32_e32 v33, v239
	v_pk_mul_f32 v[32:33], v[32:33], v[38:39]
	v_mov_b32_e32 v38, v14
	v_add_f32_e32 v17, v32, v33
	v_mov_b32_e32 v32, v14
	v_mov_b32_e32 v33, v14
	s_nop 1
	v_permlane16_swap_b32_e32 v32, v33
	v_cndmask_b32_e64 v32, v32, v33, s[6:7]
	v_cndmask_b32_e64 v33, v32, -v32, s[10:11]
	v_mov_b32_e32 v39, v240
	v_mov_b32_e32 v32, v236
	v_pk_mul_f32 v[32:33], v[38:39], v[32:33]
	v_mov_b32_e32 v34, v15
	v_add_f32_e32 v18, v32, v33
	v_mov_b32_e32 v32, v15
	v_mov_b32_e32 v33, v15
	s_nop 1
	v_permlane16_swap_b32_e32 v32, v33
	v_cndmask_b32_e64 v32, v32, v33, s[6:7]
	v_cndmask_b32_e64 v33, v32, -v32, s[10:11]
	v_mov_b32_e32 v32, v237
	v_mov_b32_e32 v35, v241
	v_pk_mul_f32 v[32:33], v[34:35], v[32:33]
	v_cndmask_b32_e64 v16, v12, v16, s[8:9]
	v_add_f32_e32 v19, v32, v33
	v_cndmask_b32_e64 v17, v13, v17, s[8:9]
	v_cndmask_b32_e64 v18, v14, v18, s[8:9]
	v_cndmask_b32_e64 v19, v15, v19, s[8:9]
	v_mov_b32_e32 v38, v16
	v_mov_b32_e32 v40, v17
	v_mov_b32_e32 v39, v18
	v_mov_b32_e32 v41, v19
	v_lshl_add_u64 v[16:17], s[82:83], 0, v[20:21]
	v_lshl_add_u64 v[16:17], s[0:1], 1, v[16:17]
	v_lshlrev_b32_e32 v96, 1, v142
	v_lshl_add_u64 v[16:17], v[16:17], 0, v[96:97]
	v_cvt_pk_bf16_f32 v18, v38, v40
	v_cvt_pk_bf16_f32 v19, v39, v41
	global_store_dwordx2 v[16:17], v[18:19], off offset:-1024
	v_lshl_add_u64 v[16:17], s[30:31], 0, v[24:25]
	v_lshl_add_u64 v[16:17], s[92:93], 2, v[16:17]
	v_lshlrev_b32_e32 v18, 2, v37
	v_mov_b32_e32 v18, v8
	v_mov_b32_e32 v19, v8
	s_nop 1
	v_permlane16_swap_b32_e32 v18, v19
	v_cndmask_b32_e64 v18, v18, v19, s[6:7]
	v_cndmask_b32_e64 v19, v18, -v18, s[10:11]
	v_mov_b32_e32 v38, v8
	v_mov_b32_e32 v18, v242
	v_mov_b32_e32 v39, v246
	v_pk_mul_f32 v[18:19], v[38:39], v[18:19]
	v_mov_b32_e32 v32, v9
	v_add_f32_e32 v12, v18, v19
	v_mov_b32_e32 v18, v9
	v_mov_b32_e32 v19, v9
	s_nop 1
	v_permlane16_swap_b32_e32 v18, v19
	v_cndmask_b32_e64 v18, v18, v19, s[6:7]
	v_cndmask_b32_e64 v19, v18, -v18, s[10:11]
	v_mov_b32_e32 v18, v243
	v_mov_b32_e32 v33, v247
	v_pk_mul_f32 v[18:19], v[32:33], v[18:19]
	v_mov_b32_e32 v32, v10
	v_add_f32_e32 v13, v18, v19
	v_mov_b32_e32 v18, v10
	v_mov_b32_e32 v19, v10
	s_nop 1
	v_permlane16_swap_b32_e32 v18, v19
	v_cndmask_b32_e64 v18, v18, v19, s[6:7]
	v_cndmask_b32_e64 v19, v18, -v18, s[10:11]
	v_mov_b32_e32 v33, v248
	v_mov_b32_e32 v18, v244
	v_pk_mul_f32 v[18:19], v[32:33], v[18:19]
	v_mov_b32_e32 v34, v11
	v_add_f32_e32 v14, v18, v19
	v_mov_b32_e32 v18, v11
	v_mov_b32_e32 v19, v11
	s_nop 1
	v_permlane16_swap_b32_e32 v18, v19
	v_cndmask_b32_e64 v18, v18, v19, s[6:7]
	v_cndmask_b32_e64 v19, v18, -v18, s[10:11]
	v_mov_b32_e32 v18, v245
	v_mov_b32_e32 v35, v249
	v_pk_mul_f32 v[18:19], v[34:35], v[18:19]
	v_cndmask_b32_e64 v12, v8, v12, s[8:9]
	v_add_f32_e32 v15, v18, v19
	v_cndmask_b32_e64 v13, v9, v13, s[8:9]
	v_cndmask_b32_e64 v14, v10, v14, s[8:9]
	v_cndmask_b32_e64 v15, v11, v15, s[8:9]
	v_mov_b32_e32 v34, v12
	v_mov_b32_e32 v38, v13
	v_mov_b32_e32 v35, v14
	v_mov_b32_e32 v39, v15
	v_lshl_add_u64 v[12:13], s[82:83], 0, v[20:21]
	v_lshl_add_u64 v[12:13], s[0:1], 1, v[12:13]
	v_lshlrev_b32_e32 v96, 1, v142
	v_lshl_add_u64 v[12:13], v[12:13], 0, v[96:97]
	v_cvt_pk_bf16_f32 v14, v34, v38
	v_cvt_pk_bf16_f32 v15, v35, v39
	global_store_dwordx2 v[12:13], v[14:15], off offset:-1016
	s_mov_b64 s[70:71], 0x1100000
	v_lshl_add_u64 v[12:13], v[28:29], 0, s[70:71]
; __device__ __forceinline__ float shx16(float v, int odd  ) { const unsigned x = __builtin_bit_cast(unsigned, v); auto r = __builtin_amdgcn_permlane16_swap(x, x, false, false); return __builtin_bit_cast(float, odd ? r[0] : r[1]); }
; __device__ __forceinline__ void st_bf4(bf16_t* p, const f32x4 v) { u32x2 w; w.x = cvt_pk_bf16(v[0], v[1]); w.y = cvt_pk_bf16(v[2], v[3]); *(u32x2*)p = w; }
;     __device__ __forceinline__ void operator()(const f32x4 (&acc)[2][2][4][2], const Unit& u, int wr, int wc, int fr, int fq) const {
;     ...
;                                 const int tix = row < cfg::MP ? (row & 2047) : 2048 + (row & 3);
;                                 const f32x4 cs = *(const f32x4*)(ropec + tix * 8 + 4 * n), sn = *(const f32x4*)(ropes + tix * 8 + 4 * n);
; #pragma unroll
;                                 for (int i = 0; i < 4; ++i) { const float p = shx16(v[i], fq & 1); const float rv = v[i] * cs[i] + (fq == 0 ? -p : p) * sn[i]; v[i] = fq < 2 ? rv : v[i]; }
;                             }
;                             if (pn < 4) st_bf4(Q + (size_t)row * 512 + (pn - 2) * 256 + tc, v);
	v_lshlrev_b32_e32 v14, 2, v37
	v_mov_b32_e32 v14, v4
	v_mov_b32_e32 v15, v4
	s_nop 1
	v_permlane16_swap_b32_e32 v14, v15
	v_cndmask_b32_e64 v14, v14, v15, s[6:7]
	v_cndmask_b32_e64 v15, v14, -v14, s[10:11]
	v_mov_b32_e32 v18, v4
	v_mov_b32_e32 v14, v234
	v_mov_b32_e32 v19, v238
	v_pk_mul_f32 v[14:15], v[18:19], v[14:15]
	v_mov_b32_e32 v28, v5
	v_add_f32_e32 v8, v14, v15
	v_mov_b32_e32 v14, v5
	v_mov_b32_e32 v15, v5
	s_nop 1
	v_permlane16_swap_b32_e32 v14, v15
	v_cndmask_b32_e64 v14, v14, v15, s[6:7]
	v_cndmask_b32_e64 v15, v14, -v14, s[10:11]
	v_mov_b32_e32 v14, v235
	v_mov_b32_e32 v29, v239
	v_pk_mul_f32 v[14:15], v[28:29], v[14:15]
	v_mov_b32_e32 v18, v6
	v_add_f32_e32 v9, v14, v15
	v_mov_b32_e32 v14, v6
	v_mov_b32_e32 v15, v6
	s_nop 1
	v_permlane16_swap_b32_e32 v14, v15
	v_cndmask_b32_e64 v14, v14, v15, s[6:7]
	v_cndmask_b32_e64 v15, v14, -v14, s[10:11]
	v_mov_b32_e32 v19, v240
	v_mov_b32_e32 v14, v236
	v_pk_mul_f32 v[14:15], v[18:19], v[14:15]
	v_mov_b32_e32 v30, v7
	v_add_f32_e32 v10, v14, v15
	v_mov_b32_e32 v14, v7
	v_mov_b32_e32 v15, v7
	s_nop 1
	v_permlane16_swap_b32_e32 v14, v15
	v_cndmask_b32_e64 v14, v14, v15, s[6:7]
	v_cndmask_b32_e64 v15, v14, -v14, s[10:11]
	v_mov_b32_e32 v14, v237
	v_mov_b32_e32 v31, v241
	v_pk_mul_f32 v[14:15], v[30:31], v[14:15]
	v_cndmask_b32_e64 v8, v4, v8, s[8:9]
	v_add_f32_e32 v11, v14, v15
	v_cndmask_b32_e64 v9, v5, v9, s[8:9]
	v_cndmask_b32_e64 v10, v6, v10, s[8:9]
	v_cndmask_b32_e64 v11, v7, v11, s[8:9]
	v_mov_b32_e32 v28, v8
	v_mov_b32_e32 v30, v9
	v_mov_b32_e32 v29, v10
	v_mov_b32_e32 v31, v11
	v_lshl_add_u64 v[8:9], s[82:83], 0, v[20:21]
	v_lshl_add_u64 v[8:9], s[0:1], 1, v[8:9]
	v_lshlrev_b32_e32 v96, 1, v142
	v_lshl_add_u64 v[8:9], v[8:9], 0, v[96:97]
	v_cvt_pk_bf16_f32 v10, v28, v30
	v_cvt_pk_bf16_f32 v11, v29, v31
	global_store_dwordx2 v[8:9], v[10:11], off offset:-768
	s_mov_b32 s70, 0x1200000
	s_mov_b32 s71, 0x1400000
	v_lshlrev_b32_e32 v8, 2, v37
	v_mov_b32_e32 v14, v0
	v_mov_b32_e32 v15, v0
	s_nop 1
	v_permlane16_swap_b32_e32 v14, v15
	v_cndmask_b32_e64 v14, v14, v15, s[6:7]
	v_cndmask_b32_e64 v15, v14, -v14, s[10:11]
	v_mov_b32_e32 v18, v0
	v_mov_b32_e32 v14, v242
	v_mov_b32_e32 v19, v246
	v_pk_mul_f32 v[14:15], v[18:19], v[14:15]
	v_mov_b32_e32 v8, v1
	v_add_f32_e32 v4, v14, v15
	v_mov_b32_e32 v14, v1
	s_nop 1
	v_permlane16_swap_b32_e32 v8, v14
	v_cndmask_b32_e64 v8, v8, v14, s[6:7]
	v_cndmask_b32_e64 v15, v8, -v8, s[10:11]
	v_mov_b32_e32 v8, v1
	v_mov_b32_e32 v14, v243
	v_mov_b32_e32 v9, v247
	v_pk_mul_f32 v[8:9], v[8:9], v[14:15]
	v_mov_b32_e32 v14, v2
	v_add_f32_e32 v5, v8, v9
	v_mov_b32_e32 v8, v2
	v_mov_b32_e32 v9, v2
	s_nop 1
	v_permlane16_swap_b32_e32 v8, v9
	v_cndmask_b32_e64 v8, v8, v9, s[6:7]
	v_cndmask_b32_e64 v9, v8, -v8, s[10:11]
	v_mov_b32_e32 v15, v248
	v_mov_b32_e32 v8, v244
	v_pk_mul_f32 v[8:9], v[14:15], v[8:9]
	v_mov_b32_e32 v10, v3
	v_add_f32_e32 v6, v8, v9
	v_mov_b32_e32 v8, v3
	v_mov_b32_e32 v9, v3
	s_nop 1
	v_permlane16_swap_b32_e32 v8, v9
	v_cndmask_b32_e64 v8, v8, v9, s[6:7]
	v_cndmask_b32_e64 v9, v8, -v8, s[10:11]
	v_mov_b32_e32 v8, v245
	v_mov_b32_e32 v11, v249
	v_pk_mul_f32 v[8:9], v[10:11], v[8:9]
	v_cndmask_b32_e64 v4, v0, v4, s[8:9]
	v_add_f32_e32 v7, v8, v9
	v_cndmask_b32_e64 v5, v1, v5, s[8:9]
	v_cndmask_b32_e64 v6, v2, v6, s[8:9]
	v_cndmask_b32_e64 v7, v3, v7, s[8:9]
	v_mov_b32_e32 v14, v4
	v_mov_b32_e32 v18, v5
	v_mov_b32_e32 v15, v6
	v_mov_b32_e32 v19, v7
	s_mov_b64 s[14:15], -1
	v_lshl_add_u64 v[4:5], s[82:83], 0, v[20:21]
	v_lshl_add_u64 v[4:5], s[0:1], 1, v[4:5]
	v_lshlrev_b32_e32 v96, 1, v142
	v_lshl_add_u64 v[4:5], v[4:5], 0, v[96:97]
	v_cvt_pk_bf16_f32 v6, v14, v18
	v_cvt_pk_bf16_f32 v7, v15, v19
	global_store_dwordx2 v[4:5], v[6:7], off offset:-760
	s_branch .LBB0_1574

; __device__ __forceinline__ float shx16(float v, int odd  ) { const unsigned x = __builtin_bit_cast(unsigned, v); auto r = __builtin_amdgcn_permlane16_swap(x, x, false, false); return __builtin_bit_cast(float, odd ? r[0] : r[1]); }
; __device__ __forceinline__ void st_bf4(bf16_t* p, const f32x4 v) { u32x2 w; w.x = cvt_pk_bf16(v[0], v[1]); w.y = cvt_pk_bf16(v[2], v[3]); *(u32x2*)p = w; }
;     __device__ __forceinline__ void operator()(const f32x4 (&acc)[2][2][4][2], const Unit& u, int wr, int wc, int fr, int fq) const {
;     ...
;                                 const int tix = row < cfg::MP ? (row & 2047) : 2048 + (row & 3);
;                                 const f32x4 cs = *(const f32x4*)(ropec + tix * 8 + 4 * n), sn = *(const f32x4*)(ropes + tix * 8 + 4 * n);
; #pragma unroll
;                                 for (int i = 0; i < 4; ++i) { const float p = shx16(v[i], fq & 1); const float rv = v[i] * cs[i] + (fq == 0 ? -p : p) * sn[i]; v[i] = fq < 2 ? rv : v[i]; }
;                             }
;                             if (pn < 4) st_bf4(Q + (size_t)row * 512 + (pn - 2) * 256 + tc, v);
;                             else { st_bf4((bj == 0 ? KB : VB) + (size_t)row * 128 + (tc & 127), v);
;                                 bool w = false; size_t o = 0;
;                                 if (row < cfg::MP) { const int t = row & 2047; if (t >= 1920) { w = true; o = (bj == 0 ? cfg::OFF_KP : cfg::OFF_VP) + ((size_t)(layer * 8 + (row >> 11)) * 128 + (t - 1920)) * 128 + (tc & 127); } }
;                                 else { const int rs = row - cfg::MP; w = true; o = (bj == 0 ? cfg::OFF_KS : cfg::OFF_VS) + ((size_t)(layer * 128 + (rs >> 2)) * 128 + 124 + (rs & 3)) * 128 + (tc & 127); }
;                                 if (w) *(f32x4*)(out + o) = v; }
.Lsp_kv0:
	s_nop 7
	v_mov_b32_e32 v232, v172
	v_cmp_gt_i32_e32 vcc, 0x4000, v232
	v_and_b32_e32 v233, 0x7ff, v232
	s_nop 0
	v_cndmask_b32_e32 v233, v151, v233, vcc
	v_lshlrev_b32_e32 v224, 5, v233
	v_or_b32_e32 v232, 16, v172
	v_cmp_gt_i32_e32 vcc, 0x4000, v232
	v_and_b32_e32 v233, 0x7ff, v232
	s_nop 0
	v_cndmask_b32_e32 v233, v151, v233, vcc
	v_lshlrev_b32_e32 v225, 5, v233
	v_or_b32_e32 v232, 32, v172
	v_cmp_gt_i32_e32 vcc, 0x4000, v232
	v_and_b32_e32 v233, 0x7ff, v232
	s_nop 0
	v_cndmask_b32_e32 v233, v151, v233, vcc
	v_lshlrev_b32_e32 v226, 5, v233
	v_or_b32_e32 v232, 48, v172
	v_cmp_gt_i32_e32 vcc, 0x4000, v232
	v_and_b32_e32 v233, 0x7ff, v232
	s_nop 0
	v_cndmask_b32_e32 v233, v151, v233, vcc
	v_lshlrev_b32_e32 v227, 5, v233
	v_or_b32_e32 v232, 128, v172
	v_cmp_gt_i32_e32 vcc, 0x4000, v232
	v_and_b32_e32 v233, 0x7ff, v232
	s_nop 0
	v_cndmask_b32_e32 v233, v151, v233, vcc
	v_lshlrev_b32_e32 v228, 5, v233
	v_or_b32_e32 v232, 144, v172
	v_cmp_gt_i32_e32 vcc, 0x4000, v232
	v_and_b32_e32 v233, 0x7ff, v232
	s_nop 0
	v_cndmask_b32_e32 v233, v151, v233, vcc
	v_lshlrev_b32_e32 v229, 5, v233
	v_or_b32_e32 v232, 160, v172
	v_cmp_gt_i32_e32 vcc, 0x4000, v232
	v_and_b32_e32 v233, 0x7ff, v232
	s_nop 0
	v_cndmask_b32_e32 v233, v151, v233, vcc
	v_lshlrev_b32_e32 v230, 5, v233
	v_or_b32_e32 v232, 176, v172
	v_cmp_gt_i32_e32 vcc, 0x4000, v232
	v_and_b32_e32 v233, 0x7ff, v232
	s_nop 0
	v_cndmask_b32_e32 v233, v151, v233, vcc
	v_lshlrev_b32_e32 v231, 5, v233
	global_load_dwordx4 v[208:211], v224, s[44:45]
	global_load_dwordx4 v[212:215], v224, s[4:5]
	global_load_dwordx4 v[216:219], v224, s[44:45] offset:16
	global_load_dwordx4 v[220:223], v224, s[4:5] offset:16
	global_load_dwordx4 v[234:237], v225, s[44:45]
	global_load_dwordx4 v[238:241], v225, s[4:5]
	global_load_dwordx4 v[242:245], v225, s[44:45] offset:16
	global_load_dwordx4 v[246:249], v225, s[4:5] offset:16
	v_lshlrev_b32_e32 v96, 2, v203
	v_mov_b32_e32 v96, v126
	v_mov_b32_e32 v146, v126
	s_nop 1
	v_permlane16_swap_b32_e32 v96, v146
	v_cndmask_b32_e64 v96, v96, v146, s[6:7]
	v_cndmask_b32_e64 v147, v96, -v96, s[10:11]
	v_mov_b32_e32 v148, v126
	s_waitcnt vmcnt(4)
	v_mov_b32_e32 v146, v208
	v_mov_b32_e32 v149, v212
	v_pk_mul_f32 v[146:147], v[148:149], v[146:147]
	v_mov_b32_e32 v186, v127
	v_add_f32_e32 v96, v146, v147
	v_cndmask_b32_e64 v130, v126, v96, s[8:9]
	v_mov_b32_e32 v96, v127
	v_mov_b32_e32 v146, v127
	s_nop 1
	v_permlane16_swap_b32_e32 v96, v146
	v_cndmask_b32_e64 v96, v96, v146, s[6:7]
	v_cndmask_b32_e64 v147, v96, -v96, s[10:11]
	v_mov_b32_e32 v146, v209
	v_mov_b32_e32 v187, v213
	v_pk_mul_f32 v[146:147], v[186:187], v[146:147]
	v_mov_b32_e32 v148, v128
	v_add_f32_e32 v96, v146, v147
	v_cndmask_b32_e64 v131, v127, v96, s[8:9]
	v_mov_b32_e32 v96, v128
	v_mov_b32_e32 v146, v128
	s_nop 1
	v_permlane16_swap_b32_e32 v96, v146
	v_cndmask_b32_e64 v96, v96, v146, s[6:7]
	v_cndmask_b32_e64 v147, v96, -v96, s[10:11]
	v_mov_b32_e32 v149, v214
	v_mov_b32_e32 v146, v210
	v_pk_mul_f32 v[146:147], v[148:149], v[146:147]
	v_mov_b32_e32 v188, v129
	v_add_f32_e32 v96, v146, v147
	v_cndmask_b32_e64 v132, v128, v96, s[8:9]
	v_mov_b32_e32 v96, v129
	v_mov_b32_e32 v146, v129
	s_nop 1
	v_permlane16_swap_b32_e32 v96, v146
	v_cndmask_b32_e64 v96, v96, v146, s[6:7]
	v_cndmask_b32_e64 v147, v96, -v96, s[10:11]
	v_mov_b32_e32 v146, v211
	v_mov_b32_e32 v189, v215
	v_pk_mul_f32 v[146:147], v[188:189], v[146:147]
	v_mov_b32_e32 v173, v130
	v_add_f32_e32 v96, v146, v147
	v_cndmask_b32_e64 v133, v129, v96, s[8:9]
	v_mov_b32_e32 v205, v131
	v_mov_b32_e32 v204, v132
	v_mov_b32_e32 v206, v133
	v_lshl_add_u64 v[146:147], v[154:155], 0, v[176:177]
	v_cvt_pk_bf16_f32 v148, v173, v205
	v_cvt_pk_bf16_f32 v149, v204, v206
	global_store_dwordx2 v[146:147], v[148:149], off
	s_and_saveexec_b64 s[16:17], s[20:21]
	s_xor_b64 s[16:17], exec, s[16:17]
	s_mov_b64 s[14:15], exec
	v_add_u32_e32 v186, s87, v202
	s_or_saveexec_b64 s[16:17], s[16:17]
	v_mov_b64_e32 v[188:189], v[160:161]
	s_xor_b64 exec, exec, s[16:17]
	s_and_saveexec_b64 s[80:81], s[18:19]
	v_readlane_b32 s86, v254, 37
	s_add_i32 vcc_lo, s75, s86
	s_or_b64 s[92:93], s[14:15], exec
	v_readlane_b32 s87, v254, 38
	s_or_b64 exec, exec, s[80:81]
	s_andn2_b64 s[14:15], s[14:15], exec
	s_and_b64 s[80:81], s[92:93], exec
	v_mov_b32_e32 v186, vcc_lo
	s_or_b64 s[14:15], s[14:15], s[80:81]
	v_mov_b64_e32 v[188:189], v[184:185]
	v_readlane_b32 s86, v254, 63
	v_readlane_b32 s87, v255, 0
	s_or_b64 exec, exec, s[16:17]
	s_and_saveexec_b64 s[16:17], s[14:15]
	v_ashrrev_i32_e32 v187, 31, v186
	v_lshl_add_u64 v[146:147], v[188:189], 2, v[156:157]
	v_lshlrev_b64 v[148:149], 16, v[186:187]
	v_lshl_add_u64 v[146:147], v[146:147], 0, v[148:149]
	global_store_dwordx4 v[146:147], v[130:133], off
	s_or_b64 exec, exec, s[16:17]
	s_ashr_i32 s93, s0, 31
	s_mov_b32 s92, s0
	v_lshlrev_b32_e32 v130, 2, v142
	v_lshlrev_b32_e32 v96, 2, v203
	v_mov_b32_e32 v96, v122
	v_mov_b32_e32 v131, v122
	s_nop 1
	v_permlane16_swap_b32_e32 v96, v131
	v_cndmask_b32_e64 v96, v96, v131, s[6:7]
	v_cndmask_b32_e64 v147, v96, -v96, s[10:11]
	v_mov_b32_e32 v148, v122
	v_mov_b32_e32 v131, v123
	v_mov_b32_e32 v146, v216
	v_mov_b32_e32 v149, v220
	v_pk_mul_f32 v[146:147], v[148:149], v[146:147]
	v_mov_b32_e32 v186, v123
	v_add_f32_e32 v96, v146, v147
	v_cndmask_b32_e64 v126, v122, v96, s[8:9]
	v_mov_b32_e32 v96, v123
	s_nop 1
	v_permlane16_swap_b32_e32 v96, v131
	v_cndmask_b32_e64 v96, v96, v131, s[6:7]
	v_cndmask_b32_e64 v147, v96, -v96, s[10:11]
	v_mov_b32_e32 v146, v217
	v_mov_b32_e32 v187, v221
	v_pk_mul_f32 v[146:147], v[186:187], v[146:147]
	v_mov_b32_e32 v131, v124
	v_add_f32_e32 v96, v146, v147
; __device__ __forceinline__ float shx16(float v, int odd  ) { const unsigned x = __builtin_bit_cast(unsigned, v); auto r = __builtin_amdgcn_permlane16_swap(x, x, false, false); return __builtin_bit_cast(float, odd ? r[0] : r[1]); }
; __device__ __forceinline__ void st_bf4(bf16_t* p, const f32x4 v) { u32x2 w; w.x = cvt_pk_bf16(v[0], v[1]); w.y = cvt_pk_bf16(v[2], v[3]); *(u32x2*)p = w; }
;     __device__ __forceinline__ void operator()(const f32x4 (&acc)[2][2][4][2], const Unit& u, int wr, int wc, int fr, int fq) const {
;     ...
;                                 const int tix = row < cfg::MP ? (row & 2047) : 2048 + (row & 3);
;                                 const f32x4 cs = *(const f32x4*)(ropec + tix * 8 + 4 * n), sn = *(const f32x4*)(ropes + tix * 8 + 4 * n);
; #pragma unroll
;                                 for (int i = 0; i < 4; ++i) { const float p = shx16(v[i], fq & 1); const float rv = v[i] * cs[i] + (fq == 0 ? -p : p) * sn[i]; v[i] = fq < 2 ? rv : v[i]; }
;                             }
;                             if (pn < 4) st_bf4(Q + (size_t)row * 512 + (pn - 2) * 256 + tc, v);
;                             else { st_bf4((bj == 0 ? KB : VB) + (size_t)row * 128 + (tc & 127), v);
;                                 bool w = false; size_t o = 0;
;                                 if (row < cfg::MP) { const int t = row & 2047; if (t >= 1920) { w = true; o = (bj == 0 ? cfg::OFF_KP : cfg::OFF_VP) + ((size_t)(layer * 8 + (row >> 11)) * 128 + (t - 1920)) * 128 + (tc & 127); } }
;                                 else { const int rs = row - cfg::MP; w = true; o = (bj == 0 ? cfg::OFF_KS : cfg::OFF_VS) + ((size_t)(layer * 128 + (rs >> 2)) * 128 + 124 + (rs & 3)) * 128 + (tc & 127); }
;                                 if (w) *(f32x4*)(out + o) = v; }
	v_cndmask_b32_e64 v127, v123, v96, s[8:9]
	v_mov_b32_e32 v96, v124
	s_nop 1
	v_permlane16_swap_b32_e32 v96, v131
	v_cndmask_b32_e64 v96, v96, v131, s[6:7]
	v_cndmask_b32_e64 v147, v96, -v96, s[10:11]
	v_mov_b32_e32 v148, v124
	v_mov_b32_e32 v149, v222
	v_mov_b32_e32 v146, v218
	v_pk_mul_f32 v[146:147], v[148:149], v[146:147]
	v_mov_b32_e32 v131, v125
	v_add_f32_e32 v96, v146, v147
	v_cndmask_b32_e64 v128, v124, v96, s[8:9]
	v_mov_b32_e32 v96, v125
	s_nop 1
	v_permlane16_swap_b32_e32 v96, v131
	v_cndmask_b32_e64 v96, v96, v131, s[6:7]
	v_cndmask_b32_e64 v147, v96, -v96, s[10:11]
	v_mov_b32_e32 v188, v125
	v_mov_b32_e32 v146, v219
	v_mov_b32_e32 v189, v223
	v_pk_mul_f32 v[146:147], v[188:189], v[146:147]
	v_mov_b32_e32 v131, v126
	v_add_f32_e32 v96, v146, v147
	v_cndmask_b32_e64 v129, v125, v96, s[8:9]
	v_mov_b32_e32 v204, v127
	v_mov_b32_e32 v173, v128
	v_mov_b32_e32 v205, v129
	v_lshl_add_u64 v[146:147], v[164:165], 0, v[176:177]
	v_cvt_pk_bf16_f32 v148, v131, v204
	v_cvt_pk_bf16_f32 v149, v173, v205
	global_store_dwordx2 v[146:147], v[148:149], off
	s_and_saveexec_b64 s[78:79], s[20:21]
	s_xor_b64 s[78:79], exec, s[78:79]
	s_mov_b64 s[70:71], exec
	v_add_u32_e32 v186, s87, v202
	s_or_saveexec_b64 s[78:79], s[78:79]
	v_mov_b64_e32 v[188:189], v[160:161]
	s_xor_b64 exec, exec, s[78:79]
	s_and_saveexec_b64 s[80:81], s[18:19]
	v_readlane_b32 s86, v254, 37
	s_add_i32 s46, s75, s86
	s_or_b64 vcc, s[70:71], exec
	v_readlane_b32 s87, v254, 38
	s_or_b64 exec, exec, s[80:81]
	s_andn2_b64 s[70:71], s[70:71], exec
	s_and_b64 s[80:81], vcc, exec
	v_mov_b32_e32 v186, s46
	s_or_b64 s[70:71], s[70:71], s[80:81]
	v_mov_b64_e32 v[188:189], v[184:185]
	v_readlane_b32 s86, v254, 63
	v_readlane_b32 s87, v255, 0
	s_or_b64 exec, exec, s[78:79]
	s_and_saveexec_b64 s[78:79], s[70:71]
	v_ashrrev_i32_e32 v187, 31, v186
	v_lshl_add_u64 v[146:147], v[188:189], 2, v[156:157]
	v_lshlrev_b64 v[148:149], 16, v[186:187]
	v_lshl_add_u64 v[146:147], v[146:147], 0, v[148:149]
	global_store_dwordx4 v[146:147], v[126:129], off offset:16
	s_or_b64 exec, exec, s[78:79]
	v_readlane_b32 s70, v254, 59
	v_readlane_b32 s71, v254, 60
	s_mov_b64 s[78:79], 0x1100000
	v_lshl_add_u64 v[126:127], v[182:183], 0, s[78:79]
	v_mov_b64_e32 v[124:125], v[120:121]
	v_mov_b64_e32 v[122:123], v[118:119]
	v_mov_b32_e32 v131, v118
	v_mov_b32_e32 v184, v119
	v_mov_b32_e32 v173, v120
	v_mov_b32_e32 v185, v121
	v_lshl_add_u64 v[128:129], v[158:159], 0, v[176:177]
	v_cvt_pk_bf16_f32 v146, v131, v184
	v_cvt_pk_bf16_f32 v147, v173, v185
	global_store_dwordx2 v[128:129], v[146:147], off
	s_and_saveexec_b64 s[78:79], s[20:21]
	s_xor_b64 s[78:79], exec, s[78:79]
	s_mov_b64 s[70:71], exec
	v_add_u32_e32 v128, s87, v202
	s_or_saveexec_b64 s[78:79], s[78:79]
	v_mov_b64_e32 v[182:183], v[162:163]
	s_xor_b64 exec, exec, s[78:79]
	s_and_saveexec_b64 vcc, s[18:19]
	v_readlane_b32 s80, v254, 37
	v_readlane_b32 s81, v254, 38
	s_add_i32 s46, s75, s80
	s_or_b64 s[80:81], s[70:71], exec
	s_or_b64 exec, exec, vcc
	s_andn2_b64 s[70:71], s[70:71], exec
	s_and_b64 s[80:81], s[80:81], exec
	v_mov_b32_e32 v128, s46
	s_or_b64 s[70:71], s[70:71], s[80:81]
	v_mov_b64_e32 v[182:183], v[126:127]
	v_readlane_b32 s86, v254, 63
	v_readlane_b32 s87, v255, 0
	s_or_b64 exec, exec, s[78:79]
	s_and_saveexec_b64 s[78:79], s[70:71]
	v_ashrrev_i32_e32 v129, 31, v128
	v_lshl_add_u64 v[146:147], v[182:183], 2, v[156:157]
	v_lshlrev_b64 v[128:129], 16, v[128:129]
	v_lshl_add_u64 v[128:129], v[146:147], 0, v[128:129]
	global_store_dwordx4 v[128:129], v[122:125], off
	s_or_b64 exec, exec, s[78:79]
	v_mov_b64_e32 v[120:121], v[116:117]
	v_mov_b64_e32 v[118:119], v[114:115]
	v_mov_b32_e32 v128, v114
	v_mov_b32_e32 v131, v115
	v_mov_b32_e32 v129, v116
	v_mov_b32_e32 v173, v117
	s_andn2_b64 vcc, exec, s[96:97]
	v_lshl_add_u64 v[122:123], v[166:167], 0, v[176:177]
	v_cvt_pk_bf16_f32 v124, v128, v131
	v_cvt_pk_bf16_f32 v125, v129, v173
	global_store_dwordx2 v[122:123], v[124:125], off
	s_and_saveexec_b64 s[78:79], s[20:21]
	s_xor_b64 s[20:21], exec, s[78:79]
	s_mov_b64 s[70:71], exec
	v_add_u32_e32 v122, s87, v202
	s_or_saveexec_b64 s[20:21], s[20:21]
	v_mov_b64_e32 v[124:125], v[162:163]
	s_xor_b64 exec, exec, s[20:21]
	s_and_saveexec_b64 s[80:81], s[18:19]
	v_readlane_b32 s18, v254, 37
	s_add_i32 s46, s75, s18
	s_or_b64 s[78:79], s[70:71], exec
	v_readlane_b32 s19, v254, 38
	s_or_b64 exec, exec, s[80:81]
	s_andn2_b64 s[18:19], s[70:71], exec
	s_and_b64 s[70:71], s[78:79], exec
	v_mov_b32_e32 v122, s46
	s_or_b64 s[70:71], s[18:19], s[70:71]
	v_mov_b64_e32 v[124:125], v[126:127]
	s_or_b64 exec, exec, s[20:21]
	s_and_saveexec_b64 s[18:19], s[70:71]
	v_ashrrev_i32_e32 v123, 31, v122
	v_lshl_add_u64 v[124:125], v[124:125], 2, v[156:157]
	v_lshlrev_b64 v[122:123], 16, v[122:123]
	v_lshl_add_u64 v[122:123], v[124:125], 0, v[122:123]
	global_store_dwordx4 v[122:123], v[118:121], off offset:16
	s_or_b64 exec, exec, s[18:19]
	v_or_b32_e32 v114, 16, v172
	v_mad_i64_i32 v[124:125], s[18:19], v114, s61, 0
	s_movk_i32 s18, 0x3fff
	s_nop 0
	v_cmp_lt_i32_e64 s[20:21], s18, v114
	s_movk_i32 s18, 0x7df
	v_bitop3_b32 v96, v172, s18, 16 bitop3:0xc8
	s_movk_i32 s18, 0x4000
	v_cmp_gt_i32_e32 vcc, s18, v114
	s_movk_i32 s18, 0x77f
	v_cmp_lt_u32_e64 s[18:19], s18, v96
	v_cndmask_b32_e32 v116, v151, v96, vcc
	v_add_u32_e32 v96, 0xfffff880, v96
	v_ashrrev_i32_e32 v115, 31, v114
	v_lshlrev_b32_e32 v176, 3, v116
	v_add_u32_e32 v116, 0xffffc010, v172
	v_lshlrev_b64 v[126:127], 7, v[96:97]
	s_mov_b64 s[70:71], 0x1080000
	v_lshlrev_b64 v[120:121], 8, v[114:115]
	v_lshrrev_b32_e32 v173, 2, v116
	v_lshl_add_u64 v[128:129], v[126:127], 0, s[70:71]
	v_lshlrev_b32_e32 v96, 2, v176
	global_load_dwordx4 v[208:211], v226, s[44:45]
	global_load_dwordx4 v[212:215], v226, s[4:5]
	global_load_dwordx4 v[216:219], v226, s[44:45] offset:16
	global_load_dwordx4 v[220:223], v226, s[4:5] offset:16
	v_mov_b32_e32 v96, v110
	v_mov_b32_e32 v131, v110
	s_nop 1
	v_permlane16_swap_b32_e32 v96, v131
	v_cndmask_b32_e64 v96, v96, v131, s[6:7]
	v_cndmask_b32_e64 v133, v96, -v96, s[10:11]
	v_mov_b32_e32 v146, v110
	v_mov_b32_e32 v131, v111
	s_waitcnt vmcnt(8)
; __device__ __forceinline__ float shx16(float v, int odd  ) { const unsigned x = __builtin_bit_cast(unsigned, v); auto r = __builtin_amdgcn_permlane16_swap(x, x, false, false); return __builtin_bit_cast(float, odd ? r[0] : r[1]); }
; __device__ __forceinline__ void st_bf4(bf16_t* p, const f32x4 v) { u32x2 w; w.x = cvt_pk_bf16(v[0], v[1]); w.y = cvt_pk_bf16(v[2], v[3]); *(u32x2*)p = w; }
;     __device__ __forceinline__ void operator()(const f32x4 (&acc)[2][2][4][2], const Unit& u, int wr, int wc, int fr, int fq) const {
;     ...
;                                 const int tix = row < cfg::MP ? (row & 2047) : 2048 + (row & 3);
;                                 const f32x4 cs = *(const f32x4*)(ropec + tix * 8 + 4 * n), sn = *(const f32x4*)(ropes + tix * 8 + 4 * n);
; #pragma unroll
;                                 for (int i = 0; i < 4; ++i) { const float p = shx16(v[i], fq & 1); const float rv = v[i] * cs[i] + (fq == 0 ? -p : p) * sn[i]; v[i] = fq < 2 ? rv : v[i]; }
;                             }
;                             if (pn < 4) st_bf4(Q + (size_t)row * 512 + (pn - 2) * 256 + tc, v);
;                             else { st_bf4((bj == 0 ? KB : VB) + (size_t)row * 128 + (tc & 127), v);
;                                 bool w = false; size_t o = 0;
;                                 if (row < cfg::MP) { const int t = row & 2047; if (t >= 1920) { w = true; o = (bj == 0 ? cfg::OFF_KP : cfg::OFF_VP) + ((size_t)(layer * 8 + (row >> 11)) * 128 + (t - 1920)) * 128 + (tc & 127); } }
;                                 else { const int rs = row - cfg::MP; w = true; o = (bj == 0 ? cfg::OFF_KS : cfg::OFF_VS) + ((size_t)(layer * 128 + (rs >> 2)) * 128 + 124 + (rs & 3)) * 128 + (tc & 127); }
;                                 if (w) *(f32x4*)(out + o) = v; }
	v_mov_b32_e32 v132, v234
	v_mov_b32_e32 v147, v238
	v_pk_mul_f32 v[132:133], v[146:147], v[132:133]
	v_mov_b32_e32 v178, v111
	v_add_f32_e32 v96, v132, v133
	v_cndmask_b32_e64 v114, v110, v96, s[8:9]
	v_mov_b32_e32 v96, v111
	s_nop 1
	v_permlane16_swap_b32_e32 v96, v131
	v_cndmask_b32_e64 v96, v96, v131, s[6:7]
	v_cndmask_b32_e64 v133, v96, -v96, s[10:11]
	v_mov_b32_e32 v132, v235
	v_mov_b32_e32 v179, v239
	v_pk_mul_f32 v[132:133], v[178:179], v[132:133]
	v_mov_b32_e32 v131, v112
	v_add_f32_e32 v96, v132, v133
	v_cndmask_b32_e64 v115, v111, v96, s[8:9]
	v_mov_b32_e32 v96, v112
	s_nop 1
	v_permlane16_swap_b32_e32 v96, v131
	v_cndmask_b32_e64 v96, v96, v131, s[6:7]
	v_cndmask_b32_e64 v133, v96, -v96, s[10:11]
	v_mov_b32_e32 v146, v112
	v_mov_b32_e32 v147, v240
	v_mov_b32_e32 v132, v236
	v_pk_mul_f32 v[132:133], v[146:147], v[132:133]
	v_mov_b32_e32 v131, v113
	v_add_f32_e32 v96, v132, v133
	v_cndmask_b32_e64 v116, v112, v96, s[8:9]
	v_mov_b32_e32 v96, v113
	s_nop 1
	v_permlane16_swap_b32_e32 v96, v131
	v_cndmask_b32_e64 v96, v96, v131, s[6:7]
	v_cndmask_b32_e64 v133, v96, -v96, s[10:11]
	v_mov_b32_e32 v180, v113
	v_mov_b32_e32 v132, v237
	v_mov_b32_e32 v181, v241
	v_pk_mul_f32 v[132:133], v[180:181], v[132:133]
	v_mov_b32_e32 v131, v114
	v_add_f32_e32 v96, v132, v133
	v_cndmask_b32_e64 v117, v113, v96, s[8:9]
	v_mov_b32_e32 v178, v115
	v_mov_b32_e32 v177, v116
	v_mov_b32_e32 v179, v117
	v_lshl_add_u64 v[132:133], v[154:155], 0, v[120:121]
	v_cvt_pk_bf16_f32 v146, v131, v178
	v_cvt_pk_bf16_f32 v147, v177, v179
	global_store_dwordx2 v[132:133], v[146:147], off
	s_and_saveexec_b64 s[78:79], s[20:21]
	s_xor_b64 s[78:79], exec, s[78:79]
	s_mov_b64 s[70:71], exec
	v_add_u32_e32 v132, s87, v173
	s_or_saveexec_b64 s[78:79], s[78:79]
	v_mov_b64_e32 v[174:175], v[160:161]
	s_xor_b64 exec, exec, s[78:79]
	s_and_saveexec_b64 vcc, s[18:19]
	v_readlane_b32 s80, v254, 37
	v_readlane_b32 s81, v254, 38
	s_add_i32 s46, s75, s80
	s_or_b64 s[80:81], s[70:71], exec
	s_or_b64 exec, exec, vcc
	s_andn2_b64 s[70:71], s[70:71], exec
	s_and_b64 s[80:81], s[80:81], exec
	v_mov_b32_e32 v132, s46
	s_or_b64 s[70:71], s[70:71], s[80:81]
	v_mov_b64_e32 v[174:175], v[128:129]
	v_readlane_b32 s86, v254, 63
	v_readlane_b32 s87, v255, 0
	s_or_b64 exec, exec, s[78:79]
	s_and_saveexec_b64 s[78:79], s[70:71]
	v_ashrrev_i32_e32 v133, 31, v132
	v_lshl_add_u64 v[146:147], v[174:175], 2, v[156:157]
	v_lshlrev_b64 v[132:133], 16, v[132:133]
	v_lshl_add_u64 v[132:133], v[146:147], 0, v[132:133]
	global_store_dwordx4 v[132:133], v[114:117], off
	s_or_b64 exec, exec, s[78:79]
	v_lshlrev_b32_e32 v96, 2, v176
	v_mov_b32_e32 v96, v106
	v_mov_b32_e32 v116, v106
	s_nop 1
	v_permlane16_swap_b32_e32 v96, v116
	v_cndmask_b32_e64 v96, v96, v116, s[6:7]
	v_cndmask_b32_e64 v117, v96, -v96, s[10:11]
	v_mov_b32_e32 v132, v106
	v_mov_b32_e32 v116, v242
	v_mov_b32_e32 v133, v246
	v_pk_mul_f32 v[116:117], v[132:133], v[116:117]
	v_mov_b32_e32 v178, v107
	v_add_f32_e32 v96, v116, v117
	v_cndmask_b32_e64 v110, v106, v96, s[8:9]
	v_mov_b32_e32 v96, v107
	v_mov_b32_e32 v116, v107
	s_nop 1
	v_permlane16_swap_b32_e32 v96, v116
	v_cndmask_b32_e64 v96, v96, v116, s[6:7]
	v_cndmask_b32_e64 v117, v96, -v96, s[10:11]
	v_mov_b32_e32 v116, v243
	v_mov_b32_e32 v179, v247
	v_pk_mul_f32 v[116:117], v[178:179], v[116:117]
	v_mov_b32_e32 v132, v108
	v_add_f32_e32 v96, v116, v117
	v_cndmask_b32_e64 v111, v107, v96, s[8:9]
	v_mov_b32_e32 v96, v108
	v_mov_b32_e32 v116, v108
	s_nop 1
	v_permlane16_swap_b32_e32 v96, v116
	v_cndmask_b32_e64 v96, v96, v116, s[6:7]
	v_cndmask_b32_e64 v117, v96, -v96, s[10:11]
	v_mov_b32_e32 v133, v248
	v_mov_b32_e32 v116, v244
	v_pk_mul_f32 v[116:117], v[132:133], v[116:117]
	v_mov_b32_e32 v180, v109
	v_add_f32_e32 v96, v116, v117
	v_cndmask_b32_e64 v112, v108, v96, s[8:9]
	v_mov_b32_e32 v96, v109
	v_mov_b32_e32 v116, v109
	s_nop 1
	v_permlane16_swap_b32_e32 v96, v116
	v_cndmask_b32_e64 v96, v96, v116, s[6:7]
	v_cndmask_b32_e64 v117, v96, -v96, s[10:11]
	v_mov_b32_e32 v116, v245
	v_mov_b32_e32 v181, v249
	v_pk_mul_f32 v[116:117], v[180:181], v[116:117]
	v_mov_b32_e32 v131, v110
	v_add_f32_e32 v96, v116, v117
	v_cndmask_b32_e64 v113, v109, v96, s[8:9]
	v_mov_b32_e32 v175, v111
	v_mov_b32_e32 v174, v112
	v_mov_b32_e32 v177, v113
	v_lshl_add_u64 v[116:117], v[164:165], 0, v[120:121]
	v_cvt_pk_bf16_f32 v132, v131, v175
	v_cvt_pk_bf16_f32 v133, v174, v177
	global_store_dwordx2 v[116:117], v[132:133], off
	s_and_saveexec_b64 s[78:79], s[20:21]
	s_xor_b64 s[78:79], exec, s[78:79]
	s_mov_b64 s[70:71], exec
	v_add_u32_e32 v116, s87, v173
	s_or_saveexec_b64 s[78:79], s[78:79]
	v_mov_b64_e32 v[132:133], v[160:161]
	s_xor_b64 exec, exec, s[78:79]
	s_and_saveexec_b64 vcc, s[18:19]
	v_readlane_b32 s80, v254, 37
	v_readlane_b32 s81, v254, 38
	s_add_i32 s46, s75, s80
	s_or_b64 s[80:81], s[70:71], exec
	s_or_b64 exec, exec, vcc
	s_andn2_b64 s[70:71], s[70:71], exec
	s_and_b64 s[80:81], s[80:81], exec
	v_mov_b32_e32 v116, s46
	s_or_b64 s[70:71], s[70:71], s[80:81]
	v_mov_b64_e32 v[132:133], v[128:129]
	v_readlane_b32 s86, v254, 63
	v_readlane_b32 s87, v255, 0
	s_or_b64 exec, exec, s[78:79]
	s_and_saveexec_b64 s[78:79], s[70:71]
	v_ashrrev_i32_e32 v117, 31, v116
	v_lshl_add_u64 v[128:129], v[132:133], 2, v[156:157]
	v_lshlrev_b64 v[116:117], 16, v[116:117]
	v_lshl_add_u64 v[116:117], v[128:129], 0, v[116:117]
	global_store_dwordx4 v[116:117], v[110:113], off offset:16
	s_or_b64 exec, exec, s[78:79]
	s_mov_b64 s[70:71], 0x1100000
	v_lshl_add_u64 v[110:111], v[126:127], 0, s[70:71]
	v_mov_b64_e32 v[108:109], v[104:105]
	v_mov_b64_e32 v[106:107], v[102:103]
	v_mov_b32_e32 v126, v102
	v_mov_b32_e32 v128, v103
; __device__ __forceinline__ float shx16(float v, int odd  ) { const unsigned x = __builtin_bit_cast(unsigned, v); auto r = __builtin_amdgcn_permlane16_swap(x, x, false, false); return __builtin_bit_cast(float, odd ? r[0] : r[1]); }
; __device__ __forceinline__ void st_bf4(bf16_t* p, const f32x4 v) { u32x2 w; w.x = cvt_pk_bf16(v[0], v[1]); w.y = cvt_pk_bf16(v[2], v[3]); *(u32x2*)p = w; }
;     __device__ __forceinline__ void operator()(const f32x4 (&acc)[2][2][4][2], const Unit& u, int wr, int wc, int fr, int fq) const {
;     ...
;                                 const int tix = row < cfg::MP ? (row & 2047) : 2048 + (row & 3);
;                                 const f32x4 cs = *(const f32x4*)(ropec + tix * 8 + 4 * n), sn = *(const f32x4*)(ropes + tix * 8 + 4 * n);
; #pragma unroll
;                                 for (int i = 0; i < 4; ++i) { const float p = shx16(v[i], fq & 1); const float rv = v[i] * cs[i] + (fq == 0 ? -p : p) * sn[i]; v[i] = fq < 2 ? rv : v[i]; }
;                             }
;                             if (pn < 4) st_bf4(Q + (size_t)row * 512 + (pn - 2) * 256 + tc, v);
;                             else { st_bf4((bj == 0 ? KB : VB) + (size_t)row * 128 + (tc & 127), v);
;                                 bool w = false; size_t o = 0;
;                                 if (row < cfg::MP) { const int t = row & 2047; if (t >= 1920) { w = true; o = (bj == 0 ? cfg::OFF_KP : cfg::OFF_VP) + ((size_t)(layer * 8 + (row >> 11)) * 128 + (t - 1920)) * 128 + (tc & 127); } }
;                                 else { const int rs = row - cfg::MP; w = true; o = (bj == 0 ? cfg::OFF_KS : cfg::OFF_VS) + ((size_t)(layer * 128 + (rs >> 2)) * 128 + 124 + (rs & 3)) * 128 + (tc & 127); }
;                                 if (w) *(f32x4*)(out + o) = v; }
	v_mov_b32_e32 v127, v104
	v_mov_b32_e32 v129, v105
	v_lshl_add_u64 v[112:113], v[158:159], 0, v[120:121]
	v_cvt_pk_bf16_f32 v116, v126, v128
	v_cvt_pk_bf16_f32 v117, v127, v129
	global_store_dwordx2 v[112:113], v[116:117], off
	s_and_saveexec_b64 s[78:79], s[20:21]
	s_xor_b64 s[78:79], exec, s[78:79]
	s_mov_b64 s[70:71], exec
	v_add_u32_e32 v112, s87, v173
	s_or_saveexec_b64 s[78:79], s[78:79]
	v_mov_b64_e32 v[116:117], v[162:163]
	s_xor_b64 exec, exec, s[78:79]
	s_and_saveexec_b64 vcc, s[18:19]
	v_readlane_b32 s80, v254, 37
	v_readlane_b32 s81, v254, 38
	s_add_i32 s46, s75, s80
	s_or_b64 s[80:81], s[70:71], exec
	s_or_b64 exec, exec, vcc
	s_andn2_b64 s[70:71], s[70:71], exec
	s_and_b64 s[80:81], s[80:81], exec
	v_mov_b32_e32 v112, s46
	s_or_b64 s[70:71], s[70:71], s[80:81]
	v_mov_b64_e32 v[116:117], v[110:111]
	v_readlane_b32 s86, v254, 63
	v_readlane_b32 s87, v255, 0
	s_or_b64 exec, exec, s[78:79]
	s_and_saveexec_b64 s[78:79], s[70:71]
	v_ashrrev_i32_e32 v113, 31, v112
	v_lshl_add_u64 v[116:117], v[116:117], 2, v[156:157]
	v_lshlrev_b64 v[112:113], 16, v[112:113]
	v_lshl_add_u64 v[112:113], v[116:117], 0, v[112:113]
	global_store_dwordx4 v[112:113], v[106:109], off
	s_or_b64 exec, exec, s[78:79]
	v_mov_b64_e32 v[104:105], v[100:101]
	v_mov_b64_e32 v[102:103], v[98:99]
	v_mov_b32_e32 v112, v98
	v_mov_b32_e32 v116, v99
	v_mov_b32_e32 v113, v100
	v_mov_b32_e32 v117, v101
	s_andn2_b64 vcc, exec, s[96:97]
	v_lshl_add_u64 v[106:107], v[166:167], 0, v[120:121]
	v_cvt_pk_bf16_f32 v108, v112, v116
	v_cvt_pk_bf16_f32 v109, v113, v117
	global_store_dwordx2 v[106:107], v[108:109], off
	s_and_saveexec_b64 s[78:79], s[20:21]
	s_xor_b64 s[20:21], exec, s[78:79]
	s_mov_b64 s[70:71], exec
	v_add_u32_e32 v106, s87, v173
	s_or_saveexec_b64 s[20:21], s[20:21]
	v_mov_b64_e32 v[108:109], v[162:163]
	s_xor_b64 exec, exec, s[20:21]
	s_and_saveexec_b64 s[80:81], s[18:19]
	v_readlane_b32 s18, v254, 37
	s_add_i32 s46, s75, s18
	s_or_b64 s[78:79], s[70:71], exec
	v_readlane_b32 s19, v254, 38
	s_or_b64 exec, exec, s[80:81]
	s_andn2_b64 s[18:19], s[70:71], exec
	s_and_b64 s[70:71], s[78:79], exec
	v_mov_b32_e32 v106, s46
	s_or_b64 s[70:71], s[18:19], s[70:71]
	v_mov_b64_e32 v[108:109], v[110:111]
	s_or_b64 exec, exec, s[20:21]
	s_and_saveexec_b64 s[18:19], s[70:71]
	v_ashrrev_i32_e32 v107, 31, v106
	v_lshl_add_u64 v[108:109], v[108:109], 2, v[156:157]
	v_lshlrev_b64 v[106:107], 16, v[106:107]
	v_lshl_add_u64 v[106:107], v[108:109], 0, v[106:107]
	global_store_dwordx4 v[106:107], v[102:105], off offset:16
	s_or_b64 exec, exec, s[18:19]
	v_or_b32_e32 v98, 32, v172
	v_mad_i64_i32 v[108:109], s[18:19], v98, s61, 0
	s_movk_i32 s18, 0x3fff
	s_nop 0
	v_cmp_lt_i32_e64 s[20:21], s18, v98
	s_movk_i32 s18, 0x7ef
	v_bitop3_b32 v96, v172, s18, 32 bitop3:0xc8
	s_movk_i32 s18, 0x4000
	v_cmp_gt_i32_e32 vcc, s18, v98
	s_movk_i32 s18, 0x77f
	v_cmp_lt_u32_e64 s[18:19], s18, v96
	v_cndmask_b32_e32 v100, v151, v96, vcc
	v_add_u32_e32 v96, 0xfffff880, v96
	v_ashrrev_i32_e32 v99, 31, v98
	v_lshlrev_b32_e32 v119, 3, v100
	v_add_u32_e32 v100, 0xffffc020, v172
	v_lshlrev_b64 v[110:111], 7, v[96:97]
	s_mov_b64 s[70:71], 0x1080000
	v_lshlrev_b64 v[104:105], 8, v[98:99]
	v_lshrrev_b32_e32 v118, 2, v100
	v_lshl_add_u64 v[112:113], v[110:111], 0, s[70:71]
	v_lshlrev_b32_e32 v96, 2, v119
	global_load_dwordx4 v[234:237], v227, s[44:45]
	global_load_dwordx4 v[238:241], v227, s[4:5]
	global_load_dwordx4 v[242:245], v227, s[44:45] offset:16
	global_load_dwordx4 v[246:249], v227, s[4:5] offset:16
	v_mov_b32_e32 v96, v92
	v_mov_b32_e32 v120, v92
	s_nop 1
	v_permlane16_swap_b32_e32 v96, v120
	v_cndmask_b32_e64 v96, v96, v120, s[6:7]
	v_cndmask_b32_e64 v121, v96, -v96, s[10:11]
	v_mov_b32_e32 v122, v92
	s_waitcnt vmcnt(8)
	v_mov_b32_e32 v120, v208
	v_mov_b32_e32 v123, v212
	v_pk_mul_f32 v[120:121], v[122:123], v[120:121]
	v_mov_b32_e32 v114, v93
	v_add_f32_e32 v96, v120, v121
	v_cndmask_b32_e64 v98, v92, v96, s[8:9]
	v_mov_b32_e32 v96, v93
	s_nop 1
	v_permlane16_swap_b32_e32 v96, v114
	v_cndmask_b32_e64 v96, v96, v114, s[6:7]
	v_cndmask_b32_e64 v121, v96, -v96, s[10:11]
	v_mov_b32_e32 v114, v93
	v_mov_b32_e32 v120, v209
	v_mov_b32_e32 v115, v213
	v_pk_mul_f32 v[114:115], v[114:115], v[120:121]
	v_mov_b32_e32 v120, v94
	v_add_f32_e32 v96, v114, v115
	v_cndmask_b32_e64 v99, v93, v96, s[8:9]
	v_mov_b32_e32 v96, v94
	v_mov_b32_e32 v114, v94
	s_nop 1
	v_permlane16_swap_b32_e32 v96, v114
	v_cndmask_b32_e64 v96, v96, v114, s[6:7]
	v_cndmask_b32_e64 v115, v96, -v96, s[10:11]
	v_mov_b32_e32 v121, v214
	v_mov_b32_e32 v114, v210
	v_pk_mul_f32 v[114:115], v[120:121], v[114:115]
	v_mov_b32_e32 v116, v95
	v_add_f32_e32 v96, v114, v115
	v_cndmask_b32_e64 v100, v94, v96, s[8:9]
	v_mov_b32_e32 v96, v95
	v_mov_b32_e32 v114, v95
	s_nop 1
	v_permlane16_swap_b32_e32 v96, v114
	v_cndmask_b32_e64 v96, v96, v114, s[6:7]
	v_cndmask_b32_e64 v115, v96, -v96, s[10:11]
	v_mov_b32_e32 v114, v211
	v_mov_b32_e32 v117, v215
	v_pk_mul_f32 v[114:115], v[116:117], v[114:115]
	v_mov_b32_e32 v120, v98
	v_add_f32_e32 v96, v114, v115
	v_cndmask_b32_e64 v101, v95, v96, s[8:9]
	v_mov_b32_e32 v122, v99
	v_mov_b32_e32 v121, v100
	v_mov_b32_e32 v123, v101
	v_lshl_add_u64 v[114:115], v[154:155], 0, v[104:105]
	v_cvt_pk_bf16_f32 v116, v120, v122
	v_cvt_pk_bf16_f32 v117, v121, v123
	global_store_dwordx2 v[114:115], v[116:117], off
	s_and_saveexec_b64 s[78:79], s[20:21]
	s_xor_b64 s[78:79], exec, s[78:79]
	s_mov_b64 s[70:71], exec
	v_add_u32_e32 v114, s87, v118
	s_or_saveexec_b64 s[78:79], s[78:79]
	v_mov_b64_e32 v[116:117], v[160:161]
	s_xor_b64 exec, exec, s[78:79]
	s_and_saveexec_b64 vcc, s[18:19]
	v_readlane_b32 s80, v254, 37
	v_readlane_b32 s81, v254, 38
; __device__ __forceinline__ float shx16(float v, int odd  ) { const unsigned x = __builtin_bit_cast(unsigned, v); auto r = __builtin_amdgcn_permlane16_swap(x, x, false, false); return __builtin_bit_cast(float, odd ? r[0] : r[1]); }
; __device__ __forceinline__ void st_bf4(bf16_t* p, const f32x4 v) { u32x2 w; w.x = cvt_pk_bf16(v[0], v[1]); w.y = cvt_pk_bf16(v[2], v[3]); *(u32x2*)p = w; }
;     __device__ __forceinline__ void operator()(const f32x4 (&acc)[2][2][4][2], const Unit& u, int wr, int wc, int fr, int fq) const {
;     ...
;                                 const int tix = row < cfg::MP ? (row & 2047) : 2048 + (row & 3);
;                                 const f32x4 cs = *(const f32x4*)(ropec + tix * 8 + 4 * n), sn = *(const f32x4*)(ropes + tix * 8 + 4 * n);
; #pragma unroll
;                                 for (int i = 0; i < 4; ++i) { const float p = shx16(v[i], fq & 1); const float rv = v[i] * cs[i] + (fq == 0 ? -p : p) * sn[i]; v[i] = fq < 2 ? rv : v[i]; }
;                             }
;                             if (pn < 4) st_bf4(Q + (size_t)row * 512 + (pn - 2) * 256 + tc, v);
;                             else { st_bf4((bj == 0 ? KB : VB) + (size_t)row * 128 + (tc & 127), v);
;                                 bool w = false; size_t o = 0;
;                                 if (row < cfg::MP) { const int t = row & 2047; if (t >= 1920) { w = true; o = (bj == 0 ? cfg::OFF_KP : cfg::OFF_VP) + ((size_t)(layer * 8 + (row >> 11)) * 128 + (t - 1920)) * 128 + (tc & 127); } }
;                                 else { const int rs = row - cfg::MP; w = true; o = (bj == 0 ? cfg::OFF_KS : cfg::OFF_VS) + ((size_t)(layer * 128 + (rs >> 2)) * 128 + 124 + (rs & 3)) * 128 + (tc & 127); }
;                                 if (w) *(f32x4*)(out + o) = v; }
	s_add_i32 s46, s75, s80
	s_or_b64 s[80:81], s[70:71], exec
	s_or_b64 exec, exec, vcc
	s_andn2_b64 s[70:71], s[70:71], exec
	s_and_b64 s[80:81], s[80:81], exec
	v_mov_b32_e32 v114, s46
	s_or_b64 s[70:71], s[70:71], s[80:81]
	v_mov_b64_e32 v[116:117], v[112:113]
	v_readlane_b32 s86, v254, 63
	v_readlane_b32 s87, v255, 0
	s_or_b64 exec, exec, s[78:79]
	s_and_saveexec_b64 s[78:79], s[70:71]
	v_ashrrev_i32_e32 v115, 31, v114
	v_lshl_add_u64 v[116:117], v[116:117], 2, v[156:157]
	v_lshlrev_b64 v[114:115], 16, v[114:115]
	v_lshl_add_u64 v[114:115], v[116:117], 0, v[114:115]
	global_store_dwordx4 v[114:115], v[98:101], off
	s_or_b64 exec, exec, s[78:79]
	v_lshlrev_b32_e32 v96, 2, v119
	v_mov_b32_e32 v96, v88
	v_mov_b32_e32 v100, v88
	s_nop 1
	v_permlane16_swap_b32_e32 v96, v100
	v_cndmask_b32_e64 v96, v96, v100, s[6:7]
	v_cndmask_b32_e64 v101, v96, -v96, s[10:11]
	v_mov_b32_e32 v120, v88
	v_mov_b32_e32 v96, v89
	v_mov_b32_e32 v100, v216
	v_mov_b32_e32 v121, v220
	v_pk_mul_f32 v[100:101], v[120:121], v[100:101]
	v_mov_b32_e32 v114, v89
	v_add_f32_e32 v92, v100, v101
	v_mov_b32_e32 v100, v89
	s_nop 1
	v_permlane16_swap_b32_e32 v96, v100
	v_cndmask_b32_e64 v96, v96, v100, s[6:7]
	v_cndmask_b32_e64 v101, v96, -v96, s[10:11]
	v_mov_b32_e32 v100, v217
	v_mov_b32_e32 v115, v221
	v_pk_mul_f32 v[100:101], v[114:115], v[100:101]
	v_mov_b32_e32 v96, v90
	v_add_f32_e32 v93, v100, v101
	v_mov_b32_e32 v100, v90
	s_nop 1
	v_permlane16_swap_b32_e32 v96, v100
	v_cndmask_b32_e64 v96, v96, v100, s[6:7]
	v_cndmask_b32_e64 v101, v96, -v96, s[10:11]
	v_mov_b32_e32 v114, v90
	v_mov_b32_e32 v115, v222
	v_mov_b32_e32 v100, v218
	v_pk_mul_f32 v[100:101], v[114:115], v[100:101]
	v_mov_b32_e32 v96, v91
	v_add_f32_e32 v94, v100, v101
	v_mov_b32_e32 v100, v91
	s_nop 1
	v_permlane16_swap_b32_e32 v96, v100
	v_cndmask_b32_e64 v96, v96, v100, s[6:7]
	v_cndmask_b32_e64 v101, v96, -v96, s[10:11]
	v_mov_b32_e32 v116, v91
	v_mov_b32_e32 v100, v219
	v_mov_b32_e32 v117, v223
	v_pk_mul_f32 v[100:101], v[116:117], v[100:101]
	v_cndmask_b32_e64 v92, v88, v92, s[8:9]
	v_add_f32_e32 v95, v100, v101
	v_cndmask_b32_e64 v93, v89, v93, s[8:9]
	v_cndmask_b32_e64 v94, v90, v94, s[8:9]
	v_cndmask_b32_e64 v95, v91, v95, s[8:9]
	v_mov_b32_e32 v116, v92
	v_mov_b32_e32 v120, v93
	v_mov_b32_e32 v117, v94
	v_mov_b32_e32 v121, v95
	v_lshl_add_u64 v[100:101], v[164:165], 0, v[104:105]
	v_cvt_pk_bf16_f32 v114, v116, v120
	v_cvt_pk_bf16_f32 v115, v117, v121
	global_store_dwordx2 v[100:101], v[114:115], off
	s_and_saveexec_b64 s[78:79], s[20:21]
	s_xor_b64 s[78:79], exec, s[78:79]
	s_mov_b64 s[70:71], exec
	v_add_u32_e32 v100, s87, v118
	s_or_saveexec_b64 s[78:79], s[78:79]
	v_mov_b64_e32 v[114:115], v[160:161]
	s_xor_b64 exec, exec, s[78:79]
	s_and_saveexec_b64 vcc, s[18:19]
	v_readlane_b32 s80, v254, 37
	v_readlane_b32 s81, v254, 38
	s_add_i32 s46, s75, s80
	s_or_b64 s[80:81], s[70:71], exec
	s_or_b64 exec, exec, vcc
	s_andn2_b64 s[70:71], s[70:71], exec
	s_and_b64 s[80:81], s[80:81], exec
	v_mov_b32_e32 v100, s46
	s_or_b64 s[70:71], s[70:71], s[80:81]
	v_mov_b64_e32 v[114:115], v[112:113]
	v_readlane_b32 s86, v254, 63
	v_readlane_b32 s87, v255, 0
	s_or_b64 exec, exec, s[78:79]
	s_and_saveexec_b64 s[78:79], s[70:71]
	v_ashrrev_i32_e32 v101, 31, v100
	v_lshl_add_u64 v[112:113], v[114:115], 2, v[156:157]
	v_lshlrev_b64 v[100:101], 16, v[100:101]
	v_lshl_add_u64 v[100:101], v[112:113], 0, v[100:101]
	global_store_dwordx4 v[100:101], v[92:95], off offset:16
	s_or_b64 exec, exec, s[78:79]
	s_mov_b64 s[70:71], 0x1100000
	v_lshl_add_u64 v[92:93], v[110:111], 0, s[70:71]
	v_mov_b64_e32 v[90:91], v[86:87]
	v_mov_b64_e32 v[88:89], v[84:85]
	v_mov_b32_e32 v110, v84
	v_mov_b32_e32 v112, v85
	v_mov_b32_e32 v111, v86
	v_mov_b32_e32 v113, v87
	v_lshl_add_u64 v[94:95], v[158:159], 0, v[104:105]
	v_cvt_pk_bf16_f32 v100, v110, v112
	v_cvt_pk_bf16_f32 v101, v111, v113
	global_store_dwordx2 v[94:95], v[100:101], off
	s_and_saveexec_b64 s[78:79], s[20:21]
	s_xor_b64 s[78:79], exec, s[78:79]
	s_mov_b64 s[70:71], exec
	v_add_u32_e32 v94, s87, v118
	s_or_saveexec_b64 s[78:79], s[78:79]
	v_mov_b64_e32 v[100:101], v[162:163]
	s_xor_b64 exec, exec, s[78:79]
	s_and_saveexec_b64 vcc, s[18:19]
	v_readlane_b32 s80, v254, 37
	v_readlane_b32 s81, v254, 38
	s_add_i32 s46, s75, s80
	s_or_b64 s[80:81], s[70:71], exec
	s_or_b64 exec, exec, vcc
	s_andn2_b64 s[70:71], s[70:71], exec
	s_and_b64 s[80:81], s[80:81], exec
	v_mov_b32_e32 v94, s46
	s_or_b64 s[70:71], s[70:71], s[80:81]
	v_mov_b64_e32 v[100:101], v[92:93]
	v_readlane_b32 s86, v254, 63
	v_readlane_b32 s87, v255, 0
	s_or_b64 exec, exec, s[78:79]
	s_and_saveexec_b64 s[78:79], s[70:71]
	v_ashrrev_i32_e32 v95, 31, v94
	v_lshl_add_u64 v[100:101], v[100:101], 2, v[156:157]
	v_lshlrev_b64 v[94:95], 16, v[94:95]
	v_lshl_add_u64 v[94:95], v[100:101], 0, v[94:95]
	global_store_dwordx4 v[94:95], v[88:91], off
	s_or_b64 exec, exec, s[78:79]
	v_mov_b64_e32 v[86:87], v[82:83]
	v_mov_b64_e32 v[84:85], v[80:81]
	v_mov_b32_e32 v94, v80
	v_mov_b32_e32 v100, v81
	v_mov_b32_e32 v95, v82
	v_mov_b32_e32 v101, v83
	s_andn2_b64 vcc, exec, s[96:97]
	v_lshl_add_u64 v[88:89], v[166:167], 0, v[104:105]
	v_cvt_pk_bf16_f32 v90, v94, v100
	v_cvt_pk_bf16_f32 v91, v95, v101
	global_store_dwordx2 v[88:89], v[90:91], off
	s_and_saveexec_b64 s[78:79], s[20:21]
	s_xor_b64 s[20:21], exec, s[78:79]
	s_mov_b64 s[70:71], exec
	v_add_u32_e32 v88, s87, v118
	s_or_saveexec_b64 s[20:21], s[20:21]
	v_mov_b64_e32 v[90:91], v[162:163]
	s_xor_b64 exec, exec, s[20:21]
	s_and_saveexec_b64 s[80:81], s[18:19]
	v_readlane_b32 s18, v254, 37
	s_add_i32 s46, s75, s18
	s_or_b64 s[78:79], s[70:71], exec
	v_readlane_b32 s19, v254, 38
; __device__ __forceinline__ float shx16(float v, int odd  ) { const unsigned x = __builtin_bit_cast(unsigned, v); auto r = __builtin_amdgcn_permlane16_swap(x, x, false, false); return __builtin_bit_cast(float, odd ? r[0] : r[1]); }
; __device__ __forceinline__ void st_bf4(bf16_t* p, const f32x4 v) { u32x2 w; w.x = cvt_pk_bf16(v[0], v[1]); w.y = cvt_pk_bf16(v[2], v[3]); *(u32x2*)p = w; }
;     __device__ __forceinline__ void operator()(const f32x4 (&acc)[2][2][4][2], const Unit& u, int wr, int wc, int fr, int fq) const {
;     ...
;                                 const int tix = row < cfg::MP ? (row & 2047) : 2048 + (row & 3);
;                                 const f32x4 cs = *(const f32x4*)(ropec + tix * 8 + 4 * n), sn = *(const f32x4*)(ropes + tix * 8 + 4 * n);
; #pragma unroll
;                                 for (int i = 0; i < 4; ++i) { const float p = shx16(v[i], fq & 1); const float rv = v[i] * cs[i] + (fq == 0 ? -p : p) * sn[i]; v[i] = fq < 2 ? rv : v[i]; }
;                             }
;                             if (pn < 4) st_bf4(Q + (size_t)row * 512 + (pn - 2) * 256 + tc, v);
;                             else { st_bf4((bj == 0 ? KB : VB) + (size_t)row * 128 + (tc & 127), v);
;                                 bool w = false; size_t o = 0;
;                                 if (row < cfg::MP) { const int t = row & 2047; if (t >= 1920) { w = true; o = (bj == 0 ? cfg::OFF_KP : cfg::OFF_VP) + ((size_t)(layer * 8 + (row >> 11)) * 128 + (t - 1920)) * 128 + (tc & 127); } }
;                                 else { const int rs = row - cfg::MP; w = true; o = (bj == 0 ? cfg::OFF_KS : cfg::OFF_VS) + ((size_t)(layer * 128 + (rs >> 2)) * 128 + 124 + (rs & 3)) * 128 + (tc & 127); }
;                                 if (w) *(f32x4*)(out + o) = v; }
	s_or_b64 exec, exec, s[80:81]
	s_andn2_b64 s[18:19], s[70:71], exec
	s_and_b64 s[70:71], s[78:79], exec
	v_mov_b32_e32 v88, s46
	s_or_b64 s[70:71], s[18:19], s[70:71]
	v_mov_b64_e32 v[90:91], v[92:93]
	s_or_b64 exec, exec, s[20:21]
	s_and_saveexec_b64 s[18:19], s[70:71]
	v_ashrrev_i32_e32 v89, 31, v88
	v_lshl_add_u64 v[90:91], v[90:91], 2, v[156:157]
	v_lshlrev_b64 v[88:89], 16, v[88:89]
	v_lshl_add_u64 v[88:89], v[90:91], 0, v[88:89]
	global_store_dwordx4 v[88:89], v[84:87], off offset:16
	s_or_b64 exec, exec, s[18:19]
	v_or_b32_e32 v80, 48, v172
	s_movk_i32 s18, 0x3fff
	v_cmp_lt_i32_e64 s[20:21], s18, v80
	s_movk_i32 s18, 0x7ff
	v_bitop3_b32 v82, v172, s18, 48 bitop3:0xc8
	s_movk_i32 s18, 0x4000
	v_cmp_gt_i32_e32 vcc, s18, v80
	v_add_u32_e32 v96, 0xfffff880, v82
	v_ashrrev_i32_e32 v81, 31, v80
	v_cndmask_b32_e32 v83, v151, v82, vcc
	v_lshlrev_b32_e32 v103, 3, v83
	v_add_u32_e32 v83, 0xffffc030, v172
	s_movk_i32 s18, 0x77f
	v_lshlrev_b64 v[92:93], 7, v[96:97]
	s_mov_b64 s[70:71], 0x1080000
	v_lshlrev_b64 v[86:87], 8, v[80:81]
	v_lshrrev_b32_e32 v102, 2, v83
	v_cmp_lt_u32_e64 s[18:19], s18, v82
	v_lshl_add_u64 v[94:95], v[92:93], 0, s[70:71]
	v_lshlrev_b32_e32 v96, 2, v103
	global_load_dwordx4 v[208:211], v228, s[44:45]
	global_load_dwordx4 v[212:215], v228, s[4:5]
	global_load_dwordx4 v[216:219], v228, s[44:45] offset:16
	global_load_dwordx4 v[220:223], v228, s[4:5] offset:16
	v_mov_b32_e32 v96, v76
	v_mov_b32_e32 v104, v76
	s_nop 1
	v_permlane16_swap_b32_e32 v96, v104
	v_cndmask_b32_e64 v96, v96, v104, s[6:7]
	v_cndmask_b32_e64 v105, v96, -v96, s[10:11]
	v_mov_b32_e32 v96, v77
	v_mov_b32_e32 v106, v76
	s_waitcnt vmcnt(8)
	v_mov_b32_e32 v104, v234
	v_mov_b32_e32 v107, v238
	v_mov_b32_e32 v98, v77
	s_nop 1
	v_permlane16_swap_b32_e32 v96, v98
	v_pk_mul_f32 v[104:105], v[106:107], v[104:105]
	v_cndmask_b32_e64 v96, v96, v98, s[6:7]
	v_add_f32_e32 v80, v104, v105
	v_cndmask_b32_e64 v105, v96, -v96, s[10:11]
	v_mov_b32_e32 v98, v77
	v_mov_b32_e32 v104, v235
	v_mov_b32_e32 v99, v239
	v_pk_mul_f32 v[98:99], v[98:99], v[104:105]
	v_mov_b32_e32 v96, v78
	v_add_f32_e32 v81, v98, v99
	v_mov_b32_e32 v98, v78
	s_nop 1
	v_permlane16_swap_b32_e32 v96, v98
	v_cndmask_b32_e64 v96, v96, v98, s[6:7]
	v_cndmask_b32_e64 v99, v96, -v96, s[10:11]
	v_mov_b32_e32 v104, v78
	v_mov_b32_e32 v105, v240
	v_mov_b32_e32 v98, v236
	v_pk_mul_f32 v[98:99], v[104:105], v[98:99]
	v_mov_b32_e32 v96, v79
	v_add_f32_e32 v82, v98, v99
	v_mov_b32_e32 v98, v79
	s_nop 1
	v_permlane16_swap_b32_e32 v96, v98
	v_cndmask_b32_e64 v96, v96, v98, s[6:7]
	v_cndmask_b32_e64 v99, v96, -v96, s[10:11]
	v_mov_b32_e32 v100, v79
	v_mov_b32_e32 v98, v237
	v_mov_b32_e32 v101, v241
	v_pk_mul_f32 v[98:99], v[100:101], v[98:99]
	v_cndmask_b32_e64 v80, v76, v80, s[8:9]
	v_add_f32_e32 v83, v98, v99
	v_cndmask_b32_e64 v81, v77, v81, s[8:9]
	v_cndmask_b32_e64 v82, v78, v82, s[8:9]
	v_cndmask_b32_e64 v83, v79, v83, s[8:9]
	v_mov_b32_e32 v104, v80
	v_mov_b32_e32 v106, v81
	v_mov_b32_e32 v105, v82
	v_mov_b32_e32 v107, v83
	v_lshl_add_u64 v[98:99], v[154:155], 0, v[86:87]
	v_cvt_pk_bf16_f32 v100, v104, v106
	v_cvt_pk_bf16_f32 v101, v105, v107
	global_store_dwordx2 v[98:99], v[100:101], off
	s_and_saveexec_b64 s[78:79], s[20:21]
	s_xor_b64 s[78:79], exec, s[78:79]
	s_mov_b64 s[70:71], exec
	v_add_u32_e32 v98, s87, v102
	s_or_saveexec_b64 s[78:79], s[78:79]
	v_mov_b64_e32 v[100:101], v[160:161]
	s_xor_b64 exec, exec, s[78:79]
	s_and_saveexec_b64 vcc, s[18:19]
	v_readlane_b32 s80, v254, 37
	v_readlane_b32 s81, v254, 38
	s_add_i32 s46, s75, s80
	s_or_b64 s[80:81], s[70:71], exec
	s_or_b64 exec, exec, vcc
	s_andn2_b64 s[70:71], s[70:71], exec
	s_and_b64 s[80:81], s[80:81], exec
	v_mov_b32_e32 v98, s46
	s_or_b64 s[70:71], s[70:71], s[80:81]
	v_mov_b64_e32 v[100:101], v[94:95]
	v_readlane_b32 s86, v254, 63
	v_readlane_b32 s87, v255, 0
	s_or_b64 exec, exec, s[78:79]
	s_and_saveexec_b64 s[78:79], s[70:71]
	v_ashrrev_i32_e32 v99, 31, v98
	v_lshl_add_u64 v[100:101], v[100:101], 2, v[156:157]
	v_lshlrev_b64 v[98:99], 16, v[98:99]
	v_lshl_add_u64 v[98:99], v[100:101], 0, v[98:99]
	global_store_dwordx4 v[98:99], v[80:83], off
	s_or_b64 exec, exec, s[78:79]
	s_nop 0
	v_lshlrev_b32_e32 v82, 2, v103
	v_mov_b32_e32 v82, v72
	v_mov_b32_e32 v83, v72
	s_nop 1
	v_permlane16_swap_b32_e32 v82, v83
	v_cndmask_b32_e64 v82, v82, v83, s[6:7]
	v_cndmask_b32_e64 v83, v82, -v82, s[10:11]
	v_mov_b32_e32 v104, v72
	v_mov_b32_e32 v82, v242
	v_mov_b32_e32 v105, v246
	v_pk_mul_f32 v[82:83], v[104:105], v[82:83]
	v_mov_b32_e32 v98, v73
	v_add_f32_e32 v76, v82, v83
	v_mov_b32_e32 v82, v73
	v_mov_b32_e32 v83, v73
	s_nop 1
	v_permlane16_swap_b32_e32 v82, v83
	v_cndmask_b32_e64 v82, v82, v83, s[6:7]
	v_cndmask_b32_e64 v83, v82, -v82, s[10:11]
	v_mov_b32_e32 v82, v243
	v_mov_b32_e32 v99, v247
	v_pk_mul_f32 v[82:83], v[98:99], v[82:83]
	v_mov_b32_e32 v98, v74
	v_add_f32_e32 v77, v82, v83
	v_mov_b32_e32 v82, v74
	v_mov_b32_e32 v83, v74
	s_nop 1
	v_permlane16_swap_b32_e32 v82, v83
	v_cndmask_b32_e64 v82, v82, v83, s[6:7]
	v_cndmask_b32_e64 v83, v82, -v82, s[10:11]
	v_mov_b32_e32 v99, v248
	v_mov_b32_e32 v82, v244
	v_pk_mul_f32 v[82:83], v[98:99], v[82:83]
	v_mov_b32_e32 v100, v75
	v_add_f32_e32 v78, v82, v83
	v_mov_b32_e32 v82, v75
	v_mov_b32_e32 v83, v75
	s_nop 1
	v_permlane16_swap_b32_e32 v82, v83
	v_cndmask_b32_e64 v82, v82, v83, s[6:7]
	v_cndmask_b32_e64 v83, v82, -v82, s[10:11]
	v_mov_b32_e32 v82, v245
	v_mov_b32_e32 v101, v249
	v_pk_mul_f32 v[82:83], v[100:101], v[82:83]
	v_cndmask_b32_e64 v76, v72, v76, s[8:9]
	v_add_f32_e32 v79, v82, v83
	v_cndmask_b32_e64 v77, v73, v77, s[8:9]
	v_cndmask_b32_e64 v78, v74, v78, s[8:9]
	v_cndmask_b32_e64 v79, v75, v79, s[8:9]
; __device__ __forceinline__ float shx16(float v, int odd  ) { const unsigned x = __builtin_bit_cast(unsigned, v); auto r = __builtin_amdgcn_permlane16_swap(x, x, false, false); return __builtin_bit_cast(float, odd ? r[0] : r[1]); }
; __device__ __forceinline__ void st_bf4(bf16_t* p, const f32x4 v) { u32x2 w; w.x = cvt_pk_bf16(v[0], v[1]); w.y = cvt_pk_bf16(v[2], v[3]); *(u32x2*)p = w; }
;     __device__ __forceinline__ void operator()(const f32x4 (&acc)[2][2][4][2], const Unit& u, int wr, int wc, int fr, int fq) const {
;     ...
;                                 const int tix = row < cfg::MP ? (row & 2047) : 2048 + (row & 3);
;                                 const f32x4 cs = *(const f32x4*)(ropec + tix * 8 + 4 * n), sn = *(const f32x4*)(ropes + tix * 8 + 4 * n);
; #pragma unroll
;                                 for (int i = 0; i < 4; ++i) { const float p = shx16(v[i], fq & 1); const float rv = v[i] * cs[i] + (fq == 0 ? -p : p) * sn[i]; v[i] = fq < 2 ? rv : v[i]; }
;                             }
;                             if (pn < 4) st_bf4(Q + (size_t)row * 512 + (pn - 2) * 256 + tc, v);
;                             else { st_bf4((bj == 0 ? KB : VB) + (size_t)row * 128 + (tc & 127), v);
;                                 bool w = false; size_t o = 0;
;                                 if (row < cfg::MP) { const int t = row & 2047; if (t >= 1920) { w = true; o = (bj == 0 ? cfg::OFF_KP : cfg::OFF_VP) + ((size_t)(layer * 8 + (row >> 11)) * 128 + (t - 1920)) * 128 + (tc & 127); } }
;                                 else { const int rs = row - cfg::MP; w = true; o = (bj == 0 ? cfg::OFF_KS : cfg::OFF_VS) + ((size_t)(layer * 128 + (rs >> 2)) * 128 + 124 + (rs & 3)) * 128 + (tc & 127); }
;                                 if (w) *(f32x4*)(out + o) = v; }
	v_mov_b32_e32 v100, v76
	v_mov_b32_e32 v104, v77
	v_mov_b32_e32 v101, v78
	v_mov_b32_e32 v105, v79
	v_lshl_add_u64 v[82:83], v[164:165], 0, v[86:87]
	v_cvt_pk_bf16_f32 v98, v100, v104
	v_cvt_pk_bf16_f32 v99, v101, v105
	global_store_dwordx2 v[82:83], v[98:99], off
	s_and_saveexec_b64 s[78:79], s[20:21]
	s_xor_b64 s[78:79], exec, s[78:79]
	s_mov_b64 s[70:71], exec
	v_add_u32_e32 v82, s87, v102
	s_or_saveexec_b64 s[78:79], s[78:79]
	v_mov_b64_e32 v[98:99], v[160:161]
	s_xor_b64 exec, exec, s[78:79]
	s_and_saveexec_b64 vcc, s[18:19]
	v_readlane_b32 s80, v254, 37
	v_readlane_b32 s81, v254, 38
	s_add_i32 s46, s75, s80
	s_or_b64 s[80:81], s[70:71], exec
	s_or_b64 exec, exec, vcc
	s_andn2_b64 s[70:71], s[70:71], exec
	s_and_b64 s[80:81], s[80:81], exec
	v_mov_b32_e32 v82, s46
	s_or_b64 s[70:71], s[70:71], s[80:81]
	v_mov_b64_e32 v[98:99], v[94:95]
	v_readlane_b32 s86, v254, 63
	v_readlane_b32 s87, v255, 0
	s_or_b64 exec, exec, s[78:79]
	s_and_saveexec_b64 s[78:79], s[70:71]
	v_ashrrev_i32_e32 v83, 31, v82
	v_lshl_add_u64 v[94:95], v[98:99], 2, v[156:157]
	v_lshlrev_b64 v[82:83], 16, v[82:83]
	v_lshl_add_u64 v[82:83], v[94:95], 0, v[82:83]
	global_store_dwordx4 v[82:83], v[76:79], off offset:16
	s_or_b64 exec, exec, s[78:79]
	s_mov_b64 s[70:71], 0x1100000
	v_lshl_add_u64 v[76:77], v[92:93], 0, s[70:71]
	v_mov_b64_e32 v[74:75], v[70:71]
	v_mov_b64_e32 v[72:73], v[68:69]
	v_mov_b32_e32 v92, v68
	v_mov_b32_e32 v94, v69
	v_mov_b32_e32 v93, v70
	v_mov_b32_e32 v95, v71
	v_lshl_add_u64 v[78:79], v[158:159], 0, v[86:87]
	v_cvt_pk_bf16_f32 v82, v92, v94
	v_cvt_pk_bf16_f32 v83, v93, v95
	global_store_dwordx2 v[78:79], v[82:83], off
	s_and_saveexec_b64 s[78:79], s[20:21]
	s_xor_b64 s[78:79], exec, s[78:79]
	s_mov_b64 s[70:71], exec
	v_add_u32_e32 v78, s87, v102
	s_or_saveexec_b64 s[78:79], s[78:79]
	v_mov_b64_e32 v[82:83], v[162:163]
	s_xor_b64 exec, exec, s[78:79]
	s_and_saveexec_b64 vcc, s[18:19]
	v_readlane_b32 s80, v254, 37
	v_readlane_b32 s81, v254, 38
	s_add_i32 s46, s75, s80
	s_or_b64 s[80:81], s[70:71], exec
	s_or_b64 exec, exec, vcc
	s_andn2_b64 s[70:71], s[70:71], exec
	s_and_b64 s[80:81], s[80:81], exec
	v_mov_b32_e32 v78, s46
	s_or_b64 s[70:71], s[70:71], s[80:81]
	v_mov_b64_e32 v[82:83], v[76:77]
	v_readlane_b32 s86, v254, 63
	v_readlane_b32 s87, v255, 0
	s_or_b64 exec, exec, s[78:79]
	s_and_saveexec_b64 s[78:79], s[70:71]
	v_ashrrev_i32_e32 v79, 31, v78
	v_lshl_add_u64 v[82:83], v[82:83], 2, v[156:157]
	v_lshlrev_b64 v[78:79], 16, v[78:79]
	v_lshl_add_u64 v[78:79], v[82:83], 0, v[78:79]
	global_store_dwordx4 v[78:79], v[72:75], off
	s_or_b64 exec, exec, s[78:79]
	v_mov_b64_e32 v[70:71], v[66:67]
	v_mov_b64_e32 v[68:69], v[64:65]
	v_mov_b32_e32 v78, v64
	v_mov_b32_e32 v82, v65
	v_mov_b32_e32 v79, v66
	v_mov_b32_e32 v83, v67
	s_andn2_b64 vcc, exec, s[96:97]
	v_lshl_add_u64 v[72:73], v[166:167], 0, v[86:87]
	v_cvt_pk_bf16_f32 v74, v78, v82
	v_cvt_pk_bf16_f32 v75, v79, v83
	global_store_dwordx2 v[72:73], v[74:75], off
	s_and_saveexec_b64 s[78:79], s[20:21]
	s_xor_b64 s[20:21], exec, s[78:79]
	s_mov_b64 s[70:71], exec
	v_add_u32_e32 v72, s87, v102
	s_or_saveexec_b64 s[20:21], s[20:21]
	v_mov_b64_e32 v[74:75], v[162:163]
	s_xor_b64 exec, exec, s[20:21]
	s_and_saveexec_b64 s[80:81], s[18:19]
	v_readlane_b32 s18, v254, 37
	s_add_i32 s46, s75, s18
	s_or_b64 s[78:79], s[70:71], exec
	v_readlane_b32 s19, v254, 38
	s_or_b64 exec, exec, s[80:81]
	s_andn2_b64 s[18:19], s[70:71], exec
	s_and_b64 s[70:71], s[78:79], exec
	v_mov_b32_e32 v72, s46
	s_or_b64 s[70:71], s[18:19], s[70:71]
	v_mov_b64_e32 v[74:75], v[76:77]
	s_or_b64 exec, exec, s[20:21]
	s_and_saveexec_b64 s[18:19], s[70:71]
	v_ashrrev_i32_e32 v73, 31, v72
	v_lshl_add_u64 v[74:75], v[74:75], 2, v[156:157]
	v_lshlrev_b64 v[72:73], 16, v[72:73]
	v_lshl_add_u64 v[72:73], v[74:75], 0, v[72:73]
	global_store_dwordx4 v[72:73], v[68:71], off offset:16
	s_or_b64 exec, exec, s[18:19]
	s_add_i32 s46, s53, 0x80
	v_or_b32_e32 v68, s46, v143
	v_mad_i64_i32 v[76:77], s[18:19], v68, s61, 0
	s_movk_i32 s18, 0x3fff
	s_nop 0
	v_cmp_lt_i32_e64 s[20:21], s18, v68
	v_mov_b32_e32 v64, 0x7cf
	s_movk_i32 s18, 0x4000
	v_bitop3_b32 v64, s46, v64, v143 bitop3:0xc8
	v_cmp_gt_i32_e32 vcc, s18, v68
	v_add_u32_e32 v96, 0xfffff880, v64
	v_ashrrev_i32_e32 v69, 31, v68
	v_cndmask_b32_e32 v65, v151, v64, vcc
	v_lshlrev_b32_e32 v87, 3, v65
	v_add_u32_e32 v65, 0xffffc000, v68
	s_movk_i32 s18, 0x77f
	v_lshlrev_b64 v[78:79], 7, v[96:97]
	s_mov_b64 s[70:71], 0x1080000
	s_ashr_i32 s53, s46, 11
	v_lshlrev_b64 v[72:73], 8, v[68:69]
	v_lshrrev_b32_e32 v86, 2, v65
	v_cmp_lt_u32_e64 s[18:19], s18, v64
	v_lshl_add_u64 v[80:81], v[78:79], 0, s[70:71]
	s_mov_b32 s75, 0x400000
	v_lshlrev_b32_e32 v69, 2, v87
	global_load_dwordx4 v[234:237], v229, s[44:45]
	global_load_dwordx4 v[238:241], v229, s[4:5]
	global_load_dwordx4 v[242:245], v229, s[44:45] offset:16
	global_load_dwordx4 v[246:249], v229, s[4:5] offset:16
	v_mov_b32_e32 v69, v60
	v_mov_b32_e32 v88, v60
	s_nop 1
	v_permlane16_swap_b32_e32 v69, v88
	v_cndmask_b32_e64 v69, v69, v88, s[6:7]
	v_cndmask_b32_e64 v89, v69, -v69, s[10:11]
	v_mov_b32_e32 v69, v61
	v_mov_b32_e32 v90, v60
	s_waitcnt vmcnt(8)
; __device__ __forceinline__ float shx16(float v, int odd  ) { const unsigned x = __builtin_bit_cast(unsigned, v); auto r = __builtin_amdgcn_permlane16_swap(x, x, false, false); return __builtin_bit_cast(float, odd ? r[0] : r[1]); }
; __device__ __forceinline__ void st_bf4(bf16_t* p, const f32x4 v) { u32x2 w; w.x = cvt_pk_bf16(v[0], v[1]); w.y = cvt_pk_bf16(v[2], v[3]); *(u32x2*)p = w; }
;     __device__ __forceinline__ void operator()(const f32x4 (&acc)[2][2][4][2], const Unit& u, int wr, int wc, int fr, int fq) const {
;     ...
;                                 const int tix = row < cfg::MP ? (row & 2047) : 2048 + (row & 3);
;                                 const f32x4 cs = *(const f32x4*)(ropec + tix * 8 + 4 * n), sn = *(const f32x4*)(ropes + tix * 8 + 4 * n);
; #pragma unroll
;                                 for (int i = 0; i < 4; ++i) { const float p = shx16(v[i], fq & 1); const float rv = v[i] * cs[i] + (fq == 0 ? -p : p) * sn[i]; v[i] = fq < 2 ? rv : v[i]; }
;                             }
;                             if (pn < 4) st_bf4(Q + (size_t)row * 512 + (pn - 2) * 256 + tc, v);
;                             else { st_bf4((bj == 0 ? KB : VB) + (size_t)row * 128 + (tc & 127), v);
;                                 bool w = false; size_t o = 0;
;                                 if (row < cfg::MP) { const int t = row & 2047; if (t >= 1920) { w = true; o = (bj == 0 ? cfg::OFF_KP : cfg::OFF_VP) + ((size_t)(layer * 8 + (row >> 11)) * 128 + (t - 1920)) * 128 + (tc & 127); } }
;                                 else { const int rs = row - cfg::MP; w = true; o = (bj == 0 ? cfg::OFF_KS : cfg::OFF_VS) + ((size_t)(layer * 128 + (rs >> 2)) * 128 + 124 + (rs & 3)) * 128 + (tc & 127); }
;                                 if (w) *(f32x4*)(out + o) = v; }
	v_mov_b32_e32 v88, v208
	v_mov_b32_e32 v91, v212
	v_mov_b32_e32 v82, v61
	s_nop 1
	v_permlane16_swap_b32_e32 v69, v82
	v_pk_mul_f32 v[88:89], v[90:91], v[88:89]
	v_cndmask_b32_e64 v69, v69, v82, s[6:7]
	v_add_f32_e32 v64, v88, v89
	v_cndmask_b32_e64 v89, v69, -v69, s[10:11]
	v_mov_b32_e32 v82, v61
	v_mov_b32_e32 v88, v209
	v_mov_b32_e32 v83, v213
	v_pk_mul_f32 v[82:83], v[82:83], v[88:89]
	v_mov_b32_e32 v69, v62
	v_add_f32_e32 v65, v82, v83
	v_mov_b32_e32 v82, v62
	s_nop 1
	v_permlane16_swap_b32_e32 v69, v82
	v_cndmask_b32_e64 v69, v69, v82, s[6:7]
	v_cndmask_b32_e64 v83, v69, -v69, s[10:11]
	v_mov_b32_e32 v88, v62
	v_mov_b32_e32 v89, v214
	v_mov_b32_e32 v82, v210
	v_pk_mul_f32 v[82:83], v[88:89], v[82:83]
	v_mov_b32_e32 v69, v63
	v_add_f32_e32 v66, v82, v83
	v_mov_b32_e32 v82, v63
	s_nop 1
	v_permlane16_swap_b32_e32 v69, v82
	v_cndmask_b32_e64 v69, v69, v82, s[6:7]
	v_cndmask_b32_e64 v83, v69, -v69, s[10:11]
	v_mov_b32_e32 v84, v63
	v_mov_b32_e32 v82, v211
	v_mov_b32_e32 v85, v215
	v_pk_mul_f32 v[82:83], v[84:85], v[82:83]
	v_cndmask_b32_e64 v64, v60, v64, s[8:9]
	v_add_f32_e32 v67, v82, v83
	v_cndmask_b32_e64 v65, v61, v65, s[8:9]
	v_cndmask_b32_e64 v66, v62, v66, s[8:9]
	v_cndmask_b32_e64 v67, v63, v67, s[8:9]
	v_mov_b32_e32 v69, v64
	v_mov_b32_e32 v89, v65
	v_mov_b32_e32 v88, v66
	v_mov_b32_e32 v90, v67
	v_lshl_add_u64 v[82:83], v[154:155], 0, v[72:73]
	v_cvt_pk_bf16_f32 v84, v69, v89
	v_cvt_pk_bf16_f32 v85, v88, v90
	global_store_dwordx2 v[82:83], v[84:85], off
	s_and_saveexec_b64 s[78:79], s[20:21]
	s_xor_b64 s[78:79], exec, s[78:79]
	s_mov_b64 s[70:71], exec
	v_add_u32_e32 v82, s87, v86
	s_or_saveexec_b64 s[78:79], s[78:79]
	v_mov_b64_e32 v[84:85], v[160:161]
	s_xor_b64 exec, exec, s[78:79]
	s_and_saveexec_b64 vcc, s[18:19]
	v_readlane_b32 s80, v254, 37
	v_readlane_b32 s81, v254, 38
	s_add_i32 s46, s53, s80
	s_or_b64 s[80:81], s[70:71], exec
	s_or_b64 exec, exec, vcc
	s_andn2_b64 s[70:71], s[70:71], exec
	s_and_b64 s[80:81], s[80:81], exec
	v_mov_b32_e32 v82, s46
	s_or_b64 s[70:71], s[70:71], s[80:81]
	v_mov_b64_e32 v[84:85], v[80:81]
	v_readlane_b32 s86, v254, 63
	v_readlane_b32 s87, v255, 0
	s_or_b64 exec, exec, s[78:79]
	s_and_saveexec_b64 s[78:79], s[70:71]
	v_ashrrev_i32_e32 v83, 31, v82
	v_lshl_add_u64 v[84:85], v[84:85], 2, v[156:157]
	v_lshlrev_b64 v[82:83], 16, v[82:83]
	v_lshl_add_u64 v[82:83], v[84:85], 0, v[82:83]
	global_store_dwordx4 v[82:83], v[64:67], off
	s_or_b64 exec, exec, s[78:79]
	s_nop 0
	v_lshlrev_b32_e32 v66, 2, v87
	v_mov_b32_e32 v66, v56
	v_mov_b32_e32 v67, v56
	s_nop 1
	v_permlane16_swap_b32_e32 v66, v67
	v_cndmask_b32_e64 v66, v66, v67, s[6:7]
	v_cndmask_b32_e64 v67, v66, -v66, s[10:11]
	v_mov_b32_e32 v88, v56
	v_mov_b32_e32 v66, v216
	v_mov_b32_e32 v89, v220
	v_pk_mul_f32 v[66:67], v[88:89], v[66:67]
	v_mov_b32_e32 v82, v57
	v_add_f32_e32 v60, v66, v67
	v_mov_b32_e32 v66, v57
	v_mov_b32_e32 v67, v57
	s_nop 1
	v_permlane16_swap_b32_e32 v66, v67
	v_cndmask_b32_e64 v66, v66, v67, s[6:7]
	v_cndmask_b32_e64 v67, v66, -v66, s[10:11]
	v_mov_b32_e32 v66, v217
	v_mov_b32_e32 v83, v221
	v_pk_mul_f32 v[66:67], v[82:83], v[66:67]
	v_mov_b32_e32 v82, v58
	v_add_f32_e32 v61, v66, v67
	v_mov_b32_e32 v66, v58
	v_mov_b32_e32 v67, v58
	s_nop 1
	v_permlane16_swap_b32_e32 v66, v67
	v_cndmask_b32_e64 v66, v66, v67, s[6:7]
	v_cndmask_b32_e64 v67, v66, -v66, s[10:11]
	v_mov_b32_e32 v83, v222
	v_mov_b32_e32 v66, v218
	v_pk_mul_f32 v[66:67], v[82:83], v[66:67]
	v_mov_b32_e32 v84, v59
	v_add_f32_e32 v62, v66, v67
	v_mov_b32_e32 v66, v59
	v_mov_b32_e32 v67, v59
	s_nop 1
	v_permlane16_swap_b32_e32 v66, v67
	v_cndmask_b32_e64 v66, v66, v67, s[6:7]
	v_cndmask_b32_e64 v67, v66, -v66, s[10:11]
	v_mov_b32_e32 v66, v219
	v_mov_b32_e32 v85, v223
	v_pk_mul_f32 v[66:67], v[84:85], v[66:67]
	v_cndmask_b32_e64 v60, v56, v60, s[8:9]
	v_add_f32_e32 v63, v66, v67
	v_cndmask_b32_e64 v61, v57, v61, s[8:9]
	v_cndmask_b32_e64 v62, v58, v62, s[8:9]
	v_cndmask_b32_e64 v63, v59, v63, s[8:9]
	v_mov_b32_e32 v69, v60
	v_mov_b32_e32 v85, v61
	v_mov_b32_e32 v84, v62
	v_mov_b32_e32 v88, v63
	v_lshl_add_u64 v[66:67], v[164:165], 0, v[72:73]
	v_cvt_pk_bf16_f32 v82, v69, v85
	v_cvt_pk_bf16_f32 v83, v84, v88
	global_store_dwordx2 v[66:67], v[82:83], off
	s_and_saveexec_b64 s[78:79], s[20:21]
	s_xor_b64 s[78:79], exec, s[78:79]
	s_mov_b64 s[70:71], exec
	v_add_u32_e32 v66, s87, v86
	s_or_saveexec_b64 s[78:79], s[78:79]
	v_mov_b64_e32 v[82:83], v[160:161]
	s_xor_b64 exec, exec, s[78:79]
	s_and_saveexec_b64 vcc, s[18:19]
	v_readlane_b32 s80, v254, 37
	v_readlane_b32 s81, v254, 38
	s_add_i32 s46, s53, s80
	s_or_b64 s[80:81], s[70:71], exec
	s_or_b64 exec, exec, vcc
	s_andn2_b64 s[70:71], s[70:71], exec
	s_and_b64 s[80:81], s[80:81], exec
	v_mov_b32_e32 v66, s46
	s_or_b64 s[70:71], s[70:71], s[80:81]
	v_mov_b64_e32 v[82:83], v[80:81]
	v_readlane_b32 s86, v254, 63
	v_readlane_b32 s87, v255, 0
	s_or_b64 exec, exec, s[78:79]
	s_and_saveexec_b64 s[78:79], s[70:71]
	v_ashrrev_i32_e32 v67, 31, v66
	v_lshl_add_u64 v[80:81], v[82:83], 2, v[156:157]
	v_lshlrev_b64 v[66:67], 16, v[66:67]
	v_lshl_add_u64 v[66:67], v[80:81], 0, v[66:67]
	global_store_dwordx4 v[66:67], v[60:63], off offset:16
	s_or_b64 exec, exec, s[78:79]
	s_mov_b64 s[70:71], 0x1100000
	v_lshl_add_u64 v[60:61], v[78:79], 0, s[70:71]
	v_mov_b64_e32 v[58:59], v[54:55]
	v_mov_b64_e32 v[56:57], v[52:53]
	v_mov_b32_e32 v69, v52
	v_mov_b32_e32 v79, v53
	v_mov_b32_e32 v78, v54
	v_mov_b32_e32 v80, v55
	v_lshl_add_u64 v[62:63], v[158:159], 0, v[72:73]
	v_cvt_pk_bf16_f32 v66, v69, v79
	v_cvt_pk_bf16_f32 v67, v78, v80
	global_store_dwordx2 v[62:63], v[66:67], off
	s_and_saveexec_b64 s[78:79], s[20:21]
; __device__ __forceinline__ float shx16(float v, int odd  ) { const unsigned x = __builtin_bit_cast(unsigned, v); auto r = __builtin_amdgcn_permlane16_swap(x, x, false, false); return __builtin_bit_cast(float, odd ? r[0] : r[1]); }
; __device__ __forceinline__ void st_bf4(bf16_t* p, const f32x4 v) { u32x2 w; w.x = cvt_pk_bf16(v[0], v[1]); w.y = cvt_pk_bf16(v[2], v[3]); *(u32x2*)p = w; }
;     __device__ __forceinline__ void operator()(const f32x4 (&acc)[2][2][4][2], const Unit& u, int wr, int wc, int fr, int fq) const {
;     ...
;                                 const int tix = row < cfg::MP ? (row & 2047) : 2048 + (row & 3);
;                                 const f32x4 cs = *(const f32x4*)(ropec + tix * 8 + 4 * n), sn = *(const f32x4*)(ropes + tix * 8 + 4 * n);
; #pragma unroll
;                                 for (int i = 0; i < 4; ++i) { const float p = shx16(v[i], fq & 1); const float rv = v[i] * cs[i] + (fq == 0 ? -p : p) * sn[i]; v[i] = fq < 2 ? rv : v[i]; }
;                             }
;                             if (pn < 4) st_bf4(Q + (size_t)row * 512 + (pn - 2) * 256 + tc, v);
;                             else { st_bf4((bj == 0 ? KB : VB) + (size_t)row * 128 + (tc & 127), v);
;                                 bool w = false; size_t o = 0;
;                                 if (row < cfg::MP) { const int t = row & 2047; if (t >= 1920) { w = true; o = (bj == 0 ? cfg::OFF_KP : cfg::OFF_VP) + ((size_t)(layer * 8 + (row >> 11)) * 128 + (t - 1920)) * 128 + (tc & 127); } }
;                                 else { const int rs = row - cfg::MP; w = true; o = (bj == 0 ? cfg::OFF_KS : cfg::OFF_VS) + ((size_t)(layer * 128 + (rs >> 2)) * 128 + 124 + (rs & 3)) * 128 + (tc & 127); }
;                                 if (w) *(f32x4*)(out + o) = v; }
	s_xor_b64 s[78:79], exec, s[78:79]
	s_mov_b64 s[70:71], exec
	v_add_u32_e32 v62, s87, v86
	s_or_saveexec_b64 s[78:79], s[78:79]
	v_mov_b64_e32 v[66:67], v[162:163]
	s_xor_b64 exec, exec, s[78:79]
	s_and_saveexec_b64 vcc, s[18:19]
	v_readlane_b32 s80, v254, 37
	v_readlane_b32 s81, v254, 38
	s_add_i32 s46, s53, s80
	s_or_b64 s[80:81], s[70:71], exec
	s_or_b64 exec, exec, vcc
	s_andn2_b64 s[70:71], s[70:71], exec
	s_and_b64 s[80:81], s[80:81], exec
	v_mov_b32_e32 v62, s46
	s_or_b64 s[70:71], s[70:71], s[80:81]
	v_mov_b64_e32 v[66:67], v[60:61]
	v_readlane_b32 s86, v254, 63
	v_readlane_b32 s87, v255, 0
	s_or_b64 exec, exec, s[78:79]
	s_and_saveexec_b64 s[78:79], s[70:71]
	v_ashrrev_i32_e32 v63, 31, v62
	v_lshl_add_u64 v[66:67], v[66:67], 2, v[156:157]
	v_lshlrev_b64 v[62:63], 16, v[62:63]
	v_lshl_add_u64 v[62:63], v[66:67], 0, v[62:63]
	global_store_dwordx4 v[62:63], v[56:59], off
	s_or_b64 exec, exec, s[78:79]
	v_mov_b64_e32 v[54:55], v[50:51]
	v_mov_b64_e32 v[52:53], v[48:49]
	v_mov_b32_e32 v62, v48
	v_mov_b32_e32 v66, v49
	v_mov_b32_e32 v63, v50
	v_mov_b32_e32 v67, v51
	s_andn2_b64 vcc, exec, s[96:97]
	v_lshl_add_u64 v[56:57], v[166:167], 0, v[72:73]
	v_cvt_pk_bf16_f32 v58, v62, v66
	v_cvt_pk_bf16_f32 v59, v63, v67
	global_store_dwordx2 v[56:57], v[58:59], off
	s_and_saveexec_b64 s[78:79], s[20:21]
	s_xor_b64 s[20:21], exec, s[78:79]
	s_mov_b64 s[70:71], exec
	v_add_u32_e32 v56, s87, v86
	s_or_saveexec_b64 s[20:21], s[20:21]
	v_mov_b64_e32 v[58:59], v[162:163]
	s_xor_b64 exec, exec, s[20:21]
	s_and_saveexec_b64 s[80:81], s[18:19]
	v_readlane_b32 s18, v254, 37
	s_add_i32 s46, s53, s18
	s_or_b64 s[78:79], s[70:71], exec
	v_readlane_b32 s19, v254, 38
	s_or_b64 exec, exec, s[80:81]
	s_andn2_b64 s[18:19], s[70:71], exec
	s_and_b64 s[70:71], s[78:79], exec
	v_mov_b32_e32 v56, s46
	s_or_b64 s[70:71], s[18:19], s[70:71]
	v_mov_b64_e32 v[58:59], v[60:61]
	s_or_b64 exec, exec, s[20:21]
	s_and_saveexec_b64 s[18:19], s[70:71]
	v_ashrrev_i32_e32 v57, 31, v56
	v_lshl_add_u64 v[58:59], v[58:59], 2, v[156:157]
	v_lshlrev_b64 v[56:57], 16, v[56:57]
	v_lshl_add_u64 v[56:57], v[58:59], 0, v[56:57]
	global_store_dwordx4 v[56:57], v[52:55], off offset:16
	s_or_b64 exec, exec, s[18:19]
	v_or_b32_e32 v48, 16, v68
	v_mad_i64_i32 v[58:59], s[18:19], v48, s61, 0
	s_movk_i32 s18, 0x3fff
	s_nop 0
	v_cmp_lt_i32_e64 s[20:21], s18, v48
	s_movk_i32 s18, 0x7df
	v_bitop3_b32 v50, v68, s18, 16 bitop3:0xc8
	s_movk_i32 s18, 0x4000
	v_cmp_gt_i32_e32 vcc, s18, v48
	v_add_u32_e32 v96, 0xfffff880, v50
	v_ashrrev_i32_e32 v49, 31, v48
	v_cndmask_b32_e32 v51, v151, v50, vcc
	v_lshlrev_b32_e32 v70, 3, v51
	v_add_u32_e32 v51, 0xffffc010, v68
	s_movk_i32 s18, 0x77f
	v_lshlrev_b64 v[60:61], 7, v[96:97]
	s_mov_b64 s[70:71], 0x1080000
	v_lshlrev_b64 v[54:55], 8, v[48:49]
	v_lshrrev_b32_e32 v69, 2, v51
	v_cmp_lt_u32_e64 s[18:19], s18, v50
	v_lshl_add_u64 v[62:63], v[60:61], 0, s[70:71]
	v_lshlrev_b32_e32 v64, 2, v70
	global_load_dwordx4 v[208:211], v230, s[44:45]
	global_load_dwordx4 v[212:215], v230, s[4:5]
	global_load_dwordx4 v[216:219], v230, s[44:45] offset:16
	global_load_dwordx4 v[220:223], v230, s[4:5] offset:16
	v_mov_b32_e32 v71, v44
	v_mov_b32_e32 v72, v44
	s_nop 1
	v_permlane16_swap_b32_e32 v71, v72
	v_cndmask_b32_e64 v71, v71, v72, s[6:7]
	v_cndmask_b32_e64 v73, v71, -v71, s[10:11]
	v_mov_b32_e32 v71, v45
	v_mov_b32_e32 v74, v44
	s_waitcnt vmcnt(8)
	v_mov_b32_e32 v72, v234
	v_mov_b32_e32 v75, v238
	v_mov_b32_e32 v64, v45
	s_nop 1
	v_permlane16_swap_b32_e32 v64, v71
	v_pk_mul_f32 v[72:73], v[74:75], v[72:73]
	v_cndmask_b32_e64 v64, v64, v71, s[6:7]
	v_add_f32_e32 v48, v72, v73
	v_cndmask_b32_e64 v73, v64, -v64, s[10:11]
	v_mov_b32_e32 v64, v45
	v_mov_b32_e32 v72, v235
	v_mov_b32_e32 v65, v239
	v_pk_mul_f32 v[64:65], v[64:65], v[72:73]
	v_mov_b32_e32 v72, v46
	v_add_f32_e32 v49, v64, v65
	v_mov_b32_e32 v64, v46
	v_mov_b32_e32 v65, v46
	s_nop 1
	v_permlane16_swap_b32_e32 v64, v65
	v_cndmask_b32_e64 v64, v64, v65, s[6:7]
	v_cndmask_b32_e64 v65, v64, -v64, s[10:11]
	v_mov_b32_e32 v73, v240
	v_mov_b32_e32 v64, v236
	v_pk_mul_f32 v[64:65], v[72:73], v[64:65]
	v_mov_b32_e32 v66, v47
	v_add_f32_e32 v50, v64, v65
	v_mov_b32_e32 v64, v47
	v_mov_b32_e32 v65, v47
	s_nop 1
	v_permlane16_swap_b32_e32 v64, v65
	v_cndmask_b32_e64 v64, v64, v65, s[6:7]
	v_cndmask_b32_e64 v65, v64, -v64, s[10:11]
	v_mov_b32_e32 v64, v237
	v_mov_b32_e32 v67, v241
	v_pk_mul_f32 v[64:65], v[66:67], v[64:65]
	v_cndmask_b32_e64 v48, v44, v48, s[8:9]
	v_add_f32_e32 v51, v64, v65
	v_cndmask_b32_e64 v49, v45, v49, s[8:9]
	v_cndmask_b32_e64 v50, v46, v50, s[8:9]
	v_cndmask_b32_e64 v51, v47, v51, s[8:9]
	v_mov_b32_e32 v71, v48
	v_mov_b32_e32 v73, v49
	v_mov_b32_e32 v72, v50
	v_mov_b32_e32 v74, v51
	v_lshl_add_u64 v[64:65], v[154:155], 0, v[54:55]
	v_cvt_pk_bf16_f32 v66, v71, v73
	v_cvt_pk_bf16_f32 v67, v72, v74
	global_store_dwordx2 v[64:65], v[66:67], off
	s_and_saveexec_b64 s[78:79], s[20:21]
	s_xor_b64 s[78:79], exec, s[78:79]
	s_mov_b64 s[70:71], exec
	v_add_u32_e32 v64, s87, v69
	s_or_saveexec_b64 s[78:79], s[78:79]
	v_mov_b64_e32 v[66:67], v[160:161]
	s_xor_b64 exec, exec, s[78:79]
	s_and_saveexec_b64 vcc, s[18:19]
	v_readlane_b32 s80, v254, 37
	v_readlane_b32 s81, v254, 38
	s_add_i32 s46, s53, s80
	s_or_b64 s[80:81], s[70:71], exec
	s_or_b64 exec, exec, vcc
	s_andn2_b64 s[70:71], s[70:71], exec
	s_and_b64 s[80:81], s[80:81], exec
	v_mov_b32_e32 v64, s46
	s_or_b64 s[70:71], s[70:71], s[80:81]
	v_mov_b64_e32 v[66:67], v[62:63]
	v_readlane_b32 s86, v254, 63
	v_readlane_b32 s87, v255, 0
	s_or_b64 exec, exec, s[78:79]
	s_and_saveexec_b64 s[78:79], s[70:71]
	v_ashrrev_i32_e32 v65, 31, v64
	v_lshl_add_u64 v[66:67], v[66:67], 2, v[156:157]
; __device__ __forceinline__ float shx16(float v, int odd  ) { const unsigned x = __builtin_bit_cast(unsigned, v); auto r = __builtin_amdgcn_permlane16_swap(x, x, false, false); return __builtin_bit_cast(float, odd ? r[0] : r[1]); }
; __device__ __forceinline__ void st_bf4(bf16_t* p, const f32x4 v) { u32x2 w; w.x = cvt_pk_bf16(v[0], v[1]); w.y = cvt_pk_bf16(v[2], v[3]); *(u32x2*)p = w; }
;     __device__ __forceinline__ void operator()(const f32x4 (&acc)[2][2][4][2], const Unit& u, int wr, int wc, int fr, int fq) const {
;     ...
;                                 const int tix = row < cfg::MP ? (row & 2047) : 2048 + (row & 3);
;                                 const f32x4 cs = *(const f32x4*)(ropec + tix * 8 + 4 * n), sn = *(const f32x4*)(ropes + tix * 8 + 4 * n);
; #pragma unroll
;                                 for (int i = 0; i < 4; ++i) { const float p = shx16(v[i], fq & 1); const float rv = v[i] * cs[i] + (fq == 0 ? -p : p) * sn[i]; v[i] = fq < 2 ? rv : v[i]; }
;                             }
;                             if (pn < 4) st_bf4(Q + (size_t)row * 512 + (pn - 2) * 256 + tc, v);
;                             else { st_bf4((bj == 0 ? KB : VB) + (size_t)row * 128 + (tc & 127), v);
;                                 bool w = false; size_t o = 0;
;                                 if (row < cfg::MP) { const int t = row & 2047; if (t >= 1920) { w = true; o = (bj == 0 ? cfg::OFF_KP : cfg::OFF_VP) + ((size_t)(layer * 8 + (row >> 11)) * 128 + (t - 1920)) * 128 + (tc & 127); } }
;                                 else { const int rs = row - cfg::MP; w = true; o = (bj == 0 ? cfg::OFF_KS : cfg::OFF_VS) + ((size_t)(layer * 128 + (rs >> 2)) * 128 + 124 + (rs & 3)) * 128 + (tc & 127); }
;                                 if (w) *(f32x4*)(out + o) = v; }
	v_lshlrev_b64 v[64:65], 16, v[64:65]
	v_lshl_add_u64 v[64:65], v[66:67], 0, v[64:65]
	global_store_dwordx4 v[64:65], v[48:51], off
	s_or_b64 exec, exec, s[78:79]
	s_nop 0
	v_lshlrev_b32_e32 v50, 2, v70
	v_mov_b32_e32 v50, v40
	v_mov_b32_e32 v51, v40
	s_nop 1
	v_permlane16_swap_b32_e32 v50, v51
	v_cndmask_b32_e64 v50, v50, v51, s[6:7]
	v_cndmask_b32_e64 v51, v50, -v50, s[10:11]
	v_mov_b32_e32 v72, v40
	v_mov_b32_e32 v50, v242
	v_mov_b32_e32 v73, v246
	v_pk_mul_f32 v[50:51], v[72:73], v[50:51]
	v_mov_b32_e32 v64, v41
	v_add_f32_e32 v44, v50, v51
	v_mov_b32_e32 v50, v41
	v_mov_b32_e32 v51, v41
	s_nop 1
	v_permlane16_swap_b32_e32 v50, v51
	v_cndmask_b32_e64 v50, v50, v51, s[6:7]
	v_cndmask_b32_e64 v51, v50, -v50, s[10:11]
	v_mov_b32_e32 v50, v243
	v_mov_b32_e32 v65, v247
	v_pk_mul_f32 v[50:51], v[64:65], v[50:51]
	v_mov_b32_e32 v64, v42
	v_add_f32_e32 v45, v50, v51
	v_mov_b32_e32 v50, v42
	v_mov_b32_e32 v51, v42
	s_nop 1
	v_permlane16_swap_b32_e32 v50, v51
	v_cndmask_b32_e64 v50, v50, v51, s[6:7]
	v_cndmask_b32_e64 v51, v50, -v50, s[10:11]
	v_mov_b32_e32 v65, v248
	v_mov_b32_e32 v50, v244
	v_pk_mul_f32 v[50:51], v[64:65], v[50:51]
	v_mov_b32_e32 v66, v43
	v_add_f32_e32 v46, v50, v51
	v_mov_b32_e32 v50, v43
	v_mov_b32_e32 v51, v43
	s_nop 1
	v_permlane16_swap_b32_e32 v50, v51
	v_cndmask_b32_e64 v50, v50, v51, s[6:7]
	v_cndmask_b32_e64 v51, v50, -v50, s[10:11]
	v_mov_b32_e32 v50, v245
	v_mov_b32_e32 v67, v249
	v_pk_mul_f32 v[50:51], v[66:67], v[50:51]
	v_cndmask_b32_e64 v44, v40, v44, s[8:9]
	v_add_f32_e32 v47, v50, v51
	v_cndmask_b32_e64 v45, v41, v45, s[8:9]
	v_cndmask_b32_e64 v46, v42, v46, s[8:9]
	v_cndmask_b32_e64 v47, v43, v47, s[8:9]
	v_mov_b32_e32 v66, v44
	v_mov_b32_e32 v71, v45
	v_mov_b32_e32 v67, v46
	v_mov_b32_e32 v72, v47
	v_lshl_add_u64 v[50:51], v[164:165], 0, v[54:55]
	v_cvt_pk_bf16_f32 v64, v66, v71
	v_cvt_pk_bf16_f32 v65, v67, v72
	global_store_dwordx2 v[50:51], v[64:65], off
	s_and_saveexec_b64 s[78:79], s[20:21]
	s_xor_b64 s[78:79], exec, s[78:79]
	s_mov_b64 s[70:71], exec
	v_add_u32_e32 v50, s87, v69
	s_or_saveexec_b64 s[78:79], s[78:79]
	v_mov_b64_e32 v[64:65], v[160:161]
	s_xor_b64 exec, exec, s[78:79]
	s_and_saveexec_b64 vcc, s[18:19]
	v_readlane_b32 s80, v254, 37
	v_readlane_b32 s81, v254, 38
	s_add_i32 s46, s53, s80
	s_or_b64 s[80:81], s[70:71], exec
	s_or_b64 exec, exec, vcc
	s_andn2_b64 s[70:71], s[70:71], exec
	s_and_b64 s[80:81], s[80:81], exec
	v_mov_b32_e32 v50, s46
	s_or_b64 s[70:71], s[70:71], s[80:81]
	v_mov_b64_e32 v[64:65], v[62:63]
	v_readlane_b32 s86, v254, 63
	v_readlane_b32 s87, v255, 0
	s_or_b64 exec, exec, s[78:79]
	s_and_saveexec_b64 s[78:79], s[70:71]
	v_ashrrev_i32_e32 v51, 31, v50
	v_lshl_add_u64 v[62:63], v[64:65], 2, v[156:157]
	v_lshlrev_b64 v[50:51], 16, v[50:51]
	v_lshl_add_u64 v[50:51], v[62:63], 0, v[50:51]
	global_store_dwordx4 v[50:51], v[44:47], off offset:16
	s_or_b64 exec, exec, s[78:79]
	s_mov_b64 s[70:71], 0x1100000
	v_lshl_add_u64 v[44:45], v[60:61], 0, s[70:71]
	v_mov_b64_e32 v[42:43], v[38:39]
	v_mov_b64_e32 v[40:41], v[36:37]
	v_mov_b32_e32 v60, v36
	v_mov_b32_e32 v62, v37
	v_mov_b32_e32 v61, v38
	v_mov_b32_e32 v63, v39
	v_lshl_add_u64 v[46:47], v[158:159], 0, v[54:55]
	v_cvt_pk_bf16_f32 v50, v60, v62
	v_cvt_pk_bf16_f32 v51, v61, v63
	global_store_dwordx2 v[46:47], v[50:51], off
	s_and_saveexec_b64 s[78:79], s[20:21]
	s_xor_b64 s[78:79], exec, s[78:79]
	s_mov_b64 s[70:71], exec
	v_add_u32_e32 v46, s87, v69
	s_or_saveexec_b64 s[78:79], s[78:79]
	v_mov_b64_e32 v[50:51], v[162:163]
	s_xor_b64 exec, exec, s[78:79]
	s_and_saveexec_b64 vcc, s[18:19]
	v_readlane_b32 s80, v254, 37
	v_readlane_b32 s81, v254, 38
	s_add_i32 s46, s53, s80
	s_or_b64 s[80:81], s[70:71], exec
	s_or_b64 exec, exec, vcc
	s_andn2_b64 s[70:71], s[70:71], exec
	s_and_b64 s[80:81], s[80:81], exec
	v_mov_b32_e32 v46, s46
	s_or_b64 s[70:71], s[70:71], s[80:81]
	v_mov_b64_e32 v[50:51], v[44:45]
	v_readlane_b32 s86, v254, 63
	v_readlane_b32 s87, v255, 0
	s_or_b64 exec, exec, s[78:79]
	s_and_saveexec_b64 s[78:79], s[70:71]
	v_ashrrev_i32_e32 v47, 31, v46
	v_lshl_add_u64 v[50:51], v[50:51], 2, v[156:157]
	v_lshlrev_b64 v[46:47], 16, v[46:47]
	v_lshl_add_u64 v[46:47], v[50:51], 0, v[46:47]
	global_store_dwordx4 v[46:47], v[40:43], off
	s_or_b64 exec, exec, s[78:79]
	v_mov_b64_e32 v[38:39], v[34:35]
	v_mov_b64_e32 v[36:37], v[32:33]
	v_mov_b32_e32 v46, v32
	v_mov_b32_e32 v50, v33
	v_mov_b32_e32 v47, v34
	v_mov_b32_e32 v51, v35
	s_andn2_b64 vcc, exec, s[96:97]
	v_lshl_add_u64 v[40:41], v[166:167], 0, v[54:55]
	v_cvt_pk_bf16_f32 v42, v46, v50
	v_cvt_pk_bf16_f32 v43, v47, v51
	global_store_dwordx2 v[40:41], v[42:43], off
	s_and_saveexec_b64 s[78:79], s[20:21]
	s_xor_b64 s[20:21], exec, s[78:79]
	s_mov_b64 s[70:71], exec
	v_add_u32_e32 v40, s87, v69
	s_or_saveexec_b64 s[20:21], s[20:21]
	v_mov_b64_e32 v[42:43], v[162:163]
	s_xor_b64 exec, exec, s[20:21]
	s_and_saveexec_b64 s[80:81], s[18:19]
	v_readlane_b32 s18, v254, 37
	s_add_i32 s46, s53, s18
	s_or_b64 s[78:79], s[70:71], exec
	v_readlane_b32 s19, v254, 38
	s_or_b64 exec, exec, s[80:81]
	s_andn2_b64 s[18:19], s[70:71], exec
	s_and_b64 s[70:71], s[78:79], exec
	v_mov_b32_e32 v40, s46
	s_or_b64 s[70:71], s[18:19], s[70:71]
	v_mov_b64_e32 v[42:43], v[44:45]
	s_or_b64 exec, exec, s[20:21]
	s_and_saveexec_b64 s[18:19], s[70:71]
	v_ashrrev_i32_e32 v41, 31, v40
	v_lshl_add_u64 v[42:43], v[42:43], 2, v[156:157]
	v_lshlrev_b64 v[40:41], 16, v[40:41]
	v_lshl_add_u64 v[40:41], v[42:43], 0, v[40:41]
	global_store_dwordx4 v[40:41], v[36:39], off offset:16
	s_or_b64 exec, exec, s[18:19]
	v_or_b32_e32 v32, 32, v68
	v_mad_i64_i32 v[42:43], s[18:19], v32, s61, 0
	s_movk_i32 s18, 0x3fff
	s_nop 0
	v_cmp_lt_i32_e64 s[20:21], s18, v32
	s_movk_i32 s18, 0x7ef
	v_bitop3_b32 v34, v68, s18, 32 bitop3:0xc8
	s_movk_i32 s18, 0x4000
	v_cmp_gt_i32_e32 vcc, s18, v32
	v_add_u32_e32 v96, 0xfffff880, v34
	v_ashrrev_i32_e32 v33, 31, v32
	v_cndmask_b32_e32 v35, v151, v34, vcc
	v_lshlrev_b32_e32 v53, 3, v35
	v_add_u32_e32 v35, 0xffffc020, v68
	s_movk_i32 s18, 0x77f
	v_lshlrev_b64 v[44:45], 7, v[96:97]
	s_mov_b64 s[70:71], 0x1080000
	v_lshlrev_b64 v[38:39], 8, v[32:33]
	v_lshrrev_b32_e32 v52, 2, v35
	v_cmp_lt_u32_e64 s[18:19], s18, v34
	v_lshl_add_u64 v[46:47], v[44:45], 0, s[70:71]
	v_lshlrev_b32_e32 v48, 2, v53
	global_load_dwordx4 v[234:237], v231, s[44:45]
	global_load_dwordx4 v[238:241], v231, s[4:5]
	global_load_dwordx4 v[242:245], v231, s[44:45] offset:16
	global_load_dwordx4 v[246:249], v231, s[4:5] offset:16
	v_mov_b32_e32 v54, v28
	v_mov_b32_e32 v55, v28
	s_nop 1
	v_permlane16_swap_b32_e32 v54, v55
	v_cndmask_b32_e64 v54, v54, v55, s[6:7]
	v_cndmask_b32_e64 v55, v54, -v54, s[10:11]
	v_mov_b32_e32 v56, v28
	s_waitcnt vmcnt(8)
; __device__ __forceinline__ float shx16(float v, int odd  ) { const unsigned x = __builtin_bit_cast(unsigned, v); auto r = __builtin_amdgcn_permlane16_swap(x, x, false, false); return __builtin_bit_cast(float, odd ? r[0] : r[1]); }
; __device__ __forceinline__ void st_bf4(bf16_t* p, const f32x4 v) { u32x2 w; w.x = cvt_pk_bf16(v[0], v[1]); w.y = cvt_pk_bf16(v[2], v[3]); *(u32x2*)p = w; }
;     __device__ __forceinline__ void operator()(const f32x4 (&acc)[2][2][4][2], const Unit& u, int wr, int wc, int fr, int fq) const {
;     ...
;                     for (int n = 0; n < 2; ++n) { const int tc = bj * 128 + wc * 32 + 8 * fq + 4 * n; f32x4 v = acc[ai][bj][m][n];
;                         if (pn < 2) { *(f32x4*)(XA + (size_t)row * 512 + pn * 256 + tc) = v; }
;                         else if (pn <= 4) {
;                             const bool isv = (pn == 4 && bj == 1);
;                             if (!isv && (wc & 1) == 0) {
;                                 const int tix = row < cfg::MP ? (row & 2047) : 2048 + (row & 3);
;                                 const f32x4 cs = *(const f32x4*)(ropec + tix * 8 + 4 * n), sn = *(const f32x4*)(ropes + tix * 8 + 4 * n);
; #pragma unroll
;                                 for (int i = 0; i < 4; ++i) { const float p = shx16(v[i], fq & 1); const float rv = v[i] * cs[i] + (fq == 0 ? -p : p) * sn[i]; v[i] = fq < 2 ? rv : v[i]; }
;                             }
;                             if (pn < 4) st_bf4(Q + (size_t)row * 512 + (pn - 2) * 256 + tc, v);
;                             else { st_bf4((bj == 0 ? KB : VB) + (size_t)row * 128 + (tc & 127), v);
;                                 bool w = false; size_t o = 0;
;                                 if (row < cfg::MP) { const int t = row & 2047; if (t >= 1920) { w = true; o = (bj == 0 ? cfg::OFF_KP : cfg::OFF_VP) + ((size_t)(layer * 8 + (row >> 11)) * 128 + (t - 1920)) * 128 + (tc & 127); } }
;                                 else { const int rs = row - cfg::MP; w = true; o = (bj == 0 ? cfg::OFF_KS : cfg::OFF_VS) + ((size_t)(layer * 128 + (rs >> 2)) * 128 + 124 + (rs & 3)) * 128 + (tc & 127); }
;                                 if (w) *(f32x4*)(out + o) = v; }
	v_mov_b32_e32 v54, v208
	v_mov_b32_e32 v57, v212
	v_pk_mul_f32 v[54:55], v[56:57], v[54:55]
	v_mov_b32_e32 v48, v29
	v_add_f32_e32 v32, v54, v55
	v_mov_b32_e32 v54, v29
	s_nop 1
	v_permlane16_swap_b32_e32 v48, v54
	v_cndmask_b32_e64 v48, v48, v54, s[6:7]
	v_cndmask_b32_e64 v55, v48, -v48, s[10:11]
	v_mov_b32_e32 v48, v29
	v_mov_b32_e32 v54, v209
	v_mov_b32_e32 v49, v213
	v_pk_mul_f32 v[48:49], v[48:49], v[54:55]
	v_mov_b32_e32 v54, v30
	v_add_f32_e32 v33, v48, v49
	v_mov_b32_e32 v48, v30
	v_mov_b32_e32 v49, v30
	s_nop 1
	v_permlane16_swap_b32_e32 v48, v49
	v_cndmask_b32_e64 v48, v48, v49, s[6:7]
	v_cndmask_b32_e64 v49, v48, -v48, s[10:11]
	v_mov_b32_e32 v55, v214
	v_mov_b32_e32 v48, v210
	v_pk_mul_f32 v[48:49], v[54:55], v[48:49]
	v_mov_b32_e32 v50, v31
	v_add_f32_e32 v34, v48, v49
	v_mov_b32_e32 v48, v31
	v_mov_b32_e32 v49, v31
	s_nop 1
	v_permlane16_swap_b32_e32 v48, v49
	v_cndmask_b32_e64 v48, v48, v49, s[6:7]
	v_cndmask_b32_e64 v49, v48, -v48, s[10:11]
	v_mov_b32_e32 v48, v211
	v_mov_b32_e32 v51, v215
	v_pk_mul_f32 v[48:49], v[50:51], v[48:49]
	v_cndmask_b32_e64 v32, v28, v32, s[8:9]
	v_add_f32_e32 v35, v48, v49
	v_cndmask_b32_e64 v33, v29, v33, s[8:9]
	v_cndmask_b32_e64 v34, v30, v34, s[8:9]
	v_cndmask_b32_e64 v35, v31, v35, s[8:9]
	v_mov_b32_e32 v54, v32
	v_mov_b32_e32 v56, v33
	v_mov_b32_e32 v55, v34
	v_mov_b32_e32 v57, v35
	v_lshl_add_u64 v[48:49], v[154:155], 0, v[38:39]
	v_cvt_pk_bf16_f32 v50, v54, v56
	v_cvt_pk_bf16_f32 v51, v55, v57
	global_store_dwordx2 v[48:49], v[50:51], off
	s_and_saveexec_b64 s[78:79], s[20:21]
	s_xor_b64 s[78:79], exec, s[78:79]
	s_mov_b64 s[70:71], exec
	v_add_u32_e32 v48, s87, v52
	s_or_saveexec_b64 s[78:79], s[78:79]
	v_mov_b64_e32 v[50:51], v[160:161]
	s_xor_b64 exec, exec, s[78:79]
	s_and_saveexec_b64 vcc, s[18:19]
	v_readlane_b32 s80, v254, 37
	v_readlane_b32 s81, v254, 38
	s_add_i32 s46, s53, s80
	s_or_b64 s[80:81], s[70:71], exec
	s_or_b64 exec, exec, vcc
	s_andn2_b64 s[70:71], s[70:71], exec
	s_and_b64 s[80:81], s[80:81], exec
	v_mov_b32_e32 v48, s46
	s_or_b64 s[70:71], s[70:71], s[80:81]
	v_mov_b64_e32 v[50:51], v[46:47]
	v_readlane_b32 s86, v254, 63
	v_readlane_b32 s87, v255, 0
	s_or_b64 exec, exec, s[78:79]
	s_and_saveexec_b64 s[78:79], s[70:71]
	v_ashrrev_i32_e32 v49, 31, v48
	v_lshl_add_u64 v[50:51], v[50:51], 2, v[156:157]
	v_lshlrev_b64 v[48:49], 16, v[48:49]
	v_lshl_add_u64 v[48:49], v[50:51], 0, v[48:49]
	global_store_dwordx4 v[48:49], v[32:35], off
	s_or_b64 exec, exec, s[78:79]
	s_nop 0
	v_lshlrev_b32_e32 v34, 2, v53
	v_mov_b32_e32 v34, v24
	v_mov_b32_e32 v35, v24
	s_nop 1
	v_permlane16_swap_b32_e32 v34, v35
	v_cndmask_b32_e64 v34, v34, v35, s[6:7]
	v_cndmask_b32_e64 v35, v34, -v34, s[10:11]
	v_mov_b32_e32 v54, v24
	v_mov_b32_e32 v34, v216
	v_mov_b32_e32 v55, v220
	v_pk_mul_f32 v[34:35], v[54:55], v[34:35]
	v_mov_b32_e32 v48, v25
	v_add_f32_e32 v28, v34, v35
	v_mov_b32_e32 v34, v25
	v_mov_b32_e32 v35, v25
	s_nop 1
	v_permlane16_swap_b32_e32 v34, v35
	v_cndmask_b32_e64 v34, v34, v35, s[6:7]
	v_cndmask_b32_e64 v35, v34, -v34, s[10:11]
	v_mov_b32_e32 v34, v217
	v_mov_b32_e32 v49, v221
	v_pk_mul_f32 v[34:35], v[48:49], v[34:35]
	v_mov_b32_e32 v48, v26
	v_add_f32_e32 v29, v34, v35
	v_mov_b32_e32 v34, v26
	v_mov_b32_e32 v35, v26
	s_nop 1
	v_permlane16_swap_b32_e32 v34, v35
	v_cndmask_b32_e64 v34, v34, v35, s[6:7]
	v_cndmask_b32_e64 v35, v34, -v34, s[10:11]
	v_mov_b32_e32 v49, v222
	v_mov_b32_e32 v34, v218
	v_pk_mul_f32 v[34:35], v[48:49], v[34:35]
	v_mov_b32_e32 v50, v27
	v_add_f32_e32 v30, v34, v35
	v_mov_b32_e32 v34, v27
	v_mov_b32_e32 v35, v27
	s_nop 1
	v_permlane16_swap_b32_e32 v34, v35
	v_cndmask_b32_e64 v34, v34, v35, s[6:7]
	v_cndmask_b32_e64 v35, v34, -v34, s[10:11]
	v_mov_b32_e32 v34, v219
	v_mov_b32_e32 v51, v223
	v_pk_mul_f32 v[34:35], v[50:51], v[34:35]
	v_cndmask_b32_e64 v28, v24, v28, s[8:9]
	v_add_f32_e32 v31, v34, v35
	v_cndmask_b32_e64 v29, v25, v29, s[8:9]
	v_cndmask_b32_e64 v30, v26, v30, s[8:9]
	v_cndmask_b32_e64 v31, v27, v31, s[8:9]
	v_mov_b32_e32 v50, v28
	v_mov_b32_e32 v54, v29
	v_mov_b32_e32 v51, v30
	v_mov_b32_e32 v55, v31
	v_lshl_add_u64 v[34:35], v[164:165], 0, v[38:39]
	v_cvt_pk_bf16_f32 v48, v50, v54
	v_cvt_pk_bf16_f32 v49, v51, v55
	global_store_dwordx2 v[34:35], v[48:49], off
	s_and_saveexec_b64 s[78:79], s[20:21]
	s_xor_b64 s[78:79], exec, s[78:79]
	s_mov_b64 s[70:71], exec
	v_add_u32_e32 v34, s87, v52
	s_or_saveexec_b64 s[78:79], s[78:79]
	v_mov_b64_e32 v[48:49], v[160:161]
	s_xor_b64 exec, exec, s[78:79]
	s_and_saveexec_b64 vcc, s[18:19]
	v_readlane_b32 s80, v254, 37
	v_readlane_b32 s81, v254, 38
	s_add_i32 s46, s53, s80
	s_or_b64 s[80:81], s[70:71], exec
	s_or_b64 exec, exec, vcc
	s_andn2_b64 s[70:71], s[70:71], exec
	s_and_b64 s[80:81], s[80:81], exec
	v_mov_b32_e32 v34, s46
	s_or_b64 s[70:71], s[70:71], s[80:81]
	v_mov_b64_e32 v[48:49], v[46:47]
	v_readlane_b32 s86, v254, 63
	v_readlane_b32 s87, v255, 0
	s_or_b64 exec, exec, s[78:79]
	s_and_saveexec_b64 s[78:79], s[70:71]
	v_ashrrev_i32_e32 v35, 31, v34
	v_lshl_add_u64 v[46:47], v[48:49], 2, v[156:157]
	v_lshlrev_b64 v[34:35], 16, v[34:35]
	v_lshl_add_u64 v[34:35], v[46:47], 0, v[34:35]
	global_store_dwordx4 v[34:35], v[28:31], off offset:16
	s_or_b64 exec, exec, s[78:79]
	s_mov_b64 s[70:71], 0x1100000
	v_lshl_add_u64 v[28:29], v[44:45], 0, s[70:71]
	v_mov_b64_e32 v[26:27], v[22:23]
	v_mov_b64_e32 v[24:25], v[20:21]
	v_mov_b32_e32 v44, v20
	v_mov_b32_e32 v46, v21
	v_mov_b32_e32 v45, v22
	v_mov_b32_e32 v47, v23
	v_lshl_add_u64 v[30:31], v[158:159], 0, v[38:39]
	v_cvt_pk_bf16_f32 v34, v44, v46
	v_cvt_pk_bf16_f32 v35, v45, v47
	global_store_dwordx2 v[30:31], v[34:35], off
	s_and_saveexec_b64 s[78:79], s[20:21]
; __device__ __forceinline__ float shx16(float v, int odd  ) { const unsigned x = __builtin_bit_cast(unsigned, v); auto r = __builtin_amdgcn_permlane16_swap(x, x, false, false); return __builtin_bit_cast(float, odd ? r[0] : r[1]); }
; __device__ __forceinline__ void st_bf4(bf16_t* p, const f32x4 v) { u32x2 w; w.x = cvt_pk_bf16(v[0], v[1]); w.y = cvt_pk_bf16(v[2], v[3]); *(u32x2*)p = w; }
;     __device__ __forceinline__ void operator()(const f32x4 (&acc)[2][2][4][2], const Unit& u, int wr, int wc, int fr, int fq) const {
;     ...
;             for (int m = 0; m < 4; ++m) { const int row = u.pm * 256 + ai * 128 + wr * 64 + m * 16 + fr;
; #pragma unroll
;                 for (int bj = 0; bj < 2; ++bj)
; #pragma unroll
;                     for (int n = 0; n < 2; ++n) { const int tc = bj * 128 + wc * 32 + 8 * fq + 4 * n; f32x4 v = acc[ai][bj][m][n];
;                         if (pn < 2) { *(f32x4*)(XA + (size_t)row * 512 + pn * 256 + tc) = v; }
;                         else if (pn <= 4) {
;                             const bool isv = (pn == 4 && bj == 1);
;                             if (!isv && (wc & 1) == 0) {
;                                 const int tix = row < cfg::MP ? (row & 2047) : 2048 + (row & 3);
;                                 const f32x4 cs = *(const f32x4*)(ropec + tix * 8 + 4 * n), sn = *(const f32x4*)(ropes + tix * 8 + 4 * n);
; #pragma unroll
;                                 for (int i = 0; i < 4; ++i) { const float p = shx16(v[i], fq & 1); const float rv = v[i] * cs[i] + (fq == 0 ? -p : p) * sn[i]; v[i] = fq < 2 ? rv : v[i]; }
;                             }
;                             if (pn < 4) st_bf4(Q + (size_t)row * 512 + (pn - 2) * 256 + tc, v);
;                             else { st_bf4((bj == 0 ? KB : VB) + (size_t)row * 128 + (tc & 127), v);
;                                 bool w = false; size_t o = 0;
;                                 if (row < cfg::MP) { const int t = row & 2047; if (t >= 1920) { w = true; o = (bj == 0 ? cfg::OFF_KP : cfg::OFF_VP) + ((size_t)(layer * 8 + (row >> 11)) * 128 + (t - 1920)) * 128 + (tc & 127); } }
;                                 else { const int rs = row - cfg::MP; w = true; o = (bj == 0 ? cfg::OFF_KS : cfg::OFF_VS) + ((size_t)(layer * 128 + (rs >> 2)) * 128 + 124 + (rs & 3)) * 128 + (tc & 127); }
;                                 if (w) *(f32x4*)(out + o) = v; }
	s_xor_b64 s[78:79], exec, s[78:79]
	s_mov_b64 s[70:71], exec
	v_add_u32_e32 v30, s87, v52
	s_or_saveexec_b64 s[78:79], s[78:79]
	v_mov_b64_e32 v[34:35], v[162:163]
	s_xor_b64 exec, exec, s[78:79]
	s_and_saveexec_b64 vcc, s[18:19]
	v_readlane_b32 s80, v254, 37
	v_readlane_b32 s81, v254, 38
	s_add_i32 s46, s53, s80
	s_or_b64 s[80:81], s[70:71], exec
	s_or_b64 exec, exec, vcc
	s_andn2_b64 s[70:71], s[70:71], exec
	s_and_b64 s[80:81], s[80:81], exec
	v_mov_b32_e32 v30, s46
	s_or_b64 s[70:71], s[70:71], s[80:81]
	v_mov_b64_e32 v[34:35], v[28:29]
	v_readlane_b32 s86, v254, 63
	v_readlane_b32 s87, v255, 0
	s_or_b64 exec, exec, s[78:79]
	s_and_saveexec_b64 s[78:79], s[70:71]
	v_ashrrev_i32_e32 v31, 31, v30
	v_lshl_add_u64 v[34:35], v[34:35], 2, v[156:157]
	v_lshlrev_b64 v[30:31], 16, v[30:31]
	v_lshl_add_u64 v[30:31], v[34:35], 0, v[30:31]
	global_store_dwordx4 v[30:31], v[24:27], off
	s_or_b64 exec, exec, s[78:79]
	v_mov_b64_e32 v[22:23], v[18:19]
	v_mov_b64_e32 v[20:21], v[16:17]
	v_mov_b32_e32 v30, v16
	v_mov_b32_e32 v34, v17
	v_mov_b32_e32 v31, v18
	v_mov_b32_e32 v35, v19
	s_andn2_b64 vcc, exec, s[96:97]
	v_lshl_add_u64 v[24:25], v[166:167], 0, v[38:39]
	v_cvt_pk_bf16_f32 v26, v30, v34
	v_cvt_pk_bf16_f32 v27, v31, v35
	global_store_dwordx2 v[24:25], v[26:27], off
	s_and_saveexec_b64 s[78:79], s[20:21]
	s_xor_b64 s[20:21], exec, s[78:79]
	s_mov_b64 s[70:71], exec
	v_add_u32_e32 v24, s87, v52
	s_or_saveexec_b64 s[20:21], s[20:21]
	v_mov_b64_e32 v[26:27], v[162:163]
	s_xor_b64 exec, exec, s[20:21]
	s_and_saveexec_b64 s[80:81], s[18:19]
	v_readlane_b32 s18, v254, 37
	s_add_i32 s46, s53, s18
	s_or_b64 s[78:79], s[70:71], exec
	v_readlane_b32 s19, v254, 38
	s_or_b64 exec, exec, s[80:81]
	s_andn2_b64 s[18:19], s[70:71], exec
	s_and_b64 s[70:71], s[78:79], exec
	v_mov_b32_e32 v24, s46
	s_or_b64 s[70:71], s[18:19], s[70:71]
	v_mov_b64_e32 v[26:27], v[28:29]
	s_or_b64 exec, exec, s[20:21]
	s_and_saveexec_b64 s[18:19], s[70:71]
	v_ashrrev_i32_e32 v25, 31, v24
	v_lshl_add_u64 v[26:27], v[26:27], 2, v[156:157]
	v_lshlrev_b64 v[24:25], 16, v[24:25]
	v_lshl_add_u64 v[24:25], v[26:27], 0, v[24:25]
	global_store_dwordx4 v[24:25], v[20:23], off offset:16
	s_or_b64 exec, exec, s[18:19]
	v_or_b32_e32 v16, 48, v68
	v_mad_i64_i32 v[26:27], s[18:19], v16, s61, 0
	s_movk_i32 s18, 0x3fff
	s_nop 0
	v_cmp_lt_i32_e64 s[20:21], s18, v16
	s_movk_i32 s18, 0x7ff
	v_bitop3_b32 v18, v68, s18, 48 bitop3:0xc8
	s_movk_i32 s18, 0x4000
	v_cmp_gt_i32_e32 vcc, s18, v16
	v_add_u32_e32 v96, 0xfffff880, v18
	v_ashrrev_i32_e32 v17, 31, v16
	v_cndmask_b32_e32 v19, v151, v18, vcc
	v_lshlrev_b32_e32 v37, 3, v19
	v_add_u32_e32 v19, 0xffffc030, v68
	s_movk_i32 s18, 0x77f
	v_lshlrev_b64 v[28:29], 7, v[96:97]
	s_mov_b64 s[70:71], 0x1080000
	v_lshlrev_b64 v[24:25], 11, v[16:17]
	v_lshlrev_b64 v[22:23], 8, v[16:17]
	v_lshrrev_b32_e32 v36, 2, v19
	v_cmp_lt_u32_e64 s[18:19], s18, v18
	v_lshlrev_b64 v[20:21], 10, v[16:17]
	v_lshl_add_u64 v[30:31], v[28:29], 0, s[70:71]
	v_lshlrev_b32_e32 v32, 2, v37
	v_mov_b32_e32 v38, v12
	v_mov_b32_e32 v39, v12
	s_nop 1
	v_permlane16_swap_b32_e32 v38, v39
	v_cndmask_b32_e64 v38, v38, v39, s[6:7]
	v_cndmask_b32_e64 v39, v38, -v38, s[10:11]
	v_mov_b32_e32 v40, v12
	s_waitcnt vmcnt(4)
	v_mov_b32_e32 v38, v234
	v_mov_b32_e32 v41, v238
	v_pk_mul_f32 v[38:39], v[40:41], v[38:39]
	v_mov_b32_e32 v32, v13
	v_add_f32_e32 v16, v38, v39
	v_mov_b32_e32 v38, v13
	s_nop 1
	v_permlane16_swap_b32_e32 v32, v38
	v_cndmask_b32_e64 v32, v32, v38, s[6:7]
	v_cndmask_b32_e64 v39, v32, -v32, s[10:11]
	v_mov_b32_e32 v32, v13
	v_mov_b32_e32 v38, v235
	v_mov_b32_e32 v33, v239
	v_pk_mul_f32 v[32:33], v[32:33], v[38:39]
	v_mov_b32_e32 v38, v14
	v_add_f32_e32 v17, v32, v33
	v_mov_b32_e32 v32, v14
	v_mov_b32_e32 v33, v14
	s_nop 1
	v_permlane16_swap_b32_e32 v32, v33
	v_cndmask_b32_e64 v32, v32, v33, s[6:7]
	v_cndmask_b32_e64 v33, v32, -v32, s[10:11]
	v_mov_b32_e32 v39, v240
	v_mov_b32_e32 v32, v236
	v_pk_mul_f32 v[32:33], v[38:39], v[32:33]
	v_mov_b32_e32 v34, v15
	v_add_f32_e32 v18, v32, v33
	v_mov_b32_e32 v32, v15
	v_mov_b32_e32 v33, v15
	s_nop 1
	v_permlane16_swap_b32_e32 v32, v33
	v_cndmask_b32_e64 v32, v32, v33, s[6:7]
	v_cndmask_b32_e64 v33, v32, -v32, s[10:11]
	v_mov_b32_e32 v32, v237
	v_mov_b32_e32 v35, v241
	v_pk_mul_f32 v[32:33], v[34:35], v[32:33]
	v_cndmask_b32_e64 v16, v12, v16, s[8:9]
	v_add_f32_e32 v19, v32, v33
	v_cndmask_b32_e64 v17, v13, v17, s[8:9]
	v_cndmask_b32_e64 v18, v14, v18, s[8:9]
	v_cndmask_b32_e64 v19, v15, v19, s[8:9]
	v_mov_b32_e32 v38, v16
	v_mov_b32_e32 v40, v17
	v_mov_b32_e32 v39, v18
	v_mov_b32_e32 v41, v19
	v_lshl_add_u64 v[32:33], v[154:155], 0, v[22:23]
	v_cvt_pk_bf16_f32 v34, v38, v40
	v_cvt_pk_bf16_f32 v35, v39, v41
	global_store_dwordx2 v[32:33], v[34:35], off
	s_and_saveexec_b64 s[78:79], s[20:21]
	s_xor_b64 s[78:79], exec, s[78:79]
	s_mov_b64 s[70:71], exec
	v_add_u32_e32 v32, s87, v36
	s_or_saveexec_b64 s[78:79], s[78:79]
	v_mov_b64_e32 v[34:35], v[160:161]
	s_xor_b64 exec, exec, s[78:79]
	s_and_saveexec_b64 vcc, s[18:19]
	v_readlane_b32 s80, v254, 37
	v_readlane_b32 s81, v254, 38
	s_add_i32 s46, s53, s80
	s_or_b64 s[80:81], s[70:71], exec
	s_or_b64 exec, exec, vcc
	s_andn2_b64 s[70:71], s[70:71], exec
	s_and_b64 s[80:81], s[80:81], exec
	v_mov_b32_e32 v32, s46
	s_or_b64 s[70:71], s[70:71], s[80:81]
	v_mov_b64_e32 v[34:35], v[30:31]
	v_readlane_b32 s86, v254, 63
	v_readlane_b32 s87, v255, 0
	s_or_b64 exec, exec, s[78:79]
	s_and_saveexec_b64 s[78:79], s[70:71]
	v_ashrrev_i32_e32 v33, 31, v32
	v_lshl_add_u64 v[34:35], v[34:35], 2, v[156:157]
	v_lshlrev_b64 v[32:33], 16, v[32:33]
; __device__ __forceinline__ float shx16(float v, int odd  ) { const unsigned x = __builtin_bit_cast(unsigned, v); auto r = __builtin_amdgcn_permlane16_swap(x, x, false, false); return __builtin_bit_cast(float, odd ? r[0] : r[1]); }
; __device__ __forceinline__ void st_bf4(bf16_t* p, const f32x4 v) { u32x2 w; w.x = cvt_pk_bf16(v[0], v[1]); w.y = cvt_pk_bf16(v[2], v[3]); *(u32x2*)p = w; }
;     __device__ __forceinline__ void operator()(const f32x4 (&acc)[2][2][4][2], const Unit& u, int wr, int wc, int fr, int fq) const {
;     ...
;                     for (int n = 0; n < 2; ++n) { const int tc = bj * 128 + wc * 32 + 8 * fq + 4 * n; f32x4 v = acc[ai][bj][m][n];
;                         if (pn < 2) { *(f32x4*)(XA + (size_t)row * 512 + pn * 256 + tc) = v; }
;                         else if (pn <= 4) {
;                             const bool isv = (pn == 4 && bj == 1);
;                             if (!isv && (wc & 1) == 0) {
;                                 const int tix = row < cfg::MP ? (row & 2047) : 2048 + (row & 3);
;                                 const f32x4 cs = *(const f32x4*)(ropec + tix * 8 + 4 * n), sn = *(const f32x4*)(ropes + tix * 8 + 4 * n);
; #pragma unroll
;                                 for (int i = 0; i < 4; ++i) { const float p = shx16(v[i], fq & 1); const float rv = v[i] * cs[i] + (fq == 0 ? -p : p) * sn[i]; v[i] = fq < 2 ? rv : v[i]; }
;                             }
;                             if (pn < 4) st_bf4(Q + (size_t)row * 512 + (pn - 2) * 256 + tc, v);
;                             else { st_bf4((bj == 0 ? KB : VB) + (size_t)row * 128 + (tc & 127), v);
;                                 bool w = false; size_t o = 0;
;                                 if (row < cfg::MP) { const int t = row & 2047; if (t >= 1920) { w = true; o = (bj == 0 ? cfg::OFF_KP : cfg::OFF_VP) + ((size_t)(layer * 8 + (row >> 11)) * 128 + (t - 1920)) * 128 + (tc & 127); } }
;                                 else { const int rs = row - cfg::MP; w = true; o = (bj == 0 ? cfg::OFF_KS : cfg::OFF_VS) + ((size_t)(layer * 128 + (rs >> 2)) * 128 + 124 + (rs & 3)) * 128 + (tc & 127); }
;                                 if (w) *(f32x4*)(out + o) = v; }
	v_lshl_add_u64 v[32:33], v[34:35], 0, v[32:33]
	global_store_dwordx4 v[32:33], v[16:19], off
	s_or_b64 exec, exec, s[78:79]
	s_nop 0
	v_lshl_add_u64 v[16:17], s[30:31], 0, v[24:25]
	v_lshl_add_u64 v[16:17], s[92:93], 2, v[16:17]
	v_lshlrev_b32_e32 v18, 2, v37
	v_mov_b32_e32 v18, v8
	v_mov_b32_e32 v19, v8
	s_nop 1
	v_permlane16_swap_b32_e32 v18, v19
	v_cndmask_b32_e64 v18, v18, v19, s[6:7]
	v_cndmask_b32_e64 v19, v18, -v18, s[10:11]
	v_mov_b32_e32 v38, v8
	v_mov_b32_e32 v18, v242
	v_mov_b32_e32 v39, v246
	v_pk_mul_f32 v[18:19], v[38:39], v[18:19]
	v_mov_b32_e32 v32, v9
	v_add_f32_e32 v12, v18, v19
	v_mov_b32_e32 v18, v9
	v_mov_b32_e32 v19, v9
	s_nop 1
	v_permlane16_swap_b32_e32 v18, v19
	v_cndmask_b32_e64 v18, v18, v19, s[6:7]
	v_cndmask_b32_e64 v19, v18, -v18, s[10:11]
	v_mov_b32_e32 v18, v243
	v_mov_b32_e32 v33, v247
	v_pk_mul_f32 v[18:19], v[32:33], v[18:19]
	v_mov_b32_e32 v32, v10
	v_add_f32_e32 v13, v18, v19
	v_mov_b32_e32 v18, v10
	v_mov_b32_e32 v19, v10
	s_nop 1
	v_permlane16_swap_b32_e32 v18, v19
	v_cndmask_b32_e64 v18, v18, v19, s[6:7]
	v_cndmask_b32_e64 v19, v18, -v18, s[10:11]
	v_mov_b32_e32 v33, v248
	v_mov_b32_e32 v18, v244
	v_pk_mul_f32 v[18:19], v[32:33], v[18:19]
	v_mov_b32_e32 v34, v11
	v_add_f32_e32 v14, v18, v19
	v_mov_b32_e32 v18, v11
	v_mov_b32_e32 v19, v11
	s_nop 1
	v_permlane16_swap_b32_e32 v18, v19
	v_cndmask_b32_e64 v18, v18, v19, s[6:7]
	v_cndmask_b32_e64 v19, v18, -v18, s[10:11]
	v_mov_b32_e32 v18, v245
	v_mov_b32_e32 v35, v249
	v_pk_mul_f32 v[18:19], v[34:35], v[18:19]
	v_cndmask_b32_e64 v12, v8, v12, s[8:9]
	v_add_f32_e32 v15, v18, v19
	v_cndmask_b32_e64 v13, v9, v13, s[8:9]
	v_cndmask_b32_e64 v14, v10, v14, s[8:9]
	v_cndmask_b32_e64 v15, v11, v15, s[8:9]
	v_mov_b32_e32 v34, v12
	v_mov_b32_e32 v38, v13
	v_mov_b32_e32 v35, v14
	v_mov_b32_e32 v39, v15
	v_lshl_add_u64 v[18:19], v[164:165], 0, v[22:23]
	v_cvt_pk_bf16_f32 v32, v34, v38
	v_cvt_pk_bf16_f32 v33, v35, v39
	global_store_dwordx2 v[18:19], v[32:33], off
	s_and_saveexec_b64 s[78:79], s[20:21]
	s_xor_b64 s[78:79], exec, s[78:79]
	s_mov_b64 s[70:71], exec
	v_add_u32_e32 v18, s87, v36
	s_or_saveexec_b64 s[78:79], s[78:79]
	v_mov_b64_e32 v[32:33], v[160:161]
	s_xor_b64 exec, exec, s[78:79]
	s_and_saveexec_b64 s[92:93], s[18:19]
	v_readlane_b32 s80, v254, 37
	v_readlane_b32 s81, v254, 38
	s_add_i32 s46, s53, s80
	s_or_b64 s[80:81], s[70:71], exec
	s_or_b64 exec, exec, s[92:93]
	s_andn2_b64 s[70:71], s[70:71], exec
	s_and_b64 s[80:81], s[80:81], exec
	v_mov_b32_e32 v18, s46
	s_or_b64 s[70:71], s[70:71], s[80:81]
	v_mov_b64_e32 v[32:33], v[30:31]
	v_readlane_b32 s86, v254, 63
	v_readlane_b32 s87, v255, 0
	s_or_b64 exec, exec, s[78:79]
	s_and_saveexec_b64 s[78:79], s[70:71]
	v_ashrrev_i32_e32 v19, 31, v18
	v_lshl_add_u64 v[30:31], v[32:33], 2, v[156:157]
	v_lshlrev_b64 v[18:19], 16, v[18:19]
	v_lshl_add_u64 v[18:19], v[30:31], 0, v[18:19]
	global_store_dwordx4 v[18:19], v[12:15], off offset:16
	s_or_b64 exec, exec, s[78:79]
	s_mov_b64 s[70:71], 0x1100000
	v_lshl_add_u64 v[12:13], v[28:29], 0, s[70:71]
	v_mov_b64_e32 v[10:11], v[6:7]
	v_mov_b64_e32 v[8:9], v[4:5]
	v_mov_b32_e32 v28, v4
	v_mov_b32_e32 v30, v5
	v_mov_b32_e32 v29, v6
	v_mov_b32_e32 v31, v7
	v_lshl_add_u64 v[14:15], v[158:159], 0, v[22:23]
	v_cvt_pk_bf16_f32 v18, v28, v30
	v_cvt_pk_bf16_f32 v19, v29, v31
	global_store_dwordx2 v[14:15], v[18:19], off
	s_and_saveexec_b64 s[78:79], s[20:21]
	s_xor_b64 s[78:79], exec, s[78:79]
	s_mov_b64 s[70:71], exec
	v_add_u32_e32 v14, s87, v36
	s_or_saveexec_b64 s[78:79], s[78:79]
	v_mov_b64_e32 v[18:19], v[162:163]
	s_xor_b64 exec, exec, s[78:79]
	s_and_saveexec_b64 s[92:93], s[18:19]
	v_readlane_b32 s80, v254, 37
	v_readlane_b32 s81, v254, 38
	s_add_i32 s46, s53, s80
	s_or_b64 s[80:81], s[70:71], exec
	s_or_b64 exec, exec, s[92:93]
	s_andn2_b64 s[70:71], s[70:71], exec
	s_and_b64 s[80:81], s[80:81], exec
	v_mov_b32_e32 v14, s46
	s_or_b64 s[70:71], s[70:71], s[80:81]
	v_mov_b64_e32 v[18:19], v[12:13]
	v_readlane_b32 s86, v254, 63
	v_readlane_b32 s87, v255, 0
	s_or_b64 exec, exec, s[78:79]
	s_and_saveexec_b64 s[78:79], s[70:71]
	v_ashrrev_i32_e32 v15, 31, v14
	v_lshl_add_u64 v[18:19], v[18:19], 2, v[156:157]
	v_lshlrev_b64 v[14:15], 16, v[14:15]
	v_lshl_add_u64 v[14:15], v[18:19], 0, v[14:15]
	global_store_dwordx4 v[14:15], v[8:11], off
	s_or_b64 exec, exec, s[78:79]
	s_mov_b32 s70, 0x1200000
	s_mov_b32 s71, 0x1400000
	v_mov_b64_e32 v[6:7], v[2:3]
	v_mov_b64_e32 v[4:5], v[0:1]
	v_mov_b32_e32 v14, v0
	v_mov_b32_e32 v18, v1
	v_mov_b32_e32 v15, v2
	v_mov_b32_e32 v19, v3
	v_lshl_add_u64 v[8:9], v[166:167], 0, v[22:23]
	v_cvt_pk_bf16_f32 v10, v14, v18
	v_cvt_pk_bf16_f32 v11, v15, v19
	global_store_dwordx2 v[8:9], v[10:11], off
	s_and_saveexec_b64 s[16:17], s[20:21]
	s_xor_b64 s[16:17], exec, s[16:17]
	s_mov_b64 s[14:15], exec
	v_add_u32_e32 v8, s87, v36
	s_or_saveexec_b64 s[16:17], s[16:17]
	v_mov_b64_e32 v[10:11], v[162:163]
	s_xor_b64 exec, exec, s[16:17]
	s_and_saveexec_b64 s[28:29], s[18:19]
	v_readlane_b32 s18, v254, 37
	s_add_i32 s46, s53, s18
	s_or_b64 s[20:21], s[14:15], exec
	v_readlane_b32 s19, v254, 38
	s_or_b64 exec, exec, s[28:29]
	s_andn2_b64 s[14:15], s[14:15], exec
	s_and_b64 s[18:19], s[20:21], exec
	v_mov_b32_e32 v8, s46
	s_or_b64 s[14:15], s[14:15], s[18:19]
	v_mov_b64_e32 v[10:11], v[12:13]
	s_or_b64 exec, exec, s[16:17]
	s_and_saveexec_b64 s[16:17], s[14:15]
	v_ashrrev_i32_e32 v9, 31, v8
	v_lshl_add_u64 v[10:11], v[10:11], 2, v[156:157]
	v_lshlrev_b64 v[8:9], 16, v[8:9]
	v_lshl_add_u64 v[8:9], v[10:11], 0, v[8:9]
	global_store_dwordx4 v[8:9], v[4:7], off offset:16
	s_or_b64 exec, exec, s[16:17]
	s_branch .LBB0_1574
